# attention loops: descending s_setprio 3,2,1,0 across the two steps between workgroup barriers (keeps SIMD partner waves in lockstep)
# speedup vs baseline: 1.0230x; 1.0032x over previous
.LBB0_641:
	v_lshl_add_u64 v[178:179], v[174:175], 0, v[170:171]
	s_mov_b32 s24, 0x1894a000
	v_add_co_u32_e32 v52, vcc, s24, v178
	v_lshl_add_u64 v[56:57], v[172:173], 0, v[170:171]
	s_nop 0
	v_addc_co_u32_e32 v53, vcc, 0, v179, vcc
	s_mov_b32 s24, 0x19980000
	v_add_co_u32_e32 v176, vcc, s24, v56
	s_waitcnt lgkmcnt(0)
	s_nop 0
	v_addc_co_u32_e32 v177, vcc, 0, v57, vcc
	s_barrier
	global_load_dwordx4 v[52:55], v[52:53], off
	s_mul_i32 s26, s25, 0x2400
	global_load_dwordx4 v[56:59], v[176:177], off offset:512
	s_add_i32 s24, s23, -7
	s_add_i32 s27, s26, 0xffffdc00
	s_cmp_lg_u32 s25, 0
	s_cselect_b32 s27, s27, 0x9000
	v_add_u32_e32 v1, s27, v163
	ds_read_b128 v[240:243], v165 offset:18432
	ds_read_b128 v[244:247], v165 offset:23040
	ds_read_b128 v[60:63], v1 offset:36864
	ds_read_b128 v[114:117], v1 offset:36896
	ds_read_b128 v[118:121], v1 offset:41472
	ds_read_b128 v[134:137], v1 offset:41504
	ds_read_b128 v[146:149], v1 offset:36928
	ds_read_b128 v[150:153], v1 offset:36960
	ds_read_b128 v[196:199], v1 offset:41536
	ds_read_b128 v[200:203], v1 offset:41568
	s_setprio 3
	v_mov_b32_e32 v1, 0
	v_cvt_pk_bf16_f32 v204, v102, v103
	v_cvt_pk_bf16_f32 v205, v104, v105
	v_cvt_pk_bf16_f32 v206, v98, v99
	v_cvt_pk_bf16_f32 v207, v100, v101
	s_waitcnt lgkmcnt(7)
	s_nop 0
	v_mfma_f32_32x32x16_bf16 v[18:33], v[60:63], v[204:207], v[18:33]
	v_add_f32_e32 v1, v1, v102
	v_add_f32_e32 v1, v1, v103
	v_add_f32_e32 v1, v1, v104
	v_add_f32_e32 v1, v1, v105
	s_waitcnt lgkmcnt(5)
	v_mfma_f32_32x32x16_bf16 v[2:17], v[118:121], v[204:207], v[2:17]
	v_cvt_pk_bf16_f32 v60, v194, v187
	v_cvt_pk_bf16_f32 v61, v186, v185
	v_cvt_pk_bf16_f32 v62, v133, v132
	v_cvt_pk_bf16_f32 v63, v131, v130
	v_add_f32_e32 v1, v1, v98
	v_add_f32_e32 v1, v1, v99
	v_add_f32_e32 v1, v1, v100
	v_add_f32_e32 v1, v1, v101
	s_nop 0
	v_mfma_f32_32x32x16_bf16 v[18:33], v[114:117], v[60:63], v[18:33]
	v_add_f32_e32 v1, v1, v194
	v_add_f32_e32 v1, v1, v187
	v_add_f32_e32 v1, v1, v186
	v_add_f32_e32 v1, v1, v185
	s_waitcnt lgkmcnt(4)
	v_mfma_f32_32x32x16_bf16 v[2:17], v[134:137], v[60:63], v[2:17]
	v_cvt_pk_bf16_f32 v98, v129, v128
	v_cvt_pk_bf16_f32 v99, v127, v126
	v_cvt_pk_bf16_f32 v100, v125, v124
	v_cvt_pk_bf16_f32 v101, v123, v122
	v_add_f32_e32 v1, v1, v133
	v_add_f32_e32 v1, v1, v132
	v_add_f32_e32 v1, v1, v131
	v_add_f32_e32 v1, v1, v130
	s_waitcnt lgkmcnt(3)
	v_mfma_f32_32x32x16_bf16 v[18:33], v[146:149], v[98:101], v[18:33]
	v_add_f32_e32 v1, v1, v129
	v_add_f32_e32 v1, v1, v128
	v_add_f32_e32 v1, v1, v127
	v_add_f32_e32 v1, v1, v126
	s_waitcnt lgkmcnt(1)
	v_mfma_f32_32x32x16_bf16 v[2:17], v[196:199], v[98:101], v[2:17]
	v_cvt_pk_bf16_f32 v60, v109, v108
	v_cvt_pk_bf16_f32 v61, v107, v106
	v_cvt_pk_bf16_f32 v62, v113, v112
	v_cvt_pk_bf16_f32 v63, v111, v110
	v_add_f32_e32 v1, v1, v125
	v_add_f32_e32 v1, v1, v124
	v_add_f32_e32 v1, v1, v123
	v_add_f32_e32 v1, v1, v122
	s_nop 0
	v_mfma_f32_32x32x16_bf16 v[18:33], v[150:153], v[60:63], v[18:33]
	v_add_f32_e32 v1, v1, v109
	v_add_f32_e32 v1, v1, v108
	v_add_f32_e32 v1, v1, v107
	v_add_f32_e32 v1, v1, v106
	s_waitcnt lgkmcnt(0)
	v_mfma_f32_32x32x16_bf16 v[2:17], v[200:203], v[60:63], v[2:17]
	v_add_f32_e32 v1, v1, v113
	v_add_f32_e32 v1, v1, v112
	v_add_f32_e32 v1, v1, v111
	v_add_f32_e32 v1, v1, v110
	s_setprio 2
	ds_read_b128 v[130:133], v165 offset:18464
	ds_read_b128 v[146:149], v165 offset:23072
	s_waitcnt lgkmcnt(2)
	v_mfma_f32_32x32x16_bf16 v[114:129], v[240:243], v[158:161], v[34:49]
	v_exp_f32_e32 v185, v82
	v_exp_f32_e32 v186, v83
	v_exp_f32_e32 v187, v84
	v_exp_f32_e32 v194, v85
	v_exp_f32_e32 v195, v86
	v_exp_f32_e32 v196, v87
	v_exp_f32_e32 v197, v88
	v_exp_f32_e32 v198, v89
	s_waitcnt lgkmcnt(1)
	v_mfma_f32_32x32x16_bf16 v[98:113], v[244:247], v[158:161], v[34:49]
	v_exp_f32_e32 v199, v90
	v_exp_f32_e32 v200, v91
	v_exp_f32_e32 v201, v92
	v_exp_f32_e32 v202, v93
	v_exp_f32_e32 v134, v94
	v_exp_f32_e32 v135, v95
	v_exp_f32_e32 v136, v96
	v_exp_f32_e32 v137, v97
	v_mfma_f32_32x32x16_bf16 v[114:129], v[130:133], v[154:157], v[114:129]
	v_exp_f32_e32 v96, v66
	v_exp_f32_e32 v97, v67
	v_exp_f32_e32 v203, v68
	v_exp_f32_e32 v204, v69
	v_exp_f32_e32 v130, v70
	v_exp_f32_e32 v131, v71
	v_exp_f32_e32 v132, v72
	v_exp_f32_e32 v133, v73
	s_waitcnt lgkmcnt(0)
	v_mfma_f32_32x32x16_bf16 v[98:113], v[146:149], v[154:157], v[98:113]
	v_exp_f32_e32 v205, v74
	v_exp_f32_e32 v206, v75
	v_exp_f32_e32 v207, v76
	v_exp_f32_e32 v208, v77
	v_exp_f32_e32 v209, v78
	v_exp_f32_e32 v210, v79
	v_exp_f32_e32 v211, v80
	v_exp_f32_e32 v212, v81
	s_cmp_gt_i32 s25, 2
	s_cselect_b32 s27, -3, 2
	s_add_i32 s27, s27, s25
	v_add_u32_e32 v88, s26, v163
	s_add_i32 s26, s23, -6
	s_mulk_i32 s27, 0x2400
	s_min_u32 s26, s26, s13
	v_add_u32_e32 v51, s27, v182
	s_min_u32 s24, s24, s13
	s_lshl_b32 s92, s26, 13
	s_waitcnt vmcnt(3)
	ds_write_b128 v182, v[138:141]
	s_waitcnt vmcnt(2)
	ds_write_b128 v51, v[142:145] offset:36864
	v_add_f32_e32 v1, v50, v1
	v_lshl_add_u64 v[50:51], v[168:169], 0, s[92:93]
	s_lshl_b32 s92, s24, 7
	global_load_dwordx4 v[146:149], v[50:51], off
	v_lshl_add_u64 v[50:51], v[166:167], 0, s[92:93]
	global_load_dwordx4 v[150:153], v[50:51], off
	ds_read_b128 v[240:243], v165 offset:27648
	ds_read_b128 v[244:247], v165 offset:32256
	ds_read_b128 v[60:63], v88 offset:41472
	ds_read_b128 v[64:67], v88 offset:36864
	ds_read_b128 v[68:71], v88 offset:36896
	ds_read_b128 v[72:75], v88 offset:41504
	ds_read_b128 v[76:79], v88 offset:36928
	ds_read_b128 v[80:83], v88 offset:41536
	ds_read_b128 v[84:87], v88 offset:36960
	ds_read_b128 v[88:91], v88 offset:41568
	s_add_i32 s27, s25, 1
	s_setprio 1
	v_mov_b32_e32 v213, 0
	v_cvt_pk_bf16_f32 v92, v185, v186
	v_cvt_pk_bf16_f32 v93, v187, v194
	v_cvt_pk_bf16_f32 v94, v195, v196
	v_cvt_pk_bf16_f32 v95, v197, v198
	s_waitcnt lgkmcnt(6)
	s_nop 0
	v_mfma_f32_32x32x16_bf16 v[18:33], v[64:67], v[92:95], v[18:33]
	v_add_f32_e32 v213, v213, v185
	v_add_f32_e32 v213, v213, v186
	v_add_f32_e32 v213, v213, v187
	v_add_f32_e32 v213, v213, v194
	s_nop 0
	v_mfma_f32_32x32x16_bf16 v[2:17], v[60:63], v[92:95], v[2:17]
	v_cvt_pk_bf16_f32 v64, v199, v200
	v_cvt_pk_bf16_f32 v65, v201, v202
	v_cvt_pk_bf16_f32 v66, v134, v135
	v_cvt_pk_bf16_f32 v67, v136, v137
	v_add_f32_e32 v213, v213, v195
	v_add_f32_e32 v213, v213, v196
	v_add_f32_e32 v213, v213, v197
	v_add_f32_e32 v213, v213, v198
	s_waitcnt lgkmcnt(5)
	v_mfma_f32_32x32x16_bf16 v[18:33], v[68:71], v[64:67], v[18:33]
	v_add_f32_e32 v213, v213, v199
	v_add_f32_e32 v213, v213, v200
	v_add_f32_e32 v213, v213, v201
	v_add_f32_e32 v213, v213, v202
	s_waitcnt lgkmcnt(4)
	v_mfma_f32_32x32x16_bf16 v[2:17], v[72:75], v[64:67], v[2:17]
	v_cvt_pk_bf16_f32 v60, v96, v97
	v_cvt_pk_bf16_f32 v61, v203, v204
	v_cvt_pk_bf16_f32 v62, v130, v131
	v_cvt_pk_bf16_f32 v63, v132, v133
	v_add_f32_e32 v213, v213, v134
	v_add_f32_e32 v213, v213, v135
	v_add_f32_e32 v213, v213, v136
	v_add_f32_e32 v213, v213, v137
	s_waitcnt lgkmcnt(3)
	v_mfma_f32_32x32x16_bf16 v[18:33], v[76:79], v[60:63], v[18:33]
	v_add_f32_e32 v213, v213, v96
	v_add_f32_e32 v213, v213, v97
	v_add_f32_e32 v213, v213, v203
	v_add_f32_e32 v213, v213, v204
	s_waitcnt lgkmcnt(2)
	v_mfma_f32_32x32x16_bf16 v[2:17], v[80:83], v[60:63], v[2:17]
	v_cvt_pk_bf16_f32 v64, v205, v206
	v_cvt_pk_bf16_f32 v65, v207, v208
	v_cvt_pk_bf16_f32 v66, v209, v210
	v_cvt_pk_bf16_f32 v67, v211, v212
	v_add_f32_e32 v213, v213, v130
	v_add_f32_e32 v213, v213, v131
	v_add_f32_e32 v213, v213, v132
	v_add_f32_e32 v213, v213, v133
	s_waitcnt lgkmcnt(1)
	v_mfma_f32_32x32x16_bf16 v[18:33], v[84:87], v[64:67], v[18:33]
	v_add_f32_e32 v213, v213, v205
	v_add_f32_e32 v213, v213, v206
	v_add_f32_e32 v213, v213, v207
	v_add_f32_e32 v213, v213, v208
	s_waitcnt lgkmcnt(0)
	v_mfma_f32_32x32x16_bf16 v[2:17], v[88:91], v[64:67], v[2:17]
	v_add_f32_e32 v213, v213, v209
	v_add_f32_e32 v213, v213, v210
	v_add_f32_e32 v213, v213, v211
	v_add_f32_e32 v213, v213, v212
	s_setprio 0
	ds_read_b128 v[64:67], v165 offset:27680
	ds_read_b128 v[72:75], v165 offset:32288
	s_cmp_lg_u32 s25, 4
	s_cselect_b32 s24, s27, 0
	s_waitcnt lgkmcnt(2)
	v_mfma_f32_32x32x16_bf16 v[130:145], v[240:243], v[158:161], v[34:49]
	v_exp_f32_e32 v185, v114
	v_exp_f32_e32 v186, v115
	v_exp_f32_e32 v187, v116
	v_exp_f32_e32 v194, v117
	v_exp_f32_e32 v195, v118
	v_exp_f32_e32 v196, v119
	v_exp_f32_e32 v197, v120
	v_exp_f32_e32 v198, v121
	s_waitcnt lgkmcnt(1)
	v_mfma_f32_32x32x16_bf16 v[82:97], v[244:247], v[158:161], v[34:49]
	v_exp_f32_e32 v199, v122
	v_exp_f32_e32 v200, v123
	v_exp_f32_e32 v201, v124
	v_exp_f32_e32 v202, v125
	v_exp_f32_e32 v122, v126
	v_exp_f32_e32 v123, v127
	v_exp_f32_e32 v124, v128
	v_exp_f32_e32 v125, v129
	v_mfma_f32_32x32x16_bf16 v[130:145], v[64:67], v[154:157], v[130:145]
	v_exp_f32_e32 v126, v98
	v_exp_f32_e32 v127, v99
	v_exp_f32_e32 v128, v100
	v_exp_f32_e32 v129, v101
	v_exp_f32_e32 v203, v102
	v_exp_f32_e32 v204, v103
	v_exp_f32_e32 v205, v104
	v_exp_f32_e32 v206, v105
	s_waitcnt lgkmcnt(0)
	v_mfma_f32_32x32x16_bf16 v[82:97], v[72:75], v[154:157], v[82:97]
	v_exp_f32_e32 v102, v106
	v_exp_f32_e32 v103, v107
	v_exp_f32_e32 v104, v108
	v_exp_f32_e32 v105, v109
	v_exp_f32_e32 v106, v110
	v_exp_f32_e32 v107, v111
	v_exp_f32_e32 v108, v112
	v_exp_f32_e32 v109, v113
	s_cmp_gt_i32 s24, 2
	s_cselect_b32 s25, -3, 2
	s_add_i32 s25, s25, s24
	s_mulk_i32 s25, 0x2400
	v_add_u32_e32 v50, s25, v182
	s_add_i32 s25, s24, 1
	s_cmp_lg_u32 s24, 4
	s_cselect_b32 s24, s25, 0
	s_add_i32 s25, s23, -5
	s_min_u32 s25, s25, s13
	s_lshl_b32 s92, s25, 13
	s_waitcnt vmcnt(3)
	ds_write_b128 v182, v[52:55] offset:9216
	s_waitcnt vmcnt(2)
	ds_write_b128 v50, v[56:59] offset:36864
	v_lshl_add_u64 v[50:51], v[168:169], 0, s[92:93]
	s_lshl_b32 s92, s26, 7
	s_waitcnt lgkmcnt(0)
	s_barrier
	v_lshl_add_u64 v[52:53], v[166:167], 0, s[92:93]
	global_load_dwordx4 v[118:121], v[50:51], off
	global_load_dwordx4 v[114:117], v[52:53], off
	s_mul_i32 s26, s24, 0x2400
	s_add_i32 s27, s26, 0xffffdc00
	s_cmp_lg_u32 s24, 0
	s_cselect_b32 s27, s27, 0x9000
	v_add_u32_e32 v78, s27, v163
	ds_read_b128 v[240:243], v165
	ds_read_b128 v[244:247], v165 offset:4608
	ds_read_b128 v[50:53], v78 offset:36864
	ds_read_b128 v[54:57], v78 offset:36896
	ds_read_b128 v[58:61], v78 offset:41472
	ds_read_b128 v[62:65], v78 offset:41504
	ds_read_b128 v[66:69], v78 offset:36928
	ds_read_b128 v[70:73], v78 offset:36960
	ds_read_b128 v[74:77], v78 offset:41536
	ds_read_b128 v[78:81], v78 offset:41568
	s_setprio 3
	v_mov_b32_e32 v110, 0
	v_cvt_pk_bf16_f32 v98, v185, v186
	v_cvt_pk_bf16_f32 v99, v187, v194
	v_cvt_pk_bf16_f32 v100, v195, v196
	v_cvt_pk_bf16_f32 v101, v197, v198
	s_waitcnt lgkmcnt(7)
	s_nop 0
	v_mfma_f32_32x32x16_bf16 v[18:33], v[50:53], v[98:101], v[18:33]
	v_add_f32_e32 v110, v110, v185
	v_add_f32_e32 v110, v110, v186
	v_add_f32_e32 v110, v110, v187
	v_add_f32_e32 v110, v110, v194
	s_waitcnt lgkmcnt(5)
	v_mfma_f32_32x32x16_bf16 v[2:17], v[58:61], v[98:101], v[2:17]
	v_cvt_pk_bf16_f32 v50, v199, v200
	v_cvt_pk_bf16_f32 v51, v201, v202
	v_cvt_pk_bf16_f32 v52, v122, v123
	v_cvt_pk_bf16_f32 v53, v124, v125
	v_add_f32_e32 v110, v110, v195
	v_add_f32_e32 v110, v110, v196
	v_add_f32_e32 v110, v110, v197
	v_add_f32_e32 v110, v110, v198
	s_nop 0
	v_mfma_f32_32x32x16_bf16 v[18:33], v[54:57], v[50:53], v[18:33]
	v_add_f32_e32 v110, v110, v199
	v_add_f32_e32 v110, v110, v200
	v_add_f32_e32 v110, v110, v201
	v_add_f32_e32 v110, v110, v202
	s_waitcnt lgkmcnt(4)
	v_mfma_f32_32x32x16_bf16 v[2:17], v[62:65], v[50:53], v[2:17]
	v_cvt_pk_bf16_f32 v54, v126, v127
	v_cvt_pk_bf16_f32 v55, v128, v129
	v_cvt_pk_bf16_f32 v56, v203, v204
	v_cvt_pk_bf16_f32 v57, v205, v206
	v_add_f32_e32 v110, v110, v122
	v_add_f32_e32 v110, v110, v123
	v_add_f32_e32 v110, v110, v124
	v_add_f32_e32 v110, v110, v125
	s_waitcnt lgkmcnt(3)
	v_mfma_f32_32x32x16_bf16 v[18:33], v[66:69], v[54:57], v[18:33]
	v_add_f32_e32 v110, v110, v126
	v_add_f32_e32 v110, v110, v127
	v_add_f32_e32 v110, v110, v128
	v_add_f32_e32 v110, v110, v129
	s_waitcnt lgkmcnt(1)
	v_mfma_f32_32x32x16_bf16 v[2:17], v[74:77], v[54:57], v[2:17]
	v_cvt_pk_bf16_f32 v50, v102, v103
	v_cvt_pk_bf16_f32 v51, v104, v105
	v_cvt_pk_bf16_f32 v52, v106, v107
	v_cvt_pk_bf16_f32 v53, v108, v109
	v_add_f32_e32 v110, v110, v203
	v_add_f32_e32 v110, v110, v204
	v_add_f32_e32 v110, v110, v205
	v_add_f32_e32 v110, v110, v206
	s_nop 0
	v_mfma_f32_32x32x16_bf16 v[18:33], v[70:73], v[50:53], v[18:33]
	v_add_f32_e32 v110, v110, v102
	v_add_f32_e32 v110, v110, v103
	v_add_f32_e32 v110, v110, v104
	v_add_f32_e32 v110, v110, v105
	s_waitcnt lgkmcnt(0)
	v_mfma_f32_32x32x16_bf16 v[2:17], v[78:81], v[50:53], v[2:17]
	v_add_f32_e32 v110, v110, v106
	v_add_f32_e32 v110, v110, v107
	v_add_f32_e32 v110, v110, v108
	v_add_f32_e32 v110, v110, v109
	s_setprio 2
	ds_read_b128 v[102:105], v165 offset:32
	ds_read_b128 v[106:109], v165 offset:4640
	v_add_f32_e32 v1, v1, v213
	s_waitcnt lgkmcnt(2)
	v_mfma_f32_32x32x16_bf16 v[66:81], v[240:243], v[158:161], v[34:49]
	v_exp_f32_e32 v185, v130
	v_exp_f32_e32 v186, v131
	v_exp_f32_e32 v187, v132
	v_exp_f32_e32 v194, v133
	v_exp_f32_e32 v195, v134
	v_exp_f32_e32 v196, v135
	v_exp_f32_e32 v197, v136
	v_exp_f32_e32 v198, v137
	v_mfma_f32_32x32x16_bf16 v[50:65], v[244:247], v[158:161], v[34:49]
	v_exp_f32_e32 v134, v138
	v_exp_f32_e32 v135, v139
	v_exp_f32_e32 v136, v140
	v_exp_f32_e32 v137, v141
	v_exp_f32_e32 v138, v142
	v_exp_f32_e32 v139, v143
	v_exp_f32_e32 v140, v144
	v_exp_f32_e32 v141, v145
	s_waitcnt lgkmcnt(1)
	v_mfma_f32_32x32x16_bf16 v[66:81], v[102:105], v[154:157], v[66:81]
	v_exp_f32_e32 v142, v82
	v_exp_f32_e32 v143, v83
	v_exp_f32_e32 v144, v84
	v_exp_f32_e32 v145, v85
	v_exp_f32_e32 v199, v86
	v_exp_f32_e32 v200, v87
	v_exp_f32_e32 v201, v88
	v_exp_f32_e32 v202, v89
	s_waitcnt lgkmcnt(0)
	v_mfma_f32_32x32x16_bf16 v[50:65], v[106:109], v[154:157], v[50:65]
	v_exp_f32_e32 v203, v90
	v_exp_f32_e32 v204, v91
	v_exp_f32_e32 v205, v92
	v_exp_f32_e32 v206, v93
	v_exp_f32_e32 v207, v94
	v_exp_f32_e32 v208, v95
	v_exp_f32_e32 v209, v96
	v_exp_f32_e32 v210, v97
	s_cmp_gt_i32 s24, 2
	s_cselect_b32 s27, -3, 2
	s_add_i32 s27, s27, s24
	s_mulk_i32 s27, 0x2400
	v_add_u32_e32 v82, s27, v182
	s_mov_b32 s27, 0x18950000
	s_waitcnt vmcnt(3)
	ds_write_b128 v182, v[146:149] offset:18432
	s_waitcnt vmcnt(2)
	ds_write_b128 v82, v[150:153] offset:36864
	v_add_co_u32_e32 v82, vcc, s27, v178
	s_lshl_b32 s92, s25, 7
	s_nop 0
	v_addc_co_u32_e32 v83, vcc, 0, v179, vcc
	global_load_dwordx4 v[126:129], v[82:83], off
	v_lshl_add_u64 v[82:83], v[166:167], 0, s[92:93]
	global_load_dwordx4 v[122:125], v[82:83], off
	v_add_u32_e32 v111, s26, v163
	v_add_f32_e32 v1, v1, v110
	ds_read_b128 v[240:243], v165 offset:9216
	ds_read_b128 v[244:247], v165 offset:13824
	ds_read_b128 v[82:85], v111 offset:41472
	ds_read_b128 v[86:89], v111 offset:36864
	ds_read_b128 v[90:93], v111 offset:36896
	ds_read_b128 v[94:97], v111 offset:41504
	ds_read_b128 v[98:101], v111 offset:36928
	ds_read_b128 v[102:105], v111 offset:41536
	ds_read_b128 v[106:109], v111 offset:36960
	ds_read_b128 v[110:113], v111 offset:41568
	s_add_i32 s26, s24, 1
	s_setprio 1
	v_mov_b32_e32 v146, 0
	v_cvt_pk_bf16_f32 v130, v185, v186
	v_cvt_pk_bf16_f32 v131, v187, v194
	v_cvt_pk_bf16_f32 v132, v195, v196
	v_cvt_pk_bf16_f32 v133, v197, v198
	s_waitcnt lgkmcnt(6)
	s_nop 0
	v_mfma_f32_32x32x16_bf16 v[18:33], v[86:89], v[130:133], v[18:33]
	v_add_f32_e32 v146, v146, v185
	v_add_f32_e32 v146, v146, v186
	v_add_f32_e32 v146, v146, v187
	v_add_f32_e32 v146, v146, v194
	s_nop 0
	v_mfma_f32_32x32x16_bf16 v[2:17], v[82:85], v[130:133], v[2:17]
	v_cvt_pk_bf16_f32 v86, v134, v135
	v_cvt_pk_bf16_f32 v87, v136, v137
	v_cvt_pk_bf16_f32 v88, v138, v139
	v_cvt_pk_bf16_f32 v89, v140, v141
	v_add_f32_e32 v146, v146, v195
	v_add_f32_e32 v146, v146, v196
	v_add_f32_e32 v146, v146, v197
	v_add_f32_e32 v146, v146, v198
	s_waitcnt lgkmcnt(5)
	v_mfma_f32_32x32x16_bf16 v[18:33], v[90:93], v[86:89], v[18:33]
	v_add_f32_e32 v146, v146, v134
	v_add_f32_e32 v146, v146, v135
	v_add_f32_e32 v146, v146, v136
	v_add_f32_e32 v146, v146, v137
	s_waitcnt lgkmcnt(4)
	v_mfma_f32_32x32x16_bf16 v[2:17], v[94:97], v[86:89], v[2:17]
	v_cvt_pk_bf16_f32 v82, v142, v143
	v_cvt_pk_bf16_f32 v83, v144, v145
	v_cvt_pk_bf16_f32 v84, v199, v200
	v_cvt_pk_bf16_f32 v85, v201, v202
	v_add_f32_e32 v146, v146, v138
	v_add_f32_e32 v146, v146, v139
	v_add_f32_e32 v146, v146, v140
	v_add_f32_e32 v146, v146, v141
	s_waitcnt lgkmcnt(3)
	v_mfma_f32_32x32x16_bf16 v[18:33], v[98:101], v[82:85], v[18:33]
	v_add_f32_e32 v146, v146, v142
	v_add_f32_e32 v146, v146, v143
	v_add_f32_e32 v146, v146, v144
	v_add_f32_e32 v146, v146, v145
	s_waitcnt lgkmcnt(2)
	v_mfma_f32_32x32x16_bf16 v[2:17], v[102:105], v[82:85], v[2:17]
	v_cvt_pk_bf16_f32 v86, v203, v204
	v_cvt_pk_bf16_f32 v87, v205, v206
	v_cvt_pk_bf16_f32 v88, v207, v208
	v_cvt_pk_bf16_f32 v89, v209, v210
	v_add_f32_e32 v146, v146, v199
	v_add_f32_e32 v146, v146, v200
	v_add_f32_e32 v146, v146, v201
	v_add_f32_e32 v146, v146, v202
	s_waitcnt lgkmcnt(1)
	v_mfma_f32_32x32x16_bf16 v[18:33], v[106:109], v[86:89], v[18:33]
	v_add_f32_e32 v146, v146, v203
	v_add_f32_e32 v146, v146, v204
	v_add_f32_e32 v146, v146, v205
	v_add_f32_e32 v146, v146, v206
	s_waitcnt lgkmcnt(0)
	v_mfma_f32_32x32x16_bf16 v[2:17], v[110:113], v[86:89], v[2:17]
	v_add_f32_e32 v146, v146, v207
	v_add_f32_e32 v146, v146, v208
	v_add_f32_e32 v146, v146, v209
	v_add_f32_e32 v146, v146, v210
	s_setprio 0
	ds_read_b128 v[130:133], v165 offset:9248
	ds_read_b128 v[138:141], v165 offset:13856
	s_cmp_lg_u32 s24, 4
	s_cselect_b32 s24, s26, 0
	s_waitcnt lgkmcnt(2)
	v_mfma_f32_32x32x16_bf16 v[98:113], v[240:243], v[158:161], v[34:49]
	v_exp_f32_e32 v142, v66
	v_exp_f32_e32 v143, v67
	v_exp_f32_e32 v144, v68
	v_exp_f32_e32 v145, v69
	v_exp_f32_e32 v147, v70
	v_exp_f32_e32 v148, v71
	v_exp_f32_e32 v149, v72
	v_exp_f32_e32 v150, v73
	s_waitcnt lgkmcnt(1)
	v_mfma_f32_32x32x16_bf16 v[82:97], v[244:247], v[158:161], v[34:49]
	v_exp_f32_e32 v151, v74
	v_exp_f32_e32 v152, v75
	v_exp_f32_e32 v153, v76
	v_exp_f32_e32 v178, v77
	v_exp_f32_e32 v134, v78
	v_exp_f32_e32 v135, v79
	v_exp_f32_e32 v136, v80
	v_exp_f32_e32 v137, v81
	v_mfma_f32_32x32x16_bf16 v[98:113], v[130:133], v[154:157], v[98:113]
	v_exp_f32_e32 v179, v50
	v_exp_f32_e32 v185, v51
	v_exp_f32_e32 v186, v52
	v_exp_f32_e32 v187, v53
	v_exp_f32_e32 v194, v54
	v_exp_f32_e32 v195, v55
	v_exp_f32_e32 v196, v56
	v_exp_f32_e32 v197, v57
	s_waitcnt lgkmcnt(0)
	v_mfma_f32_32x32x16_bf16 v[82:97], v[138:141], v[154:157], v[82:97]
	v_exp_f32_e32 v198, v58
	v_exp_f32_e32 v199, v59
	v_exp_f32_e32 v200, v60
	v_exp_f32_e32 v201, v61
	v_exp_f32_e32 v138, v62
	v_exp_f32_e32 v139, v63
	v_exp_f32_e32 v140, v64
	v_exp_f32_e32 v141, v65
	s_cmp_gt_i32 s24, 2
	s_cselect_b32 s25, -3, 2
	s_add_i32 s25, s25, s24
	s_mulk_i32 s25, 0x2400
	v_add_u32_e32 v50, s25, v182
	s_add_i32 s25, s24, 1
	s_cmp_lg_u32 s24, 4
	s_cselect_b32 s25, s25, 0
	s_add_i32 s24, s23, -3
	s_min_u32 s26, s24, s13
	s_lshl_b32 s92, s26, 13
	s_waitcnt vmcnt(3)
	ds_write_b128 v182, v[118:121] offset:27648
	s_waitcnt vmcnt(2)
	ds_write_b128 v50, v[114:117] offset:36864
	v_lshl_add_u64 v[50:51], v[168:169], 0, s[92:93]
	s_waitcnt lgkmcnt(0)
	s_barrier
	global_load_dwordx4 v[118:121], v[50:51], off
	global_load_dwordx4 v[114:117], v[176:177], off offset:1024
	s_mul_i32 s27, s25, 0x2400
	s_add_i32 s28, s27, 0xffffdc00
	s_cmp_lg_u32 s25, 0
	s_cselect_b32 s28, s28, 0x9000
	v_add_u32_e32 v78, s28, v163
	ds_read_b128 v[240:243], v165 offset:18432
	ds_read_b128 v[244:247], v165 offset:23040
	ds_read_b128 v[50:53], v78 offset:36864
	ds_read_b128 v[54:57], v78 offset:36896
	ds_read_b128 v[58:61], v78 offset:41472
	ds_read_b128 v[62:65], v78 offset:41504
	ds_read_b128 v[66:69], v78 offset:36928
	ds_read_b128 v[70:73], v78 offset:36960
	ds_read_b128 v[74:77], v78 offset:41536
	ds_read_b128 v[78:81], v78 offset:41568
	s_setprio 3
	v_mov_b32_e32 v176, 0
	v_cvt_pk_bf16_f32 v130, v142, v143
	v_cvt_pk_bf16_f32 v131, v144, v145
	v_cvt_pk_bf16_f32 v132, v147, v148
	v_cvt_pk_bf16_f32 v133, v149, v150
	s_waitcnt lgkmcnt(7)
	s_nop 0
	v_mfma_f32_32x32x16_bf16 v[18:33], v[50:53], v[130:133], v[18:33]
	v_add_f32_e32 v176, v176, v142
	v_add_f32_e32 v176, v176, v143
	v_add_f32_e32 v176, v176, v144
	v_add_f32_e32 v176, v176, v145
	s_waitcnt lgkmcnt(5)
	v_mfma_f32_32x32x16_bf16 v[2:17], v[58:61], v[130:133], v[2:17]
	v_cvt_pk_bf16_f32 v50, v151, v152
	v_cvt_pk_bf16_f32 v51, v153, v178
	v_cvt_pk_bf16_f32 v52, v134, v135
	v_cvt_pk_bf16_f32 v53, v136, v137
	v_add_f32_e32 v176, v176, v147
	v_add_f32_e32 v176, v176, v148
	v_add_f32_e32 v176, v176, v149
	v_add_f32_e32 v176, v176, v150
	s_nop 0
	v_mfma_f32_32x32x16_bf16 v[18:33], v[54:57], v[50:53], v[18:33]
	v_add_f32_e32 v176, v176, v151
	v_add_f32_e32 v176, v176, v152
	v_add_f32_e32 v176, v176, v153
	v_add_f32_e32 v176, v176, v178
	s_waitcnt lgkmcnt(4)
	v_mfma_f32_32x32x16_bf16 v[2:17], v[62:65], v[50:53], v[2:17]
	v_cvt_pk_bf16_f32 v54, v179, v185
	v_cvt_pk_bf16_f32 v55, v186, v187
	v_cvt_pk_bf16_f32 v56, v194, v195
	v_cvt_pk_bf16_f32 v57, v196, v197
	v_add_f32_e32 v176, v176, v134
	v_add_f32_e32 v176, v176, v135
	v_add_f32_e32 v176, v176, v136
	v_add_f32_e32 v176, v176, v137
	s_waitcnt lgkmcnt(3)
	v_mfma_f32_32x32x16_bf16 v[18:33], v[66:69], v[54:57], v[18:33]
	v_add_f32_e32 v176, v176, v179
	v_add_f32_e32 v176, v176, v185
	v_add_f32_e32 v176, v176, v186
	v_add_f32_e32 v176, v176, v187
	s_waitcnt lgkmcnt(1)
	v_mfma_f32_32x32x16_bf16 v[2:17], v[74:77], v[54:57], v[2:17]
	v_cvt_pk_bf16_f32 v50, v198, v199
	v_cvt_pk_bf16_f32 v51, v200, v201
	v_cvt_pk_bf16_f32 v52, v138, v139
	v_cvt_pk_bf16_f32 v53, v140, v141
	v_add_f32_e32 v176, v176, v194
	v_add_f32_e32 v176, v176, v195
	v_add_f32_e32 v176, v176, v196
	v_add_f32_e32 v176, v176, v197
	s_nop 0
	v_mfma_f32_32x32x16_bf16 v[18:33], v[70:73], v[50:53], v[18:33]
	v_add_f32_e32 v176, v176, v198
	v_add_f32_e32 v176, v176, v199
	v_add_f32_e32 v176, v176, v200
	v_add_f32_e32 v176, v176, v201
	s_waitcnt lgkmcnt(0)
	v_mfma_f32_32x32x16_bf16 v[2:17], v[78:81], v[50:53], v[2:17]
	v_add_f32_e32 v176, v176, v138
	v_add_f32_e32 v176, v176, v139
	v_add_f32_e32 v176, v176, v140
	v_add_f32_e32 v176, v176, v141
	s_setprio 2
	ds_read_b128 v[134:137], v165 offset:18464
	ds_read_b128 v[138:141], v165 offset:23072
	v_add_f32_e32 v1, v1, v146
	s_waitcnt lgkmcnt(2)
	v_mfma_f32_32x32x16_bf16 v[66:81], v[240:243], v[158:161], v[34:49]
	v_exp_f32_e32 v142, v98
	v_exp_f32_e32 v143, v99
	v_exp_f32_e32 v144, v100
	v_exp_f32_e32 v145, v101
	v_exp_f32_e32 v146, v102
	v_exp_f32_e32 v147, v103
	v_exp_f32_e32 v148, v104
	v_exp_f32_e32 v149, v105
	v_mfma_f32_32x32x16_bf16 v[50:65], v[244:247], v[158:161], v[34:49]
	v_exp_f32_e32 v150, v106
	v_exp_f32_e32 v151, v107
	v_exp_f32_e32 v152, v108
	v_exp_f32_e32 v153, v109
	v_exp_f32_e32 v177, v110
	v_exp_f32_e32 v178, v111
	v_exp_f32_e32 v179, v112
	v_exp_f32_e32 v185, v113
	s_waitcnt lgkmcnt(1)
	v_mfma_f32_32x32x16_bf16 v[66:81], v[134:137], v[154:157], v[66:81]
	v_exp_f32_e32 v186, v82
	v_exp_f32_e32 v187, v83
	v_exp_f32_e32 v194, v84
	v_exp_f32_e32 v195, v85
	v_exp_f32_e32 v134, v86
	v_exp_f32_e32 v135, v87
	v_exp_f32_e32 v136, v88
	v_exp_f32_e32 v137, v89
	s_waitcnt lgkmcnt(0)
	v_mfma_f32_32x32x16_bf16 v[50:65], v[138:141], v[154:157], v[50:65]
	v_exp_f32_e32 v196, v90
	v_exp_f32_e32 v197, v91
	v_exp_f32_e32 v198, v92
	v_exp_f32_e32 v199, v93
	v_exp_f32_e32 v138, v94
	v_exp_f32_e32 v139, v95
	v_exp_f32_e32 v140, v96
	v_exp_f32_e32 v141, v97
	s_cmp_gt_i32 s25, 2
	s_cselect_b32 s28, -3, 2
	s_waitcnt vmcnt(3)
	ds_write_b128 v182, v[126:129]
	s_add_i32 s28, s28, s25
	v_add_u32_e32 v126, s27, v163
	s_add_i32 s27, s23, -2
	s_mulk_i32 s28, 0x2400
	s_min_u32 s27, s27, s13
	v_add_u32_e32 v82, s28, v182
	s_lshl_b32 s92, s27, 13
	s_waitcnt vmcnt(2)
	ds_write_b128 v82, v[122:125] offset:36864
	v_lshl_add_u64 v[82:83], v[168:169], 0, s[92:93]
	s_lshl_b32 s92, s26, 7
	global_load_dwordx4 v[98:101], v[82:83], off
	v_lshl_add_u64 v[82:83], v[166:167], 0, s[92:93]
	global_load_dwordx4 v[102:105], v[82:83], off
	ds_read_b128 v[240:243], v165 offset:27648
	ds_read_b128 v[244:247], v165 offset:32256
	ds_read_b128 v[82:85], v126 offset:41472
	ds_read_b128 v[86:89], v126 offset:36864
	ds_read_b128 v[90:93], v126 offset:36896
	ds_read_b128 v[94:97], v126 offset:41504
	ds_read_b128 v[106:109], v126 offset:36928
	ds_read_b128 v[110:113], v126 offset:41536
	ds_read_b128 v[122:125], v126 offset:36960
	ds_read_b128 v[126:129], v126 offset:41568
	v_add_f32_e32 v1, v1, v176
	s_add_i32 s28, s25, 1
	s_setprio 1
	v_mov_b32_e32 v176, 0
	v_cvt_pk_bf16_f32 v130, v142, v143
	v_cvt_pk_bf16_f32 v131, v144, v145
	v_cvt_pk_bf16_f32 v132, v146, v147
	v_cvt_pk_bf16_f32 v133, v148, v149
	s_waitcnt lgkmcnt(6)
	s_nop 0
	v_mfma_f32_32x32x16_bf16 v[18:33], v[86:89], v[130:133], v[18:33]
	v_add_f32_e32 v176, v176, v142
	v_add_f32_e32 v176, v176, v143
	v_add_f32_e32 v176, v176, v144
	v_add_f32_e32 v176, v176, v145
	s_nop 0
	v_mfma_f32_32x32x16_bf16 v[2:17], v[82:85], v[130:133], v[2:17]
	v_cvt_pk_bf16_f32 v86, v150, v151
	v_cvt_pk_bf16_f32 v87, v152, v153
	v_cvt_pk_bf16_f32 v88, v177, v178
	v_cvt_pk_bf16_f32 v89, v179, v185
	v_add_f32_e32 v176, v176, v146
	v_add_f32_e32 v176, v176, v147
	v_add_f32_e32 v176, v176, v148
	v_add_f32_e32 v176, v176, v149
	s_waitcnt lgkmcnt(5)
	v_mfma_f32_32x32x16_bf16 v[18:33], v[90:93], v[86:89], v[18:33]
	v_add_f32_e32 v176, v176, v150
	v_add_f32_e32 v176, v176, v151
	v_add_f32_e32 v176, v176, v152
	v_add_f32_e32 v176, v176, v153
	s_waitcnt lgkmcnt(4)
	v_mfma_f32_32x32x16_bf16 v[2:17], v[94:97], v[86:89], v[2:17]
	v_cvt_pk_bf16_f32 v82, v186, v187
	v_cvt_pk_bf16_f32 v83, v194, v195
	v_cvt_pk_bf16_f32 v84, v134, v135
	v_cvt_pk_bf16_f32 v85, v136, v137
	v_add_f32_e32 v176, v176, v177
	v_add_f32_e32 v176, v176, v178
	v_add_f32_e32 v176, v176, v179
	v_add_f32_e32 v176, v176, v185
	s_waitcnt lgkmcnt(3)
	v_mfma_f32_32x32x16_bf16 v[18:33], v[106:109], v[82:85], v[18:33]
	v_add_f32_e32 v176, v176, v186
	v_add_f32_e32 v176, v176, v187
	v_add_f32_e32 v176, v176, v194
	v_add_f32_e32 v176, v176, v195
	s_waitcnt lgkmcnt(2)
	v_mfma_f32_32x32x16_bf16 v[2:17], v[110:113], v[82:85], v[2:17]
	v_cvt_pk_bf16_f32 v86, v196, v197
	v_cvt_pk_bf16_f32 v87, v198, v199
	v_cvt_pk_bf16_f32 v88, v138, v139
	v_cvt_pk_bf16_f32 v89, v140, v141
	v_add_f32_e32 v176, v176, v134
	v_add_f32_e32 v176, v176, v135
	v_add_f32_e32 v176, v176, v136
	v_add_f32_e32 v176, v176, v137
	s_waitcnt lgkmcnt(1)
	v_mfma_f32_32x32x16_bf16 v[18:33], v[122:125], v[86:89], v[18:33]
	v_add_f32_e32 v176, v176, v196
	v_add_f32_e32 v176, v176, v197
	v_add_f32_e32 v176, v176, v198
	v_add_f32_e32 v176, v176, v199
	s_waitcnt lgkmcnt(0)
	v_mfma_f32_32x32x16_bf16 v[2:17], v[126:129], v[86:89], v[2:17]
	v_add_f32_e32 v176, v176, v138
	v_add_f32_e32 v176, v176, v139
	v_add_f32_e32 v176, v176, v140
	v_add_f32_e32 v176, v176, v141
	s_setprio 0
	ds_read_b128 v[106:109], v165 offset:27680
	ds_read_b128 v[122:125], v165 offset:32288
	s_cmp_lg_u32 s25, 4
	s_cselect_b32 s25, s28, 0
	s_waitcnt lgkmcnt(2)
	v_mfma_f32_32x32x16_bf16 v[138:153], v[240:243], v[158:161], v[34:49]
	v_exp_f32_e32 v126, v66
	v_exp_f32_e32 v127, v67
	v_exp_f32_e32 v128, v68
	v_exp_f32_e32 v129, v69
	v_exp_f32_e32 v130, v70
	v_exp_f32_e32 v131, v71
	v_exp_f32_e32 v132, v72
	v_exp_f32_e32 v133, v73
	s_waitcnt lgkmcnt(1)
	v_mfma_f32_32x32x16_bf16 v[82:97], v[244:247], v[158:161], v[34:49]
	v_exp_f32_e32 v134, v74
	v_exp_f32_e32 v135, v75
	v_exp_f32_e32 v136, v76
	v_exp_f32_e32 v137, v77
	v_exp_f32_e32 v177, v78
	v_exp_f32_e32 v178, v79
	v_exp_f32_e32 v179, v80
	v_exp_f32_e32 v185, v81
	v_mfma_f32_32x32x16_bf16 v[138:153], v[106:109], v[154:157], v[138:153]
	v_exp_f32_e32 v80, v50
	v_exp_f32_e32 v81, v51
	v_exp_f32_e32 v186, v52
	v_exp_f32_e32 v187, v53
	v_exp_f32_e32 v194, v54
	v_exp_f32_e32 v195, v55
	v_exp_f32_e32 v196, v56
	v_exp_f32_e32 v197, v57
	s_waitcnt lgkmcnt(0)
	v_mfma_f32_32x32x16_bf16 v[82:97], v[122:125], v[154:157], v[82:97]
	v_exp_f32_e32 v198, v58
	v_exp_f32_e32 v199, v59
	v_exp_f32_e32 v200, v60
	v_exp_f32_e32 v201, v61
	v_exp_f32_e32 v122, v62
	v_exp_f32_e32 v123, v63
	v_exp_f32_e32 v124, v64
	v_exp_f32_e32 v125, v65
	s_cmp_gt_i32 s25, 2
	s_cselect_b32 s26, -3, 2
	s_add_i32 s26, s26, s25
	s_mulk_i32 s26, 0x2400
	v_add_u32_e32 v50, s26, v182
	s_add_i32 s26, s25, 1
	s_cmp_lg_u32 s25, 4
	s_cselect_b32 s25, s26, 0
	s_add_i32 s26, s23, -1
	s_min_u32 s26, s26, s13
	s_lshl_b32 s92, s26, 13
	s_waitcnt vmcnt(3)
	ds_write_b128 v182, v[118:121] offset:9216
	s_waitcnt vmcnt(2)
	ds_write_b128 v50, v[114:117] offset:36864
	v_lshl_add_u64 v[50:51], v[168:169], 0, s[92:93]
	s_lshl_b32 s92, s27, 7
	v_lshl_add_u64 v[52:53], v[166:167], 0, s[92:93]
	s_waitcnt lgkmcnt(0)
	s_barrier
	global_load_dwordx4 v[56:59], v[50:51], off
	s_nop 0
	global_load_dwordx4 v[52:55], v[52:53], off
	s_mul_i32 s27, s25, 0x2400
	s_add_i32 s28, s27, 0xffffdc00
	s_cmp_lg_u32 s25, 0
	s_cselect_b32 s28, s28, 0x9000
	v_add_u32_e32 v50, s28, v163
	ds_read_b128 v[240:243], v165
	ds_read_b128 v[244:247], v165 offset:4608
	ds_read_b128 v[60:63], v50 offset:36864
	ds_read_b128 v[64:67], v50 offset:36896
	ds_read_b128 v[68:71], v50 offset:41472
	ds_read_b128 v[72:75], v50 offset:41504
	ds_read_b128 v[76:79], v50 offset:36928
	ds_read_b128 v[106:109], v50 offset:36960
	ds_read_b128 v[110:113], v50 offset:41536
	ds_read_b128 v[114:117], v50 offset:41568
	s_setprio 3
	v_mov_b32_e32 v50, 0
	v_cvt_pk_bf16_f32 v118, v126, v127
	v_cvt_pk_bf16_f32 v119, v128, v129
	v_cvt_pk_bf16_f32 v120, v130, v131
	v_cvt_pk_bf16_f32 v121, v132, v133
	s_waitcnt lgkmcnt(7)
	s_nop 0
	v_mfma_f32_32x32x16_bf16 v[18:33], v[60:63], v[118:121], v[18:33]
	v_add_f32_e32 v50, v50, v126
	v_add_f32_e32 v50, v50, v127
	v_add_f32_e32 v50, v50, v128
	v_add_f32_e32 v50, v50, v129
	s_waitcnt lgkmcnt(5)
	v_mfma_f32_32x32x16_bf16 v[2:17], v[68:71], v[118:121], v[2:17]
	v_cvt_pk_bf16_f32 v60, v134, v135
	v_cvt_pk_bf16_f32 v61, v136, v137
	v_cvt_pk_bf16_f32 v62, v177, v178
	v_cvt_pk_bf16_f32 v63, v179, v185
	v_add_f32_e32 v50, v50, v130
	v_add_f32_e32 v50, v50, v131
	v_add_f32_e32 v50, v50, v132
	v_add_f32_e32 v50, v50, v133
	s_nop 0
	v_mfma_f32_32x32x16_bf16 v[18:33], v[64:67], v[60:63], v[18:33]
	v_add_f32_e32 v50, v50, v134
	v_add_f32_e32 v50, v50, v135
	v_add_f32_e32 v50, v50, v136
	v_add_f32_e32 v50, v50, v137
	s_waitcnt lgkmcnt(4)
	v_mfma_f32_32x32x16_bf16 v[2:17], v[72:75], v[60:63], v[2:17]
	v_cvt_pk_bf16_f32 v64, v80, v81
	v_cvt_pk_bf16_f32 v65, v186, v187
	v_cvt_pk_bf16_f32 v66, v194, v195
	v_cvt_pk_bf16_f32 v67, v196, v197
	v_add_f32_e32 v50, v50, v177
	v_add_f32_e32 v50, v50, v178
	v_add_f32_e32 v50, v50, v179
	v_add_f32_e32 v50, v50, v185
	s_waitcnt lgkmcnt(3)
	v_mfma_f32_32x32x16_bf16 v[18:33], v[76:79], v[64:67], v[18:33]
	v_add_f32_e32 v50, v50, v80
	v_add_f32_e32 v50, v50, v81
	v_add_f32_e32 v50, v50, v186
	v_add_f32_e32 v50, v50, v187
	s_waitcnt lgkmcnt(1)
	v_mfma_f32_32x32x16_bf16 v[2:17], v[110:113], v[64:67], v[2:17]
	v_cvt_pk_bf16_f32 v60, v198, v199
	v_cvt_pk_bf16_f32 v61, v200, v201
	v_cvt_pk_bf16_f32 v62, v122, v123
	v_cvt_pk_bf16_f32 v63, v124, v125
	v_add_f32_e32 v50, v50, v194
	v_add_f32_e32 v50, v50, v195
	v_add_f32_e32 v50, v50, v196
	v_add_f32_e32 v50, v50, v197
	s_nop 0
	v_mfma_f32_32x32x16_bf16 v[18:33], v[106:109], v[60:63], v[18:33]
	v_add_f32_e32 v50, v50, v198
	v_add_f32_e32 v50, v50, v199
	v_add_f32_e32 v50, v50, v200
	v_add_f32_e32 v50, v50, v201
	s_waitcnt lgkmcnt(0)
	v_mfma_f32_32x32x16_bf16 v[2:17], v[114:117], v[60:63], v[2:17]
	v_add_f32_e32 v50, v50, v122
	v_add_f32_e32 v50, v50, v123
	v_add_f32_e32 v50, v50, v124
	v_add_f32_e32 v50, v50, v125
	s_setprio 2
	ds_read_b128 v[68:71], v165 offset:32
	ds_read_b128 v[72:75], v165 offset:4640
	v_add_f32_e32 v1, v1, v176
	s_waitcnt lgkmcnt(2)
	v_mfma_f32_32x32x16_bf16 v[122:137], v[240:243], v[158:161], v[34:49]
	v_exp_f32_e32 v176, v138
	v_exp_f32_e32 v177, v139
	v_exp_f32_e32 v178, v140
	v_exp_f32_e32 v179, v141
	v_exp_f32_e32 v185, v142
	v_exp_f32_e32 v186, v143
	v_exp_f32_e32 v187, v144
	v_exp_f32_e32 v194, v145
	v_mfma_f32_32x32x16_bf16 v[106:121], v[244:247], v[158:161], v[34:49]
	v_exp_f32_e32 v195, v146
	v_exp_f32_e32 v196, v147
	v_exp_f32_e32 v197, v148
	v_exp_f32_e32 v198, v149
	v_exp_f32_e32 v146, v150
	v_exp_f32_e32 v147, v151
	v_exp_f32_e32 v148, v152
	v_exp_f32_e32 v149, v153
	s_waitcnt lgkmcnt(1)
	v_mfma_f32_32x32x16_bf16 v[122:137], v[68:71], v[154:157], v[122:137]
	v_exp_f32_e32 v150, v82
	v_exp_f32_e32 v151, v83
	v_exp_f32_e32 v152, v84
	v_exp_f32_e32 v153, v85
	v_exp_f32_e32 v199, v86
	v_exp_f32_e32 v200, v87
	v_exp_f32_e32 v201, v88
	v_exp_f32_e32 v202, v89
	s_waitcnt lgkmcnt(0)
	v_mfma_f32_32x32x16_bf16 v[106:121], v[72:75], v[154:157], v[106:121]
	v_exp_f32_e32 v203, v90
	v_exp_f32_e32 v204, v91
	v_exp_f32_e32 v205, v92
	v_exp_f32_e32 v206, v93
	v_exp_f32_e32 v207, v94
	v_exp_f32_e32 v208, v95
	v_exp_f32_e32 v209, v96
	v_exp_f32_e32 v210, v97
	s_cmp_gt_i32 s25, 2
	s_cselect_b32 s28, -3, 2
	s_add_i32 s28, s28, s25
	s_mulk_i32 s28, 0x2400
	v_add_u32_e32 v88, s27, v163
	s_min_u32 s27, s23, s13
	v_add_u32_e32 v51, s28, v182
	s_lshl_b32 s92, s27, 13
	s_waitcnt vmcnt(3)
	ds_write_b128 v182, v[98:101] offset:18432
	s_waitcnt vmcnt(2)
	ds_write_b128 v51, v[102:105] offset:36864
	v_add_f32_e32 v1, v1, v50
	v_lshl_add_u64 v[50:51], v[168:169], 0, s[92:93]
	s_lshl_b32 s92, s26, 7
	global_load_dwordx4 v[138:141], v[50:51], off
	v_lshl_add_u64 v[50:51], v[166:167], 0, s[92:93]
	global_load_dwordx4 v[142:145], v[50:51], off
	ds_read_b128 v[240:243], v165 offset:9216
	ds_read_b128 v[244:247], v165 offset:13824
	ds_read_b128 v[60:63], v88 offset:41472
	ds_read_b128 v[64:67], v88 offset:36864
	ds_read_b128 v[68:71], v88 offset:36896
	ds_read_b128 v[72:75], v88 offset:41504
	ds_read_b128 v[76:79], v88 offset:36928
	ds_read_b128 v[80:83], v88 offset:41536
	ds_read_b128 v[84:87], v88 offset:36960
	ds_read_b128 v[88:91], v88 offset:41568
	s_setprio 1
	v_mov_b32_e32 v50, 0
	v_mov_b32_e32 v51, v122
	v_cvt_pk_bf16_f32 v92, v176, v177
	v_cvt_pk_bf16_f32 v93, v178, v179
	v_cvt_pk_bf16_f32 v94, v185, v186
	v_cvt_pk_bf16_f32 v95, v187, v194
	s_waitcnt lgkmcnt(6)
	s_nop 0
	v_mfma_f32_32x32x16_bf16 v[18:33], v[64:67], v[92:95], v[18:33]
	v_max3_f32 v51, v51, v123, v124
	v_max3_f32 v51, v51, v125, v126
	v_add_f32_e32 v50, v50, v176
	v_add_f32_e32 v50, v50, v177
	v_add_f32_e32 v50, v50, v178
	v_add_f32_e32 v50, v50, v179
	s_nop 0
	v_mfma_f32_32x32x16_bf16 v[2:17], v[60:63], v[92:95], v[2:17]
	v_cvt_pk_bf16_f32 v64, v195, v196
	v_cvt_pk_bf16_f32 v65, v197, v198
	v_cvt_pk_bf16_f32 v66, v146, v147
	v_cvt_pk_bf16_f32 v67, v148, v149
	v_max3_f32 v51, v51, v127, v128
	v_max3_f32 v51, v51, v129, v130
	v_add_f32_e32 v50, v50, v185
	v_add_f32_e32 v50, v50, v186
	v_add_f32_e32 v50, v50, v187
	v_add_f32_e32 v50, v50, v194
	s_waitcnt lgkmcnt(5)
	v_mfma_f32_32x32x16_bf16 v[18:33], v[68:71], v[64:67], v[18:33]
	v_max3_f32 v51, v51, v131, v132
	v_max3_f32 v51, v51, v133, v134
	v_add_f32_e32 v50, v50, v195
	v_add_f32_e32 v50, v50, v196
	v_add_f32_e32 v50, v50, v197
	v_add_f32_e32 v50, v50, v198
	s_waitcnt lgkmcnt(4)
	v_mfma_f32_32x32x16_bf16 v[2:17], v[72:75], v[64:67], v[2:17]
	v_cvt_pk_bf16_f32 v60, v150, v151
	v_cvt_pk_bf16_f32 v61, v152, v153
	v_cvt_pk_bf16_f32 v62, v199, v200
	v_cvt_pk_bf16_f32 v63, v201, v202
	v_max3_f32 v51, v51, v135, v136
	v_max3_f32 v51, v51, v137, v106
	v_add_f32_e32 v50, v50, v146
	v_add_f32_e32 v50, v50, v147
	v_add_f32_e32 v50, v50, v148
	v_add_f32_e32 v50, v50, v149
	s_waitcnt lgkmcnt(3)
	v_mfma_f32_32x32x16_bf16 v[18:33], v[76:79], v[60:63], v[18:33]
	v_max3_f32 v51, v51, v107, v108
	v_max3_f32 v51, v51, v109, v110
	v_add_f32_e32 v50, v50, v150
	v_add_f32_e32 v50, v50, v151
	v_add_f32_e32 v50, v50, v152
	v_add_f32_e32 v50, v50, v153
	s_waitcnt lgkmcnt(2)
	v_mfma_f32_32x32x16_bf16 v[2:17], v[80:83], v[60:63], v[2:17]
	v_cvt_pk_bf16_f32 v64, v203, v204
	v_cvt_pk_bf16_f32 v65, v205, v206
	v_cvt_pk_bf16_f32 v66, v207, v208
	v_cvt_pk_bf16_f32 v67, v209, v210
	v_max3_f32 v51, v51, v111, v112
	v_max3_f32 v51, v51, v113, v114
	v_add_f32_e32 v50, v50, v199
	v_add_f32_e32 v50, v50, v200
	v_add_f32_e32 v50, v50, v201
	v_add_f32_e32 v50, v50, v202
	s_waitcnt lgkmcnt(1)
	v_mfma_f32_32x32x16_bf16 v[18:33], v[84:87], v[64:67], v[18:33]
	v_max3_f32 v51, v51, v115, v116
	v_max3_f32 v51, v51, v117, v118
	v_add_f32_e32 v50, v50, v203
	v_add_f32_e32 v50, v50, v204
	v_add_f32_e32 v50, v50, v205
	v_add_f32_e32 v50, v50, v206
	s_waitcnt lgkmcnt(0)
	v_mfma_f32_32x32x16_bf16 v[2:17], v[88:91], v[64:67], v[2:17]
	v_max3_f32 v51, v51, v119, v120
	v_max3_f32 v51, v51, v121, v121
	v_add_f32_e32 v50, v50, v207
	v_add_f32_e32 v50, v50, v208
	v_add_f32_e32 v50, v50, v209
	v_add_f32_e32 v50, v50, v210
	s_setprio 0
	ds_read_b128 v[146:149], v165 offset:9248
	ds_read_b128 v[60:63], v165 offset:13856
	v_add_f32_e32 v50, v1, v50
	v_mov_b32_e32 v1, v51
	s_nop 1
	v_permlane32_swap_b32_e32 v51, v1
	v_max_f32_e32 v1, v1, v1
	v_max_f32_e32 v51, v51, v51
	v_max_f32_e32 v1, v51, v1
	v_cmp_lt_f32_e32 vcc, s52, v1
	s_cbranch_vccz .LBB0_643
	v_max_f32_e32 v1, v1, v1
	v_max_f32_e32 v68, 0, v1
	v_add_f32_e32 v183, v183, v68
	v_xor_b32_e32 v34, 0x80000000, v183
	v_pk_add_f32 v[122:123], v[122:123], v[68:69] op_sel_hi:[1,0] neg_lo:[0,1] neg_hi:[0,1]
	v_pk_add_f32 v[106:107], v[106:107], v[68:69] op_sel_hi:[1,0] neg_lo:[0,1] neg_hi:[0,1]
	v_pk_add_f32 v[124:125], v[124:125], v[68:69] op_sel_hi:[1,0] neg_lo:[0,1] neg_hi:[0,1]
	v_pk_add_f32 v[108:109], v[108:109], v[68:69] op_sel_hi:[1,0] neg_lo:[0,1] neg_hi:[0,1]
	v_pk_add_f32 v[126:127], v[126:127], v[68:69] op_sel_hi:[1,0] neg_lo:[0,1] neg_hi:[0,1]
	v_pk_add_f32 v[110:111], v[110:111], v[68:69] op_sel_hi:[1,0] neg_lo:[0,1] neg_hi:[0,1]
	v_pk_add_f32 v[128:129], v[128:129], v[68:69] op_sel_hi:[1,0] neg_lo:[0,1] neg_hi:[0,1]
	v_pk_add_f32 v[112:113], v[112:113], v[68:69] op_sel_hi:[1,0] neg_lo:[0,1] neg_hi:[0,1]
	v_pk_add_f32 v[130:131], v[130:131], v[68:69] op_sel_hi:[1,0] neg_lo:[0,1] neg_hi:[0,1]
	v_pk_add_f32 v[114:115], v[114:115], v[68:69] op_sel_hi:[1,0] neg_lo:[0,1] neg_hi:[0,1]
	v_pk_add_f32 v[132:133], v[132:133], v[68:69] op_sel_hi:[1,0] neg_lo:[0,1] neg_hi:[0,1]
	v_pk_add_f32 v[116:117], v[116:117], v[68:69] op_sel_hi:[1,0] neg_lo:[0,1] neg_hi:[0,1]
	v_pk_add_f32 v[134:135], v[134:135], v[68:69] op_sel_hi:[1,0] neg_lo:[0,1] neg_hi:[0,1]
	v_pk_add_f32 v[118:119], v[118:119], v[68:69] op_sel_hi:[1,0] neg_lo:[0,1] neg_hi:[0,1]
	v_pk_add_f32 v[136:137], v[136:137], v[68:69] op_sel_hi:[1,0] neg_lo:[0,1] neg_hi:[0,1]
	v_pk_add_f32 v[120:121], v[120:121], v[68:69] op_sel_hi:[1,0] neg_lo:[0,1] neg_hi:[0,1]
	v_exp_f32_e64 v68, -v68
	v_mov_b32_e32 v35, v34
	v_mov_b32_e32 v36, v34
	v_mov_b32_e32 v37, v34
	v_mov_b32_e32 v38, v34
	v_mov_b32_e32 v39, v34
	v_mov_b32_e32 v40, v34
	v_mov_b32_e32 v41, v34
	v_mov_b32_e32 v42, v34
	v_mov_b32_e32 v43, v34
	v_mov_b32_e32 v44, v34
	v_mov_b32_e32 v45, v34
	v_mov_b32_e32 v46, v34
	v_mov_b32_e32 v47, v34
	v_mov_b32_e32 v48, v34
	v_mov_b32_e32 v49, v34
	s_nop 11
	v_pk_mul_f32 v[32:33], v[32:33], v[68:69] op_sel_hi:[1,0]
	v_pk_mul_f32 v[30:31], v[30:31], v[68:69] op_sel_hi:[1,0]
	v_pk_mul_f32 v[28:29], v[28:29], v[68:69] op_sel_hi:[1,0]
	v_pk_mul_f32 v[26:27], v[26:27], v[68:69] op_sel_hi:[1,0]
	v_pk_mul_f32 v[24:25], v[24:25], v[68:69] op_sel_hi:[1,0]
	v_pk_mul_f32 v[22:23], v[22:23], v[68:69] op_sel_hi:[1,0]
	v_pk_mul_f32 v[20:21], v[20:21], v[68:69] op_sel_hi:[1,0]
	v_pk_mul_f32 v[18:19], v[18:19], v[68:69] op_sel_hi:[1,0]
	v_pk_mul_f32 v[16:17], v[16:17], v[68:69] op_sel_hi:[1,0]
	v_pk_mul_f32 v[14:15], v[14:15], v[68:69] op_sel_hi:[1,0]
	v_pk_mul_f32 v[12:13], v[12:13], v[68:69] op_sel_hi:[1,0]
	v_pk_mul_f32 v[10:11], v[10:11], v[68:69] op_sel_hi:[1,0]
	v_pk_mul_f32 v[8:9], v[8:9], v[68:69] op_sel_hi:[1,0]
	v_pk_mul_f32 v[6:7], v[6:7], v[68:69] op_sel_hi:[1,0]
	v_pk_mul_f32 v[4:5], v[4:5], v[68:69] op_sel_hi:[1,0]
	v_pk_mul_f32 v[2:3], v[2:3], v[68:69] op_sel_hi:[1,0]
	v_mul_f32_e32 v50, v50, v68

.LBB0_661:
	v_lshl_add_u64 v[164:165], v[204:205], 0, v[200:201]
	s_mov_b32 s26, 0x1da8a000
	v_add_co_u32_e32 v2, vcc, s26, v164
	v_lshl_add_u64 v[6:7], v[202:203], 0, v[200:201]
	s_nop 0
	v_addc_co_u32_e32 v3, vcc, 0, v165, vcc
	s_mov_b32 s26, 0x1e2a0000
	v_add_co_u32_e32 v14, vcc, s26, v6
	s_waitcnt lgkmcnt(0)
	s_nop 0
	v_addc_co_u32_e32 v15, vcc, 0, v7, vcc
	s_barrier
	global_load_dwordx4 v[2:5], v[2:3], off
	s_mul_i32 s28, s27, 0x2400
	global_load_dwordx4 v[6:9], v[14:15], off offset:512
	s_add_i32 s26, s13, -7
	s_add_i32 s29, s28, 0xffffdc00
	s_cmp_lg_u32 s27, 0
	s_cselect_b32 s29, s29, 0x9000
	v_add_u32_e32 v1, s29, v195
	ds_read_b128 v[240:243], v195 offset:18432
	ds_read_b128 v[244:247], v195 offset:23040
	ds_read_b128 v[10:13], v1 offset:36864
	ds_read_b128 v[66:69], v1 offset:36896
	ds_read_b128 v[70:73], v1 offset:41472
	ds_read_b128 v[74:77], v1 offset:41504
	ds_read_b128 v[128:131], v1 offset:36928
	ds_read_b128 v[132:135], v1 offset:36960
	ds_read_b128 v[148:151], v1 offset:41536
	ds_read_b128 v[160:163], v1 offset:41568
	s_setprio 3
	v_mov_b32_e32 v1, 0
	v_cvt_pk_bf16_f32 v210, v116, v117
	v_cvt_pk_bf16_f32 v211, v118, v119
	v_cvt_pk_bf16_f32 v212, v112, v113
	v_cvt_pk_bf16_f32 v213, v114, v115
	s_waitcnt lgkmcnt(7)
	s_nop 0
	v_mfma_f32_32x32x16_bf16 v[16:31], v[10:13], v[210:213], v[16:31]
	v_add_f32_e32 v1, v1, v116
	v_add_f32_e32 v1, v1, v117
	v_add_f32_e32 v1, v1, v118
	v_add_f32_e32 v1, v1, v119
	s_waitcnt lgkmcnt(5)
	v_mfma_f32_32x32x16_bf16 v[32:47], v[70:73], v[210:213], v[32:47]
	v_cvt_pk_bf16_f32 v10, v187, v186
	v_cvt_pk_bf16_f32 v11, v185, v184
	v_cvt_pk_bf16_f32 v12, v147, v146
	v_cvt_pk_bf16_f32 v13, v145, v144
	v_add_f32_e32 v1, v1, v112
	v_add_f32_e32 v1, v1, v113
	v_add_f32_e32 v1, v1, v114
	v_add_f32_e32 v1, v1, v115
	s_nop 0
	v_mfma_f32_32x32x16_bf16 v[16:31], v[66:69], v[10:13], v[16:31]
	v_add_f32_e32 v1, v1, v187
	v_add_f32_e32 v1, v1, v186
	v_add_f32_e32 v1, v1, v185
	v_add_f32_e32 v1, v1, v184
	s_waitcnt lgkmcnt(4)
	v_mfma_f32_32x32x16_bf16 v[32:47], v[74:77], v[10:13], v[32:47]
	v_cvt_pk_bf16_f32 v66, v143, v142
	v_cvt_pk_bf16_f32 v67, v141, v140
	v_cvt_pk_bf16_f32 v68, v139, v138
	v_cvt_pk_bf16_f32 v69, v137, v136
	v_add_f32_e32 v1, v1, v147
	v_add_f32_e32 v1, v1, v146
	v_add_f32_e32 v1, v1, v145
	v_add_f32_e32 v1, v1, v144
	s_waitcnt lgkmcnt(3)
	v_mfma_f32_32x32x16_bf16 v[16:31], v[128:131], v[66:69], v[16:31]
	v_add_f32_e32 v1, v1, v143
	v_add_f32_e32 v1, v1, v142
	v_add_f32_e32 v1, v1, v141
	v_add_f32_e32 v1, v1, v140
	s_waitcnt lgkmcnt(1)
	v_mfma_f32_32x32x16_bf16 v[32:47], v[148:151], v[66:69], v[32:47]
	v_cvt_pk_bf16_f32 v10, v123, v122
	v_cvt_pk_bf16_f32 v11, v121, v120
	v_cvt_pk_bf16_f32 v12, v127, v126
	v_cvt_pk_bf16_f32 v13, v125, v124
	v_add_f32_e32 v1, v1, v139
	v_add_f32_e32 v1, v1, v138
	v_add_f32_e32 v1, v1, v137
	v_add_f32_e32 v1, v1, v136
	s_nop 0
	v_mfma_f32_32x32x16_bf16 v[16:31], v[132:135], v[10:13], v[16:31]
	v_add_f32_e32 v1, v1, v123
	v_add_f32_e32 v1, v1, v122
	v_add_f32_e32 v1, v1, v121
	v_add_f32_e32 v1, v1, v120
	s_waitcnt lgkmcnt(0)
	v_mfma_f32_32x32x16_bf16 v[32:47], v[160:163], v[10:13], v[32:47]
	v_add_f32_e32 v1, v1, v127
	v_add_f32_e32 v1, v1, v126
	v_add_f32_e32 v1, v1, v125
	v_add_f32_e32 v1, v1, v124
	s_setprio 2
	ds_read_b128 v[66:69], v195 offset:18464
	ds_read_b128 v[74:77], v195 offset:23072
	ds_read_b128 v[144:147], v195 offset:18496
	ds_read_b128 v[148:151], v195 offset:18528
	ds_read_b128 v[160:163], v195 offset:23104
	ds_read_b128 v[184:187], v195 offset:23136
	s_waitcnt lgkmcnt(6)
	v_mfma_f32_32x32x16_bf16 v[128:143], v[240:243], v[180:183], v[48:63]
	v_exp_f32_e32 v166, v96
	v_exp_f32_e32 v167, v97
	v_exp_f32_e32 v210, v98
	v_exp_f32_e32 v211, v99
	s_waitcnt lgkmcnt(5)
	v_mfma_f32_32x32x16_bf16 v[112:127], v[244:247], v[180:183], v[48:63]
	v_exp_f32_e32 v212, v100
	v_exp_f32_e32 v213, v101
	v_exp_f32_e32 v214, v102
	v_exp_f32_e32 v215, v103
	v_mfma_f32_32x32x16_bf16 v[128:143], v[66:69], v[176:179], v[128:143]
	v_exp_f32_e32 v100, v104
	v_exp_f32_e32 v101, v105
	v_exp_f32_e32 v102, v106
	v_exp_f32_e32 v103, v107
	s_waitcnt lgkmcnt(4)
	v_mfma_f32_32x32x16_bf16 v[112:127], v[74:77], v[176:179], v[112:127]
	v_exp_f32_e32 v104, v108
	v_exp_f32_e32 v105, v109
	v_exp_f32_e32 v106, v110
	v_exp_f32_e32 v107, v111
	s_waitcnt lgkmcnt(3)
	v_mfma_f32_32x32x16_bf16 v[128:143], v[144:147], v[172:175], v[128:143]
	v_exp_f32_e32 v108, v80
	v_exp_f32_e32 v109, v81
	v_exp_f32_e32 v110, v82
	v_exp_f32_e32 v111, v83
	s_waitcnt lgkmcnt(1)
	v_mfma_f32_32x32x16_bf16 v[112:127], v[160:163], v[172:175], v[112:127]
	v_exp_f32_e32 v144, v84
	v_exp_f32_e32 v145, v85
	v_exp_f32_e32 v146, v86
	v_exp_f32_e32 v147, v87
	v_mfma_f32_32x32x16_bf16 v[128:143], v[148:151], v[168:171], v[128:143]
	v_exp_f32_e32 v216, v88
	v_exp_f32_e32 v217, v89
	v_exp_f32_e32 v218, v90
	v_exp_f32_e32 v219, v91
	s_waitcnt lgkmcnt(0)
	v_mfma_f32_32x32x16_bf16 v[112:127], v[184:187], v[168:171], v[112:127]
	v_exp_f32_e32 v148, v92
	v_exp_f32_e32 v149, v93
	v_exp_f32_e32 v150, v94
	v_exp_f32_e32 v151, v95
	s_cmp_gt_i32 s27, 2
	s_cselect_b32 s29, -3, 2
	s_add_i32 s29, s29, s27
	v_add_u32_e32 v92, s28, v195
	s_add_i32 s28, s13, -6
	s_mulk_i32 s29, 0x2400
	s_min_u32 s28, s28, s12
	v_add_u32_e32 v10, s29, v208
	s_min_u32 s26, s26, s12
	s_lshl_b32 s92, s28, 13
	s_waitcnt vmcnt(3)
	ds_write_b128 v208, v[152:155]
	s_waitcnt vmcnt(2)
	ds_write_b128 v10, v[156:159] offset:36864
	v_lshl_add_u64 v[10:11], v[198:199], 0, s[92:93]
	s_lshl_b32 s92, s26, 7
	v_add_f32_e32 v1, v64, v1
	v_lshl_add_u64 v[64:65], v[196:197], 0, s[92:93]
	global_load_dwordx4 v[10:13], v[10:11], off
	s_add_i32 s29, s27, 1
	global_load_dwordx4 v[160:163], v[64:65], off
	ds_read_b128 v[240:243], v195 offset:27648
	ds_read_b128 v[244:247], v195 offset:32256
	ds_read_b128 v[64:67], v92 offset:41472
	ds_read_b128 v[68:71], v92 offset:36864
	ds_read_b128 v[72:75], v92 offset:36896
	ds_read_b128 v[76:79], v92 offset:41504
	ds_read_b128 v[80:83], v92 offset:36928
	ds_read_b128 v[84:87], v92 offset:41536
	ds_read_b128 v[88:91], v92 offset:36960
	ds_read_b128 v[92:95], v92 offset:41568
	s_setprio 1
	v_mov_b32_e32 v184, 0
	v_cvt_pk_bf16_f32 v96, v166, v167
	v_cvt_pk_bf16_f32 v97, v210, v211
	v_cvt_pk_bf16_f32 v98, v212, v213
	v_cvt_pk_bf16_f32 v99, v214, v215
	s_waitcnt lgkmcnt(6)
	s_nop 0
	v_mfma_f32_32x32x16_bf16 v[16:31], v[68:71], v[96:99], v[16:31]
	v_add_f32_e32 v184, v184, v166
	v_add_f32_e32 v184, v184, v167
	v_add_f32_e32 v184, v184, v210
	v_add_f32_e32 v184, v184, v211
	s_nop 0
	v_mfma_f32_32x32x16_bf16 v[32:47], v[64:67], v[96:99], v[32:47]
	v_cvt_pk_bf16_f32 v68, v100, v101
	v_cvt_pk_bf16_f32 v69, v102, v103
	v_cvt_pk_bf16_f32 v70, v104, v105
	v_cvt_pk_bf16_f32 v71, v106, v107
	v_add_f32_e32 v184, v184, v212
	v_add_f32_e32 v184, v184, v213
	v_add_f32_e32 v184, v184, v214
	v_add_f32_e32 v184, v184, v215
	s_waitcnt lgkmcnt(5)
	v_mfma_f32_32x32x16_bf16 v[16:31], v[72:75], v[68:71], v[16:31]
	v_add_f32_e32 v184, v184, v100
	v_add_f32_e32 v184, v184, v101
	v_add_f32_e32 v184, v184, v102
	v_add_f32_e32 v184, v184, v103
	s_waitcnt lgkmcnt(4)
	v_mfma_f32_32x32x16_bf16 v[32:47], v[76:79], v[68:71], v[32:47]
	v_cvt_pk_bf16_f32 v64, v108, v109
	v_cvt_pk_bf16_f32 v65, v110, v111
	v_cvt_pk_bf16_f32 v66, v144, v145
	v_cvt_pk_bf16_f32 v67, v146, v147
	v_add_f32_e32 v184, v184, v104
	v_add_f32_e32 v184, v184, v105
	v_add_f32_e32 v184, v184, v106
	v_add_f32_e32 v184, v184, v107
	s_waitcnt lgkmcnt(3)
	v_mfma_f32_32x32x16_bf16 v[16:31], v[80:83], v[64:67], v[16:31]
	v_add_f32_e32 v184, v184, v108
	v_add_f32_e32 v184, v184, v109
	v_add_f32_e32 v184, v184, v110
	v_add_f32_e32 v184, v184, v111
	s_waitcnt lgkmcnt(2)
	v_mfma_f32_32x32x16_bf16 v[32:47], v[84:87], v[64:67], v[32:47]
	v_cvt_pk_bf16_f32 v68, v216, v217
	v_cvt_pk_bf16_f32 v69, v218, v219
	v_cvt_pk_bf16_f32 v70, v148, v149
	v_cvt_pk_bf16_f32 v71, v150, v151
	v_add_f32_e32 v184, v184, v144
	v_add_f32_e32 v184, v184, v145
	v_add_f32_e32 v184, v184, v146
	v_add_f32_e32 v184, v184, v147
	s_waitcnt lgkmcnt(1)
	v_mfma_f32_32x32x16_bf16 v[16:31], v[88:91], v[68:71], v[16:31]
	v_add_f32_e32 v184, v184, v216
	v_add_f32_e32 v184, v184, v217
	v_add_f32_e32 v184, v184, v218
	v_add_f32_e32 v184, v184, v219
	s_waitcnt lgkmcnt(0)
	v_mfma_f32_32x32x16_bf16 v[32:47], v[92:95], v[68:71], v[32:47]
	v_add_f32_e32 v184, v184, v148
	v_add_f32_e32 v184, v184, v149
	v_add_f32_e32 v184, v184, v150
	v_add_f32_e32 v184, v184, v151
	s_setprio 0
	ds_read_b128 v[68:71], v195 offset:27680
	ds_read_b128 v[76:79], v195 offset:32288
	ds_read_b128 v[80:83], v195 offset:27712
	ds_read_b128 v[84:87], v195 offset:27744
	ds_read_b128 v[88:91], v195 offset:32320
	ds_read_b128 v[92:95], v195 offset:32352
	s_cmp_lg_u32 s27, 4
	s_cselect_b32 s26, s29, 0
	s_waitcnt lgkmcnt(6)
	v_mfma_f32_32x32x16_bf16 v[144:159], v[240:243], v[180:183], v[48:63]
	v_exp_f32_e32 v166, v128
	v_exp_f32_e32 v167, v129
	v_exp_f32_e32 v185, v130
	v_exp_f32_e32 v186, v131
	s_waitcnt lgkmcnt(5)
	v_mfma_f32_32x32x16_bf16 v[96:111], v[244:247], v[180:183], v[48:63]
	v_exp_f32_e32 v128, v132
	v_exp_f32_e32 v129, v133
	v_exp_f32_e32 v130, v134
	v_exp_f32_e32 v131, v135
	v_mfma_f32_32x32x16_bf16 v[144:159], v[68:71], v[176:179], v[144:159]
	v_exp_f32_e32 v132, v136
	v_exp_f32_e32 v133, v137
	v_exp_f32_e32 v134, v138
	v_exp_f32_e32 v135, v139
	s_waitcnt lgkmcnt(4)
	v_mfma_f32_32x32x16_bf16 v[96:111], v[76:79], v[176:179], v[96:111]
	v_exp_f32_e32 v136, v140
	v_exp_f32_e32 v137, v141
	v_exp_f32_e32 v138, v142
	v_exp_f32_e32 v139, v143
	s_waitcnt lgkmcnt(3)
	v_mfma_f32_32x32x16_bf16 v[144:159], v[80:83], v[172:175], v[144:159]
	v_exp_f32_e32 v140, v112
	v_exp_f32_e32 v141, v113
	v_exp_f32_e32 v142, v114
	v_exp_f32_e32 v143, v115
	s_waitcnt lgkmcnt(1)
	v_mfma_f32_32x32x16_bf16 v[96:111], v[88:91], v[172:175], v[96:111]
	v_exp_f32_e32 v187, v116
	v_exp_f32_e32 v210, v117
	v_exp_f32_e32 v211, v118
	v_exp_f32_e32 v212, v119
	v_mfma_f32_32x32x16_bf16 v[144:159], v[84:87], v[168:171], v[144:159]
	v_exp_f32_e32 v116, v120
	v_exp_f32_e32 v117, v121
	v_exp_f32_e32 v118, v122
	v_exp_f32_e32 v119, v123
	s_waitcnt lgkmcnt(0)
	v_mfma_f32_32x32x16_bf16 v[96:111], v[92:95], v[168:171], v[96:111]
	v_exp_f32_e32 v120, v124
	v_exp_f32_e32 v121, v125
	v_exp_f32_e32 v122, v126
	v_exp_f32_e32 v123, v127
	s_cmp_gt_i32 s26, 2
	s_cselect_b32 s27, -3, 2
	s_add_i32 s27, s27, s26
	s_mulk_i32 s27, 0x2400
	s_waitcnt vmcnt(3)
	ds_write_b128 v208, v[2:5] offset:9216
	v_add_u32_e32 v2, s27, v208
	s_add_i32 s27, s26, 1
	s_cmp_lg_u32 s26, 4
	s_cselect_b32 s26, s27, 0
	s_add_i32 s27, s13, -5
	s_min_u32 s27, s27, s12
	s_lshl_b32 s92, s27, 13
	s_waitcnt vmcnt(2)
	ds_write_b128 v2, v[6:9] offset:36864
	v_lshl_add_u64 v[2:3], v[198:199], 0, s[92:93]
	s_lshl_b32 s92, s28, 7
	v_lshl_add_u64 v[4:5], v[196:197], 0, s[92:93]
	s_waitcnt lgkmcnt(0)
	s_barrier
	global_load_dwordx4 v[6:9], v[2:3], off
	s_nop 0
	global_load_dwordx4 v[2:5], v[4:5], off
	s_mul_i32 s28, s26, 0x2400
	s_add_i32 s29, s28, 0xffffdc00
	s_cmp_lg_u32 s26, 0
	s_cselect_b32 s29, s29, 0x9000
	v_add_u32_e32 v92, s29, v195
	ds_read_b128 v[240:243], v195
	ds_read_b128 v[244:247], v195 offset:4608
	ds_read_b128 v[64:67], v92 offset:36864
	ds_read_b128 v[68:71], v92 offset:36896
	ds_read_b128 v[72:75], v92 offset:41472
	ds_read_b128 v[76:79], v92 offset:41504
	ds_read_b128 v[80:83], v92 offset:36928
	ds_read_b128 v[84:87], v92 offset:36960
	ds_read_b128 v[88:91], v92 offset:41536
	ds_read_b128 v[92:95], v92 offset:41568
	s_setprio 3
	v_mov_b32_e32 v213, 0
	v_cvt_pk_bf16_f32 v112, v166, v167
	v_cvt_pk_bf16_f32 v113, v185, v186
	v_cvt_pk_bf16_f32 v114, v128, v129
	v_cvt_pk_bf16_f32 v115, v130, v131
	s_waitcnt lgkmcnt(7)
	s_nop 0
	v_mfma_f32_32x32x16_bf16 v[16:31], v[64:67], v[112:115], v[16:31]
	v_add_f32_e32 v213, v213, v166
	v_add_f32_e32 v213, v213, v167
	v_add_f32_e32 v213, v213, v185
	v_add_f32_e32 v213, v213, v186
	s_waitcnt lgkmcnt(5)
	v_mfma_f32_32x32x16_bf16 v[32:47], v[72:75], v[112:115], v[32:47]
	v_cvt_pk_bf16_f32 v64, v132, v133
	v_cvt_pk_bf16_f32 v65, v134, v135
	v_cvt_pk_bf16_f32 v66, v136, v137
	v_cvt_pk_bf16_f32 v67, v138, v139
	v_add_f32_e32 v213, v213, v128
	v_add_f32_e32 v213, v213, v129
	v_add_f32_e32 v213, v213, v130
	v_add_f32_e32 v213, v213, v131
	s_nop 0
	v_mfma_f32_32x32x16_bf16 v[16:31], v[68:71], v[64:67], v[16:31]
	v_add_f32_e32 v213, v213, v132
	v_add_f32_e32 v213, v213, v133
	v_add_f32_e32 v213, v213, v134
	v_add_f32_e32 v213, v213, v135
	s_waitcnt lgkmcnt(4)
	v_mfma_f32_32x32x16_bf16 v[32:47], v[76:79], v[64:67], v[32:47]
	v_cvt_pk_bf16_f32 v68, v140, v141
	v_cvt_pk_bf16_f32 v69, v142, v143
	v_cvt_pk_bf16_f32 v70, v187, v210
	v_cvt_pk_bf16_f32 v71, v211, v212
	v_add_f32_e32 v213, v213, v136
	v_add_f32_e32 v213, v213, v137
	v_add_f32_e32 v213, v213, v138
	v_add_f32_e32 v213, v213, v139
	s_waitcnt lgkmcnt(3)
	v_mfma_f32_32x32x16_bf16 v[16:31], v[80:83], v[68:71], v[16:31]
	v_add_f32_e32 v213, v213, v140
	v_add_f32_e32 v213, v213, v141
	v_add_f32_e32 v213, v213, v142
	v_add_f32_e32 v213, v213, v143
	s_waitcnt lgkmcnt(1)
	v_mfma_f32_32x32x16_bf16 v[32:47], v[88:91], v[68:71], v[32:47]
	v_cvt_pk_bf16_f32 v64, v116, v117
	v_cvt_pk_bf16_f32 v65, v118, v119
	v_cvt_pk_bf16_f32 v66, v120, v121
	v_cvt_pk_bf16_f32 v67, v122, v123
	v_add_f32_e32 v213, v213, v187
	v_add_f32_e32 v213, v213, v210
	v_add_f32_e32 v213, v213, v211
	v_add_f32_e32 v213, v213, v212
	s_nop 0
	v_mfma_f32_32x32x16_bf16 v[16:31], v[84:87], v[64:67], v[16:31]
	v_add_f32_e32 v213, v213, v116
	v_add_f32_e32 v213, v213, v117
	v_add_f32_e32 v213, v213, v118
	v_add_f32_e32 v213, v213, v119
	s_waitcnt lgkmcnt(0)
	v_mfma_f32_32x32x16_bf16 v[32:47], v[92:95], v[64:67], v[32:47]
	v_add_f32_e32 v213, v213, v120
	v_add_f32_e32 v213, v213, v121
	v_add_f32_e32 v213, v213, v122
	v_add_f32_e32 v213, v213, v123
	s_setprio 2
	ds_read_b128 v[116:119], v195 offset:32
	ds_read_b128 v[120:123], v195 offset:4640
	ds_read_b128 v[124:127], v195 offset:64
	ds_read_b128 v[128:131], v195 offset:4672
	ds_read_b128 v[132:135], v195 offset:96
	ds_read_b128 v[136:139], v195 offset:4704
	v_add_f32_e32 v1, v1, v184
	s_waitcnt lgkmcnt(6)
	v_mfma_f32_32x32x16_bf16 v[80:95], v[240:243], v[180:183], v[48:63]
	v_exp_f32_e32 v140, v144
	v_exp_f32_e32 v141, v145
	v_exp_f32_e32 v142, v146
	v_exp_f32_e32 v143, v147
	v_mfma_f32_32x32x16_bf16 v[64:79], v[244:247], v[180:183], v[48:63]
	v_exp_f32_e32 v144, v148
	v_exp_f32_e32 v145, v149
	v_exp_f32_e32 v146, v150
	v_exp_f32_e32 v147, v151
	s_waitcnt lgkmcnt(5)
	v_mfma_f32_32x32x16_bf16 v[80:95], v[116:119], v[176:179], v[80:95]
	v_exp_f32_e32 v148, v152
	v_exp_f32_e32 v149, v153
	v_exp_f32_e32 v150, v154
	v_exp_f32_e32 v151, v155
	s_waitcnt lgkmcnt(4)
	v_mfma_f32_32x32x16_bf16 v[64:79], v[120:123], v[176:179], v[64:79]
	v_exp_f32_e32 v152, v156
	v_exp_f32_e32 v153, v157
	v_exp_f32_e32 v154, v158
	v_exp_f32_e32 v155, v159
	s_waitcnt lgkmcnt(3)
	v_mfma_f32_32x32x16_bf16 v[80:95], v[124:127], v[172:175], v[80:95]
	v_exp_f32_e32 v156, v96
	v_exp_f32_e32 v157, v97
	v_exp_f32_e32 v158, v98
	v_exp_f32_e32 v159, v99
	s_waitcnt lgkmcnt(2)
	v_mfma_f32_32x32x16_bf16 v[64:79], v[128:131], v[172:175], v[64:79]
	v_exp_f32_e32 v166, v100
	v_exp_f32_e32 v167, v101
	v_exp_f32_e32 v184, v102
	v_exp_f32_e32 v185, v103
	s_waitcnt lgkmcnt(1)
	v_mfma_f32_32x32x16_bf16 v[80:95], v[132:135], v[168:171], v[80:95]
	v_exp_f32_e32 v186, v104
	v_exp_f32_e32 v187, v105
	v_exp_f32_e32 v210, v106
	v_exp_f32_e32 v211, v107
	s_waitcnt lgkmcnt(0)
	v_mfma_f32_32x32x16_bf16 v[64:79], v[136:139], v[168:171], v[64:79]
	v_exp_f32_e32 v212, v108
	v_exp_f32_e32 v214, v109
	v_exp_f32_e32 v215, v110
	v_exp_f32_e32 v216, v111
	s_cmp_gt_i32 s26, 2
	s_cselect_b32 s29, -3, 2
	s_add_i32 s29, s29, s26
	s_mulk_i32 s29, 0x2400
	s_waitcnt vmcnt(3)
	ds_write_b128 v208, v[10:13] offset:18432
	v_add_u32_e32 v10, s29, v208
	s_mov_b32 s29, 0x1da90000
	s_waitcnt vmcnt(2)
	ds_write_b128 v10, v[160:163] offset:36864
	v_add_co_u32_e32 v10, vcc, s29, v164
	s_lshl_b32 s92, s27, 7
	s_nop 0
	v_addc_co_u32_e32 v11, vcc, 0, v165, vcc
	global_load_dwordx4 v[128:131], v[10:11], off
	v_lshl_add_u64 v[10:11], v[196:197], 0, s[92:93]
	global_load_dwordx4 v[10:13], v[10:11], off
	v_add_u32_e32 v124, s28, v195
	ds_read_b128 v[240:243], v195 offset:9216
	ds_read_b128 v[244:247], v195 offset:13824
	ds_read_b128 v[96:99], v124 offset:41472
	ds_read_b128 v[100:103], v124 offset:36864
	ds_read_b128 v[104:107], v124 offset:36896
	ds_read_b128 v[108:111], v124 offset:41504
	ds_read_b128 v[112:115], v124 offset:36928
	ds_read_b128 v[116:119], v124 offset:41536
	ds_read_b128 v[120:123], v124 offset:36960
	ds_read_b128 v[124:127], v124 offset:41568
	v_add_f32_e32 v1, v1, v213
	s_add_i32 s28, s26, 1
	s_setprio 1
	v_mov_b32_e32 v160, 0
	v_cvt_pk_bf16_f32 v132, v140, v141
	v_cvt_pk_bf16_f32 v133, v142, v143
	v_cvt_pk_bf16_f32 v134, v144, v145
	v_cvt_pk_bf16_f32 v135, v146, v147
	s_waitcnt lgkmcnt(6)
	s_nop 0
	v_mfma_f32_32x32x16_bf16 v[16:31], v[100:103], v[132:135], v[16:31]
	v_add_f32_e32 v160, v160, v140
	v_add_f32_e32 v160, v160, v141
	v_add_f32_e32 v160, v160, v142
	v_add_f32_e32 v160, v160, v143
	s_nop 0
	v_mfma_f32_32x32x16_bf16 v[32:47], v[96:99], v[132:135], v[32:47]
	v_cvt_pk_bf16_f32 v100, v148, v149
	v_cvt_pk_bf16_f32 v101, v150, v151
	v_cvt_pk_bf16_f32 v102, v152, v153
	v_cvt_pk_bf16_f32 v103, v154, v155
	v_add_f32_e32 v160, v160, v144
	v_add_f32_e32 v160, v160, v145
	v_add_f32_e32 v160, v160, v146
	v_add_f32_e32 v160, v160, v147
	s_waitcnt lgkmcnt(5)
	v_mfma_f32_32x32x16_bf16 v[16:31], v[104:107], v[100:103], v[16:31]
	v_add_f32_e32 v160, v160, v148
	v_add_f32_e32 v160, v160, v149
	v_add_f32_e32 v160, v160, v150
	v_add_f32_e32 v160, v160, v151
	s_waitcnt lgkmcnt(4)
	v_mfma_f32_32x32x16_bf16 v[32:47], v[108:111], v[100:103], v[32:47]
	v_cvt_pk_bf16_f32 v96, v156, v157
	v_cvt_pk_bf16_f32 v97, v158, v159
	v_cvt_pk_bf16_f32 v98, v166, v167
	v_cvt_pk_bf16_f32 v99, v184, v185
	v_add_f32_e32 v160, v160, v152
	v_add_f32_e32 v160, v160, v153
	v_add_f32_e32 v160, v160, v154
	v_add_f32_e32 v160, v160, v155
	s_waitcnt lgkmcnt(3)
	v_mfma_f32_32x32x16_bf16 v[16:31], v[112:115], v[96:99], v[16:31]
	v_add_f32_e32 v160, v160, v156
	v_add_f32_e32 v160, v160, v157
	v_add_f32_e32 v160, v160, v158
	v_add_f32_e32 v160, v160, v159
	s_waitcnt lgkmcnt(2)
	v_mfma_f32_32x32x16_bf16 v[32:47], v[116:119], v[96:99], v[32:47]
	v_cvt_pk_bf16_f32 v100, v186, v187
	v_cvt_pk_bf16_f32 v101, v210, v211
	v_cvt_pk_bf16_f32 v102, v212, v214
	v_cvt_pk_bf16_f32 v103, v215, v216
	v_add_f32_e32 v160, v160, v166
	v_add_f32_e32 v160, v160, v167
	v_add_f32_e32 v160, v160, v184
	v_add_f32_e32 v160, v160, v185
	s_waitcnt lgkmcnt(1)
	v_mfma_f32_32x32x16_bf16 v[16:31], v[120:123], v[100:103], v[16:31]
	v_add_f32_e32 v160, v160, v186
	v_add_f32_e32 v160, v160, v187
	v_add_f32_e32 v160, v160, v210
	v_add_f32_e32 v160, v160, v211
	s_waitcnt lgkmcnt(0)
	v_mfma_f32_32x32x16_bf16 v[32:47], v[124:127], v[100:103], v[32:47]
	v_add_f32_e32 v160, v160, v212
	v_add_f32_e32 v160, v160, v214
	v_add_f32_e32 v160, v160, v215
	v_add_f32_e32 v160, v160, v216
	s_setprio 0
	ds_read_b128 v[132:135], v195 offset:9248
	ds_read_b128 v[140:143], v195 offset:13856
	ds_read_b128 v[144:147], v195 offset:9280
	ds_read_b128 v[148:151], v195 offset:9312
	ds_read_b128 v[152:155], v195 offset:13888
	ds_read_b128 v[156:159], v195 offset:13920
	s_cmp_lg_u32 s26, 4
	s_cselect_b32 s26, s28, 0
	s_waitcnt lgkmcnt(6)
	v_mfma_f32_32x32x16_bf16 v[112:127], v[240:243], v[180:183], v[48:63]
	v_exp_f32_e32 v161, v80
	v_exp_f32_e32 v162, v81
	v_exp_f32_e32 v163, v82
	v_exp_f32_e32 v164, v83
	s_waitcnt lgkmcnt(5)
	v_mfma_f32_32x32x16_bf16 v[96:111], v[244:247], v[180:183], v[48:63]
	v_exp_f32_e32 v165, v84
	v_exp_f32_e32 v166, v85
	v_exp_f32_e32 v167, v86
	v_exp_f32_e32 v184, v87
	v_mfma_f32_32x32x16_bf16 v[112:127], v[132:135], v[176:179], v[112:127]
	v_exp_f32_e32 v136, v88
	v_exp_f32_e32 v137, v89
	v_exp_f32_e32 v138, v90
	v_exp_f32_e32 v139, v91
	s_waitcnt lgkmcnt(4)
	v_mfma_f32_32x32x16_bf16 v[96:111], v[140:143], v[176:179], v[96:111]
	v_exp_f32_e32 v185, v92
	v_exp_f32_e32 v186, v93
	v_exp_f32_e32 v187, v94
	v_exp_f32_e32 v210, v95
	s_waitcnt lgkmcnt(3)
	v_mfma_f32_32x32x16_bf16 v[112:127], v[144:147], v[172:175], v[112:127]
	v_exp_f32_e32 v140, v64
	v_exp_f32_e32 v141, v65
	v_exp_f32_e32 v142, v66
	v_exp_f32_e32 v143, v67
	s_waitcnt lgkmcnt(1)
	v_mfma_f32_32x32x16_bf16 v[96:111], v[152:155], v[172:175], v[96:111]
	v_exp_f32_e32 v144, v68
	v_exp_f32_e32 v145, v69
	v_exp_f32_e32 v146, v70
	v_exp_f32_e32 v147, v71
	v_mfma_f32_32x32x16_bf16 v[112:127], v[148:151], v[168:171], v[112:127]
	v_exp_f32_e32 v152, v72
	v_exp_f32_e32 v153, v73
	v_exp_f32_e32 v154, v74
	v_exp_f32_e32 v155, v75
	s_waitcnt lgkmcnt(0)
	v_mfma_f32_32x32x16_bf16 v[96:111], v[156:159], v[168:171], v[96:111]
	v_exp_f32_e32 v148, v76
	v_exp_f32_e32 v149, v77
	v_exp_f32_e32 v150, v78
	v_exp_f32_e32 v151, v79
	s_cmp_gt_i32 s26, 2
	s_cselect_b32 s27, -3, 2
	s_add_i32 s27, s27, s26
	s_mulk_i32 s27, 0x2400
	s_waitcnt vmcnt(3)
	ds_write_b128 v208, v[6:9] offset:27648
	v_add_u32_e32 v6, s27, v208
	s_add_i32 s27, s26, 1
	s_cmp_lg_u32 s26, 4
	s_cselect_b32 s27, s27, 0
	s_add_i32 s26, s13, -3
	s_min_u32 s28, s26, s12
	s_lshl_b32 s92, s28, 13
	s_waitcnt vmcnt(2)
	ds_write_b128 v6, v[2:5] offset:36864
	v_lshl_add_u64 v[2:3], v[198:199], 0, s[92:93]
	s_waitcnt lgkmcnt(0)
	s_barrier
	global_load_dwordx4 v[6:9], v[2:3], off
	s_nop 0
	global_load_dwordx4 v[2:5], v[14:15], off offset:1024
	s_mul_i32 s29, s27, 0x2400
	s_add_i32 s34, s29, 0xffffdc00
	s_cmp_lg_u32 s27, 0
	s_cselect_b32 s34, s34, 0x9000
	v_add_u32_e32 v14, s34, v195
	ds_read_b128 v[240:243], v195 offset:18432
	ds_read_b128 v[244:247], v195 offset:23040
	ds_read_b128 v[64:67], v14 offset:36864
	ds_read_b128 v[68:71], v14 offset:36896
	ds_read_b128 v[72:75], v14 offset:41472
	ds_read_b128 v[76:79], v14 offset:41504
	ds_read_b128 v[80:83], v14 offset:36928
	ds_read_b128 v[84:87], v14 offset:36960
	ds_read_b128 v[88:91], v14 offset:41536
	ds_read_b128 v[92:95], v14 offset:41568
	s_setprio 3
	v_mov_b32_e32 v14, 0
	v_cvt_pk_bf16_f32 v132, v161, v162
	v_cvt_pk_bf16_f32 v133, v163, v164
	v_cvt_pk_bf16_f32 v134, v165, v166
	v_cvt_pk_bf16_f32 v135, v167, v184
	s_waitcnt lgkmcnt(7)
	s_nop 0
	v_mfma_f32_32x32x16_bf16 v[16:31], v[64:67], v[132:135], v[16:31]
	v_add_f32_e32 v14, v14, v161
	v_add_f32_e32 v14, v14, v162
	v_add_f32_e32 v14, v14, v163
	v_add_f32_e32 v14, v14, v164
	s_waitcnt lgkmcnt(5)
	v_mfma_f32_32x32x16_bf16 v[32:47], v[72:75], v[132:135], v[32:47]
	v_cvt_pk_bf16_f32 v64, v136, v137
	v_cvt_pk_bf16_f32 v65, v138, v139
	v_cvt_pk_bf16_f32 v66, v185, v186
	v_cvt_pk_bf16_f32 v67, v187, v210
	v_add_f32_e32 v14, v14, v165
	v_add_f32_e32 v14, v14, v166
	v_add_f32_e32 v14, v14, v167
	v_add_f32_e32 v14, v14, v184
	s_nop 0
	v_mfma_f32_32x32x16_bf16 v[16:31], v[68:71], v[64:67], v[16:31]
	v_add_f32_e32 v14, v14, v136
	v_add_f32_e32 v14, v14, v137
	v_add_f32_e32 v14, v14, v138
	v_add_f32_e32 v14, v14, v139
	s_waitcnt lgkmcnt(4)
	v_mfma_f32_32x32x16_bf16 v[32:47], v[76:79], v[64:67], v[32:47]
	v_cvt_pk_bf16_f32 v68, v140, v141
	v_cvt_pk_bf16_f32 v69, v142, v143
	v_cvt_pk_bf16_f32 v70, v144, v145
	v_cvt_pk_bf16_f32 v71, v146, v147
	v_add_f32_e32 v14, v14, v185
	v_add_f32_e32 v14, v14, v186
	v_add_f32_e32 v14, v14, v187
	v_add_f32_e32 v14, v14, v210
	s_waitcnt lgkmcnt(3)
	v_mfma_f32_32x32x16_bf16 v[16:31], v[80:83], v[68:71], v[16:31]
	v_add_f32_e32 v14, v14, v140
	v_add_f32_e32 v14, v14, v141
	v_add_f32_e32 v14, v14, v142
	v_add_f32_e32 v14, v14, v143
	s_waitcnt lgkmcnt(1)
	v_mfma_f32_32x32x16_bf16 v[32:47], v[88:91], v[68:71], v[32:47]
	v_cvt_pk_bf16_f32 v64, v152, v153
	v_cvt_pk_bf16_f32 v65, v154, v155
	v_cvt_pk_bf16_f32 v66, v148, v149
	v_cvt_pk_bf16_f32 v67, v150, v151
	v_add_f32_e32 v14, v14, v144
	v_add_f32_e32 v14, v14, v145
	v_add_f32_e32 v14, v14, v146
	v_add_f32_e32 v14, v14, v147
	s_nop 0
	v_mfma_f32_32x32x16_bf16 v[16:31], v[84:87], v[64:67], v[16:31]
	v_add_f32_e32 v14, v14, v152
	v_add_f32_e32 v14, v14, v153
	v_add_f32_e32 v14, v14, v154
	v_add_f32_e32 v14, v14, v155
	s_waitcnt lgkmcnt(0)
	v_mfma_f32_32x32x16_bf16 v[32:47], v[92:95], v[64:67], v[32:47]
	v_add_f32_e32 v14, v14, v148
	v_add_f32_e32 v14, v14, v149
	v_add_f32_e32 v14, v14, v150
	v_add_f32_e32 v14, v14, v151
	s_setprio 2
	ds_read_b128 v[136:139], v195 offset:18464
	ds_read_b128 v[140:143], v195 offset:23072
	ds_read_b128 v[144:147], v195 offset:18496
	ds_read_b128 v[148:151], v195 offset:23104
	ds_read_b128 v[152:155], v195 offset:18528
	ds_read_b128 v[156:159], v195 offset:23136
	v_add_f32_e32 v1, v1, v160
	s_waitcnt lgkmcnt(6)
	v_mfma_f32_32x32x16_bf16 v[80:95], v[240:243], v[180:183], v[48:63]
	v_exp_f32_e32 v160, v112
	v_exp_f32_e32 v161, v113
	v_exp_f32_e32 v162, v114
	v_exp_f32_e32 v163, v115
	v_mfma_f32_32x32x16_bf16 v[64:79], v[244:247], v[180:183], v[48:63]
	v_exp_f32_e32 v164, v116
	v_exp_f32_e32 v165, v117
	v_exp_f32_e32 v166, v118
	v_exp_f32_e32 v167, v119
	s_waitcnt lgkmcnt(5)
	v_mfma_f32_32x32x16_bf16 v[80:95], v[136:139], v[176:179], v[80:95]
	v_exp_f32_e32 v184, v120
	v_exp_f32_e32 v185, v121
	v_exp_f32_e32 v186, v122
	v_exp_f32_e32 v187, v123
	s_waitcnt lgkmcnt(4)
	v_mfma_f32_32x32x16_bf16 v[64:79], v[140:143], v[176:179], v[64:79]
	v_exp_f32_e32 v136, v124
	v_exp_f32_e32 v137, v125
	v_exp_f32_e32 v138, v126
	v_exp_f32_e32 v139, v127
	s_waitcnt lgkmcnt(3)
	v_mfma_f32_32x32x16_bf16 v[80:95], v[144:147], v[172:175], v[80:95]
	v_exp_f32_e32 v140, v96
	v_exp_f32_e32 v141, v97
	v_exp_f32_e32 v142, v98
	v_exp_f32_e32 v143, v99
	s_waitcnt lgkmcnt(2)
	v_mfma_f32_32x32x16_bf16 v[64:79], v[148:151], v[172:175], v[64:79]
	v_exp_f32_e32 v144, v100
	v_exp_f32_e32 v145, v101
	v_exp_f32_e32 v146, v102
	v_exp_f32_e32 v147, v103
	s_waitcnt lgkmcnt(1)
	v_mfma_f32_32x32x16_bf16 v[80:95], v[152:155], v[168:171], v[80:95]
	v_exp_f32_e32 v148, v104
	v_exp_f32_e32 v149, v105
	v_exp_f32_e32 v150, v106
	v_exp_f32_e32 v151, v107
	s_waitcnt lgkmcnt(0)
	v_mfma_f32_32x32x16_bf16 v[64:79], v[156:159], v[168:171], v[64:79]
	v_exp_f32_e32 v152, v108
	v_exp_f32_e32 v153, v109
	v_exp_f32_e32 v154, v110
	v_exp_f32_e32 v155, v111
	s_cmp_gt_i32 s27, 2
	s_cselect_b32 s34, -3, 2
	s_waitcnt vmcnt(3)
	ds_write_b128 v208, v[128:131]
	s_add_i32 s34, s34, s27
	v_add_u32_e32 v128, s29, v195
	s_add_i32 s29, s13, -2
	s_mulk_i32 s34, 0x2400
	s_min_u32 s29, s29, s12
	v_add_u32_e32 v15, s34, v208
	s_lshl_b32 s92, s29, 13
	s_waitcnt vmcnt(2)
	ds_write_b128 v15, v[10:13] offset:36864
	v_lshl_add_u64 v[10:11], v[198:199], 0, s[92:93]
	s_lshl_b32 s92, s28, 7
	v_add_f32_e32 v1, v1, v14
	global_load_dwordx4 v[10:13], v[10:11], off
	v_lshl_add_u64 v[14:15], v[196:197], 0, s[92:93]
	global_load_dwordx4 v[112:115], v[14:15], off
	ds_read_b128 v[240:243], v195 offset:27648
	ds_read_b128 v[244:247], v195 offset:32256
	ds_read_b128 v[96:99], v128 offset:41472
	ds_read_b128 v[100:103], v128 offset:36864
	ds_read_b128 v[104:107], v128 offset:36896
	ds_read_b128 v[108:111], v128 offset:41504
	ds_read_b128 v[116:119], v128 offset:36928
	ds_read_b128 v[120:123], v128 offset:41536
	ds_read_b128 v[124:127], v128 offset:36960
	ds_read_b128 v[128:131], v128 offset:41568
	s_add_i32 s34, s27, 1
	s_setprio 1
	v_mov_b32_e32 v14, 0
	v_cvt_pk_bf16_f32 v132, v160, v161
	v_cvt_pk_bf16_f32 v133, v162, v163
	v_cvt_pk_bf16_f32 v134, v164, v165
	v_cvt_pk_bf16_f32 v135, v166, v167
	s_waitcnt lgkmcnt(6)
	s_nop 0
	v_mfma_f32_32x32x16_bf16 v[16:31], v[100:103], v[132:135], v[16:31]
	v_add_f32_e32 v14, v14, v160
	v_add_f32_e32 v14, v14, v161
	v_add_f32_e32 v14, v14, v162
	v_add_f32_e32 v14, v14, v163
	s_nop 0
	v_mfma_f32_32x32x16_bf16 v[32:47], v[96:99], v[132:135], v[32:47]
	v_cvt_pk_bf16_f32 v100, v184, v185
	v_cvt_pk_bf16_f32 v101, v186, v187
	v_cvt_pk_bf16_f32 v102, v136, v137
	v_cvt_pk_bf16_f32 v103, v138, v139
	v_add_f32_e32 v14, v14, v164
	v_add_f32_e32 v14, v14, v165
	v_add_f32_e32 v14, v14, v166
	v_add_f32_e32 v14, v14, v167
	s_waitcnt lgkmcnt(5)
	v_mfma_f32_32x32x16_bf16 v[16:31], v[104:107], v[100:103], v[16:31]
	v_add_f32_e32 v14, v14, v184
	v_add_f32_e32 v14, v14, v185
	v_add_f32_e32 v14, v14, v186
	v_add_f32_e32 v14, v14, v187
	s_waitcnt lgkmcnt(4)
	v_mfma_f32_32x32x16_bf16 v[32:47], v[108:111], v[100:103], v[32:47]
	v_cvt_pk_bf16_f32 v96, v140, v141
	v_cvt_pk_bf16_f32 v97, v142, v143
	v_cvt_pk_bf16_f32 v98, v144, v145
	v_cvt_pk_bf16_f32 v99, v146, v147
	v_add_f32_e32 v14, v14, v136
	v_add_f32_e32 v14, v14, v137
	v_add_f32_e32 v14, v14, v138
	v_add_f32_e32 v14, v14, v139
	s_waitcnt lgkmcnt(3)
	v_mfma_f32_32x32x16_bf16 v[16:31], v[116:119], v[96:99], v[16:31]
	v_add_f32_e32 v14, v14, v140
	v_add_f32_e32 v14, v14, v141
	v_add_f32_e32 v14, v14, v142
	v_add_f32_e32 v14, v14, v143
	s_waitcnt lgkmcnt(2)
	v_mfma_f32_32x32x16_bf16 v[32:47], v[120:123], v[96:99], v[32:47]
	v_cvt_pk_bf16_f32 v100, v148, v149
	v_cvt_pk_bf16_f32 v101, v150, v151
	v_cvt_pk_bf16_f32 v102, v152, v153
	v_cvt_pk_bf16_f32 v103, v154, v155
	v_add_f32_e32 v14, v14, v144
	v_add_f32_e32 v14, v14, v145
	v_add_f32_e32 v14, v14, v146
	v_add_f32_e32 v14, v14, v147
	s_waitcnt lgkmcnt(1)
	v_mfma_f32_32x32x16_bf16 v[16:31], v[124:127], v[100:103], v[16:31]
	v_add_f32_e32 v14, v14, v148
	v_add_f32_e32 v14, v14, v149
	v_add_f32_e32 v14, v14, v150
	v_add_f32_e32 v14, v14, v151
	s_waitcnt lgkmcnt(0)
	v_mfma_f32_32x32x16_bf16 v[32:47], v[128:131], v[100:103], v[32:47]
	v_add_f32_e32 v14, v14, v152
	v_add_f32_e32 v14, v14, v153
	v_add_f32_e32 v14, v14, v154
	v_add_f32_e32 v14, v14, v155
	s_setprio 0
	ds_read_b128 v[116:119], v195 offset:27680
	ds_read_b128 v[124:127], v195 offset:32288
	ds_read_b128 v[128:131], v195 offset:27712
	ds_read_b128 v[132:135], v195 offset:27744
	ds_read_b128 v[136:139], v195 offset:32320
	ds_read_b128 v[140:143], v195 offset:32352
	s_cmp_lg_u32 s27, 4
	s_cselect_b32 s27, s34, 0
	s_waitcnt lgkmcnt(6)
	v_mfma_f32_32x32x16_bf16 v[152:167], v[240:243], v[180:183], v[48:63]
	v_exp_f32_e32 v15, v80
	v_exp_f32_e32 v144, v81
	v_exp_f32_e32 v145, v82
	v_exp_f32_e32 v146, v83
	s_waitcnt lgkmcnt(5)
	v_mfma_f32_32x32x16_bf16 v[96:111], v[244:247], v[180:183], v[48:63]
	v_exp_f32_e32 v147, v84
	v_exp_f32_e32 v148, v85
	v_exp_f32_e32 v149, v86
	v_exp_f32_e32 v150, v87
	v_mfma_f32_32x32x16_bf16 v[152:167], v[116:119], v[176:179], v[152:167]
	v_exp_f32_e32 v120, v88
	v_exp_f32_e32 v121, v89
	v_exp_f32_e32 v122, v90
	v_exp_f32_e32 v123, v91
	s_waitcnt lgkmcnt(4)
	v_mfma_f32_32x32x16_bf16 v[96:111], v[124:127], v[176:179], v[96:111]
	v_exp_f32_e32 v151, v92
	v_exp_f32_e32 v184, v93
	v_exp_f32_e32 v185, v94
	v_exp_f32_e32 v186, v95
	s_waitcnt lgkmcnt(3)
	v_mfma_f32_32x32x16_bf16 v[152:167], v[128:131], v[172:175], v[152:167]
	v_exp_f32_e32 v124, v64
	v_exp_f32_e32 v125, v65
	v_exp_f32_e32 v126, v66
	v_exp_f32_e32 v127, v67
	s_waitcnt lgkmcnt(1)
	v_mfma_f32_32x32x16_bf16 v[96:111], v[136:139], v[172:175], v[96:111]
	v_exp_f32_e32 v128, v68
	v_exp_f32_e32 v129, v69
	v_exp_f32_e32 v130, v70
	v_exp_f32_e32 v131, v71
	v_mfma_f32_32x32x16_bf16 v[152:167], v[132:135], v[168:171], v[152:167]
	v_exp_f32_e32 v136, v72
	v_exp_f32_e32 v137, v73
	v_exp_f32_e32 v138, v74
	v_exp_f32_e32 v139, v75
	s_waitcnt lgkmcnt(0)
	v_mfma_f32_32x32x16_bf16 v[96:111], v[140:143], v[168:171], v[96:111]
	v_exp_f32_e32 v132, v76
	v_exp_f32_e32 v133, v77
	v_exp_f32_e32 v134, v78
	v_exp_f32_e32 v135, v79
	s_cmp_gt_i32 s27, 2
	s_cselect_b32 s28, -3, 2
	s_add_i32 s28, s28, s27
	s_mulk_i32 s28, 0x2400
	s_waitcnt vmcnt(3)
	ds_write_b128 v208, v[6:9] offset:9216
	v_add_u32_e32 v6, s28, v208
	s_add_i32 s28, s27, 1
	s_cmp_lg_u32 s27, 4
	s_cselect_b32 s27, s28, 0
	s_add_i32 s28, s13, -1
	s_min_u32 s28, s28, s12
	s_lshl_b32 s92, s28, 13
	s_waitcnt vmcnt(2)
	ds_write_b128 v6, v[2:5] offset:36864
	v_lshl_add_u64 v[2:3], v[198:199], 0, s[92:93]
	s_lshl_b32 s92, s29, 7
	v_lshl_add_u64 v[4:5], v[196:197], 0, s[92:93]
	s_waitcnt lgkmcnt(0)
	s_barrier
	global_load_dwordx4 v[6:9], v[2:3], off
	s_nop 0
	global_load_dwordx4 v[2:5], v[4:5], off
	s_mul_i32 s29, s27, 0x2400
	s_add_i32 s34, s29, 0xffffdc00
	s_cmp_lg_u32 s27, 0
	s_cselect_b32 s34, s34, 0x9000
	v_add_u32_e32 v92, s34, v195
	ds_read_b128 v[240:243], v195
	ds_read_b128 v[244:247], v195 offset:4608
	ds_read_b128 v[64:67], v92 offset:36864
	ds_read_b128 v[68:71], v92 offset:36896
	ds_read_b128 v[72:75], v92 offset:41472
	ds_read_b128 v[76:79], v92 offset:41504
	ds_read_b128 v[80:83], v92 offset:36928
	ds_read_b128 v[84:87], v92 offset:36960
	ds_read_b128 v[88:91], v92 offset:41536
	ds_read_b128 v[92:95], v92 offset:41568
	s_setprio 3
	v_mov_b32_e32 v187, 0
	v_cvt_pk_bf16_f32 v116, v15, v144
	v_cvt_pk_bf16_f32 v117, v145, v146
	v_cvt_pk_bf16_f32 v118, v147, v148
	v_cvt_pk_bf16_f32 v119, v149, v150
	s_waitcnt lgkmcnt(7)
	s_nop 0
	v_mfma_f32_32x32x16_bf16 v[16:31], v[64:67], v[116:119], v[16:31]
	v_add_f32_e32 v187, v187, v15
	v_add_f32_e32 v187, v187, v144
	v_add_f32_e32 v187, v187, v145
	v_add_f32_e32 v187, v187, v146
	s_waitcnt lgkmcnt(5)
	v_mfma_f32_32x32x16_bf16 v[32:47], v[72:75], v[116:119], v[32:47]
	v_cvt_pk_bf16_f32 v64, v120, v121
	v_cvt_pk_bf16_f32 v65, v122, v123
	v_cvt_pk_bf16_f32 v66, v151, v184
	v_cvt_pk_bf16_f32 v67, v185, v186
	v_add_f32_e32 v187, v187, v147
	v_add_f32_e32 v187, v187, v148
	v_add_f32_e32 v187, v187, v149
	v_add_f32_e32 v187, v187, v150
	s_nop 0
	v_mfma_f32_32x32x16_bf16 v[16:31], v[68:71], v[64:67], v[16:31]
	v_add_f32_e32 v187, v187, v120
	v_add_f32_e32 v187, v187, v121
	v_add_f32_e32 v187, v187, v122
	v_add_f32_e32 v187, v187, v123
	s_waitcnt lgkmcnt(4)
	v_mfma_f32_32x32x16_bf16 v[32:47], v[76:79], v[64:67], v[32:47]
	v_cvt_pk_bf16_f32 v68, v124, v125
	v_cvt_pk_bf16_f32 v69, v126, v127
	v_cvt_pk_bf16_f32 v70, v128, v129
	v_cvt_pk_bf16_f32 v71, v130, v131
	v_add_f32_e32 v187, v187, v151
	v_add_f32_e32 v187, v187, v184
	v_add_f32_e32 v187, v187, v185
	v_add_f32_e32 v187, v187, v186
	s_waitcnt lgkmcnt(3)
	v_mfma_f32_32x32x16_bf16 v[16:31], v[80:83], v[68:71], v[16:31]
	v_add_f32_e32 v187, v187, v124
	v_add_f32_e32 v187, v187, v125
	v_add_f32_e32 v187, v187, v126
	v_add_f32_e32 v187, v187, v127
	s_waitcnt lgkmcnt(1)
	v_mfma_f32_32x32x16_bf16 v[32:47], v[88:91], v[68:71], v[32:47]
	v_cvt_pk_bf16_f32 v64, v136, v137
	v_cvt_pk_bf16_f32 v65, v138, v139
	v_cvt_pk_bf16_f32 v66, v132, v133
	v_cvt_pk_bf16_f32 v67, v134, v135
	v_add_f32_e32 v187, v187, v128
	v_add_f32_e32 v187, v187, v129
	v_add_f32_e32 v187, v187, v130
	v_add_f32_e32 v187, v187, v131
	s_nop 0
	v_mfma_f32_32x32x16_bf16 v[16:31], v[84:87], v[64:67], v[16:31]
	v_add_f32_e32 v187, v187, v136
	v_add_f32_e32 v187, v187, v137
	v_add_f32_e32 v187, v187, v138
	v_add_f32_e32 v187, v187, v139
	s_waitcnt lgkmcnt(0)
	v_mfma_f32_32x32x16_bf16 v[32:47], v[92:95], v[64:67], v[32:47]
	v_add_f32_e32 v187, v187, v132
	v_add_f32_e32 v187, v187, v133
	v_add_f32_e32 v187, v187, v134
	v_add_f32_e32 v187, v187, v135
	s_setprio 2
	ds_read_b128 v[72:75], v195 offset:32
	ds_read_b128 v[76:79], v195 offset:4640
	ds_read_b128 v[80:83], v195 offset:64
	ds_read_b128 v[84:87], v195 offset:4672
	ds_read_b128 v[88:91], v195 offset:96
	ds_read_b128 v[92:95], v195 offset:4704
	v_add_f32_e32 v1, v1, v14
	s_waitcnt lgkmcnt(6)
	v_mfma_f32_32x32x16_bf16 v[136:151], v[240:243], v[180:183], v[48:63]
	v_exp_f32_e32 v14, v152
	v_exp_f32_e32 v15, v153
	v_exp_f32_e32 v116, v154
	v_exp_f32_e32 v117, v155
	v_mfma_f32_32x32x16_bf16 v[120:135], v[244:247], v[180:183], v[48:63]
	v_exp_f32_e32 v118, v156
	v_exp_f32_e32 v119, v157
	v_exp_f32_e32 v184, v158
	v_exp_f32_e32 v185, v159
	s_waitcnt lgkmcnt(5)
	v_mfma_f32_32x32x16_bf16 v[136:151], v[72:75], v[176:179], v[136:151]
	v_exp_f32_e32 v186, v160
	v_exp_f32_e32 v210, v161
	v_exp_f32_e32 v211, v162
	v_exp_f32_e32 v212, v163
	s_waitcnt lgkmcnt(4)
	v_mfma_f32_32x32x16_bf16 v[120:135], v[76:79], v[176:179], v[120:135]
	v_exp_f32_e32 v160, v164
	v_exp_f32_e32 v161, v165
	v_exp_f32_e32 v162, v166
	v_exp_f32_e32 v163, v167
	s_waitcnt lgkmcnt(3)
	v_mfma_f32_32x32x16_bf16 v[136:151], v[80:83], v[172:175], v[136:151]
	v_exp_f32_e32 v164, v96
	v_exp_f32_e32 v165, v97
	v_exp_f32_e32 v166, v98
	v_exp_f32_e32 v167, v99
	s_waitcnt lgkmcnt(2)
	v_mfma_f32_32x32x16_bf16 v[120:135], v[84:87], v[172:175], v[120:135]
	v_exp_f32_e32 v96, v100
	v_exp_f32_e32 v97, v101
	v_exp_f32_e32 v98, v102
	v_exp_f32_e32 v99, v103
	s_waitcnt lgkmcnt(1)
	v_mfma_f32_32x32x16_bf16 v[136:151], v[88:91], v[168:171], v[136:151]
	v_exp_f32_e32 v100, v104
	v_exp_f32_e32 v101, v105
	v_exp_f32_e32 v102, v106
	v_exp_f32_e32 v103, v107
	s_waitcnt lgkmcnt(0)
	v_mfma_f32_32x32x16_bf16 v[120:135], v[92:95], v[168:171], v[120:135]
	v_exp_f32_e32 v104, v108
	v_exp_f32_e32 v105, v109
	v_exp_f32_e32 v106, v110
	v_exp_f32_e32 v107, v111
	s_cmp_gt_i32 s27, 2
	s_cselect_b32 s34, -3, 2
	s_add_i32 s34, s34, s27
	s_mulk_i32 s34, 0x2400
	v_add_u32_e32 v88, s29, v195
	s_min_u32 s29, s13, s12
	s_waitcnt vmcnt(3)
	ds_write_b128 v208, v[10:13] offset:18432
	v_add_u32_e32 v10, s34, v208
	s_lshl_b32 s92, s29, 13
	s_waitcnt vmcnt(2)
	ds_write_b128 v10, v[112:115] offset:36864
	v_lshl_add_u64 v[10:11], v[198:199], 0, s[92:93]
	s_lshl_b32 s92, s28, 7
	global_load_dwordx4 v[152:155], v[10:11], off
	v_lshl_add_u64 v[10:11], v[196:197], 0, s[92:93]
	global_load_dwordx4 v[156:159], v[10:11], off
	ds_read_b128 v[240:243], v195 offset:9216
	ds_read_b128 v[244:247], v195 offset:13824
	ds_read_b128 v[10:13], v88 offset:41472
	ds_read_b128 v[64:67], v88 offset:36864
	ds_read_b128 v[68:71], v88 offset:36896
	ds_read_b128 v[72:75], v88 offset:41504
	ds_read_b128 v[76:79], v88 offset:36928
	ds_read_b128 v[80:83], v88 offset:41536
	ds_read_b128 v[84:87], v88 offset:36960
	ds_read_b128 v[88:91], v88 offset:41568
	v_add_f32_e32 v1, v1, v187
	s_setprio 1
	v_mov_b32_e32 v108, 0
	v_mov_b32_e32 v109, v136
	v_cvt_pk_bf16_f32 v92, v14, v15
	v_cvt_pk_bf16_f32 v93, v116, v117
	v_cvt_pk_bf16_f32 v94, v118, v119
	v_cvt_pk_bf16_f32 v95, v184, v185
	s_waitcnt lgkmcnt(6)
	s_nop 0
	v_mfma_f32_32x32x16_bf16 v[16:31], v[64:67], v[92:95], v[16:31]
	v_max3_f32 v109, v109, v137, v138
	v_max3_f32 v109, v109, v139, v140
	v_add_f32_e32 v108, v108, v14
	v_add_f32_e32 v108, v108, v15
	v_add_f32_e32 v108, v108, v116
	v_add_f32_e32 v108, v108, v117
	s_nop 0
	v_mfma_f32_32x32x16_bf16 v[32:47], v[10:13], v[92:95], v[32:47]
	v_cvt_pk_bf16_f32 v64, v186, v210
	v_cvt_pk_bf16_f32 v65, v211, v212
	v_cvt_pk_bf16_f32 v66, v160, v161
	v_cvt_pk_bf16_f32 v67, v162, v163
	v_max3_f32 v109, v109, v141, v142
	v_max3_f32 v109, v109, v143, v144
	v_add_f32_e32 v108, v108, v118
	v_add_f32_e32 v108, v108, v119
	v_add_f32_e32 v108, v108, v184
	v_add_f32_e32 v108, v108, v185
	s_waitcnt lgkmcnt(5)
	v_mfma_f32_32x32x16_bf16 v[16:31], v[68:71], v[64:67], v[16:31]
	v_max3_f32 v109, v109, v145, v146
	v_max3_f32 v109, v109, v147, v148
	v_add_f32_e32 v108, v108, v186
	v_add_f32_e32 v108, v108, v210
	v_add_f32_e32 v108, v108, v211
	v_add_f32_e32 v108, v108, v212
	s_waitcnt lgkmcnt(4)
	v_mfma_f32_32x32x16_bf16 v[32:47], v[72:75], v[64:67], v[32:47]
	v_cvt_pk_bf16_f32 v10, v164, v165
	v_cvt_pk_bf16_f32 v11, v166, v167
	v_cvt_pk_bf16_f32 v12, v96, v97
	v_cvt_pk_bf16_f32 v13, v98, v99
	v_max3_f32 v109, v109, v149, v150
	v_max3_f32 v109, v109, v151, v120
	v_add_f32_e32 v108, v108, v160
	v_add_f32_e32 v108, v108, v161
	v_add_f32_e32 v108, v108, v162
	v_add_f32_e32 v108, v108, v163
	s_waitcnt lgkmcnt(3)
	v_mfma_f32_32x32x16_bf16 v[16:31], v[76:79], v[10:13], v[16:31]
	v_max3_f32 v109, v109, v121, v122
	v_max3_f32 v109, v109, v123, v124
	v_add_f32_e32 v108, v108, v164
	v_add_f32_e32 v108, v108, v165
	v_add_f32_e32 v108, v108, v166
	v_add_f32_e32 v108, v108, v167
	s_waitcnt lgkmcnt(2)
	v_mfma_f32_32x32x16_bf16 v[32:47], v[80:83], v[10:13], v[32:47]
	v_cvt_pk_bf16_f32 v64, v100, v101
	v_cvt_pk_bf16_f32 v65, v102, v103
	v_cvt_pk_bf16_f32 v66, v104, v105
	v_cvt_pk_bf16_f32 v67, v106, v107
	v_max3_f32 v109, v109, v125, v126
	v_max3_f32 v109, v109, v127, v128
	v_add_f32_e32 v108, v108, v96
	v_add_f32_e32 v108, v108, v97
	v_add_f32_e32 v108, v108, v98
	v_add_f32_e32 v108, v108, v99
	s_waitcnt lgkmcnt(1)
	v_mfma_f32_32x32x16_bf16 v[16:31], v[84:87], v[64:67], v[16:31]
	v_max3_f32 v109, v109, v129, v130
	v_max3_f32 v109, v109, v131, v132
	v_add_f32_e32 v108, v108, v100
	v_add_f32_e32 v108, v108, v101
	v_add_f32_e32 v108, v108, v102
	v_add_f32_e32 v108, v108, v103
	s_waitcnt lgkmcnt(0)
	v_mfma_f32_32x32x16_bf16 v[32:47], v[88:91], v[64:67], v[32:47]
	v_max3_f32 v109, v109, v133, v134
	v_max3_f32 v109, v109, v135, v135
	v_add_f32_e32 v108, v108, v104
	v_add_f32_e32 v108, v108, v105
	v_add_f32_e32 v108, v108, v106
	v_add_f32_e32 v108, v108, v107
	s_setprio 0
	ds_read_b128 v[164:167], v195 offset:9248
	ds_read_b128 v[160:163], v195 offset:13856
	ds_read_b128 v[74:77], v195 offset:9280
	ds_read_b128 v[66:69], v195 offset:9312
	ds_read_b128 v[70:73], v195 offset:13888
	ds_read_b128 v[10:13], v195 offset:13920
	v_add_f32_e32 v64, v1, v108
	v_mov_b32_e32 v1, v109
	s_nop 1
	v_permlane32_swap_b32_e32 v109, v1
	v_max_f32_e32 v1, v1, v1
	v_max_f32_e32 v14, v109, v109
	v_max_f32_e32 v1, v14, v1
	v_cmp_lt_f32_e32 vcc, s52, v1
	s_cbranch_vccz .LBB0_663
	v_max_f32_e32 v1, v1, v1
	v_max_f32_e32 v14, 0, v1
	v_add_f32_e32 v209, v209, v14
	v_xor_b32_e32 v48, 0x80000000, v209
	v_pk_add_f32 v[136:137], v[136:137], v[14:15] op_sel_hi:[1,0] neg_lo:[0,1] neg_hi:[0,1]
	v_pk_add_f32 v[120:121], v[120:121], v[14:15] op_sel_hi:[1,0] neg_lo:[0,1] neg_hi:[0,1]
	v_pk_add_f32 v[138:139], v[138:139], v[14:15] op_sel_hi:[1,0] neg_lo:[0,1] neg_hi:[0,1]
	v_pk_add_f32 v[122:123], v[122:123], v[14:15] op_sel_hi:[1,0] neg_lo:[0,1] neg_hi:[0,1]
	v_pk_add_f32 v[140:141], v[140:141], v[14:15] op_sel_hi:[1,0] neg_lo:[0,1] neg_hi:[0,1]
	v_pk_add_f32 v[124:125], v[124:125], v[14:15] op_sel_hi:[1,0] neg_lo:[0,1] neg_hi:[0,1]
	v_pk_add_f32 v[142:143], v[142:143], v[14:15] op_sel_hi:[1,0] neg_lo:[0,1] neg_hi:[0,1]
	v_pk_add_f32 v[126:127], v[126:127], v[14:15] op_sel_hi:[1,0] neg_lo:[0,1] neg_hi:[0,1]
	v_pk_add_f32 v[144:145], v[144:145], v[14:15] op_sel_hi:[1,0] neg_lo:[0,1] neg_hi:[0,1]
	v_pk_add_f32 v[128:129], v[128:129], v[14:15] op_sel_hi:[1,0] neg_lo:[0,1] neg_hi:[0,1]
	v_pk_add_f32 v[146:147], v[146:147], v[14:15] op_sel_hi:[1,0] neg_lo:[0,1] neg_hi:[0,1]
	v_pk_add_f32 v[130:131], v[130:131], v[14:15] op_sel_hi:[1,0] neg_lo:[0,1] neg_hi:[0,1]
	v_pk_add_f32 v[148:149], v[148:149], v[14:15] op_sel_hi:[1,0] neg_lo:[0,1] neg_hi:[0,1]
	v_pk_add_f32 v[132:133], v[132:133], v[14:15] op_sel_hi:[1,0] neg_lo:[0,1] neg_hi:[0,1]
	v_pk_add_f32 v[150:151], v[150:151], v[14:15] op_sel_hi:[1,0] neg_lo:[0,1] neg_hi:[0,1]
	v_pk_add_f32 v[134:135], v[134:135], v[14:15] op_sel_hi:[1,0] neg_lo:[0,1] neg_hi:[0,1]
	v_exp_f32_e64 v14, -v14
	v_mov_b32_e32 v49, v48
	v_mov_b32_e32 v50, v48
	v_mov_b32_e32 v51, v48
	v_mov_b32_e32 v52, v48
	v_mov_b32_e32 v53, v48
	v_mov_b32_e32 v54, v48
	v_mov_b32_e32 v55, v48
	v_mov_b32_e32 v56, v48
	v_mov_b32_e32 v57, v48
	v_mov_b32_e32 v58, v48
	v_mov_b32_e32 v59, v48
	v_mov_b32_e32 v60, v48
	v_mov_b32_e32 v61, v48
	v_mov_b32_e32 v62, v48
	v_mov_b32_e32 v63, v48
	s_nop 11
	v_pk_mul_f32 v[30:31], v[30:31], v[14:15] op_sel_hi:[1,0]
	v_pk_mul_f32 v[28:29], v[28:29], v[14:15] op_sel_hi:[1,0]
	v_pk_mul_f32 v[26:27], v[26:27], v[14:15] op_sel_hi:[1,0]
	v_pk_mul_f32 v[24:25], v[24:25], v[14:15] op_sel_hi:[1,0]
	v_pk_mul_f32 v[22:23], v[22:23], v[14:15] op_sel_hi:[1,0]
	v_pk_mul_f32 v[20:21], v[20:21], v[14:15] op_sel_hi:[1,0]
	v_pk_mul_f32 v[18:19], v[18:19], v[14:15] op_sel_hi:[1,0]
	v_pk_mul_f32 v[16:17], v[16:17], v[14:15] op_sel_hi:[1,0]
	v_pk_mul_f32 v[46:47], v[46:47], v[14:15] op_sel_hi:[1,0]
	v_pk_mul_f32 v[44:45], v[44:45], v[14:15] op_sel_hi:[1,0]
	v_pk_mul_f32 v[42:43], v[42:43], v[14:15] op_sel_hi:[1,0]
	v_pk_mul_f32 v[40:41], v[40:41], v[14:15] op_sel_hi:[1,0]
	v_pk_mul_f32 v[38:39], v[38:39], v[14:15] op_sel_hi:[1,0]
	v_pk_mul_f32 v[36:37], v[36:37], v[14:15] op_sel_hi:[1,0]
	v_pk_mul_f32 v[34:35], v[34:35], v[14:15] op_sel_hi:[1,0]
	v_pk_mul_f32 v[32:33], v[32:33], v[14:15] op_sel_hi:[1,0]
	v_mul_f32_e32 v64, v64, v14

.LBB0_697:
	s_add_i32 s22, s45, s18
	s_ashr_i32 s23, s22, 31
	s_lshl_b64 s[24:25], s[22:23], 13
	s_lshl_b32 s22, s22, 6
	v_lshl_add_u64 v[2:3], v[198:199], 0, s[24:25]
	s_sub_i32 s24, s22, 64
	s_ashr_i32 s25, s24, 31
	v_lshl_add_u64 v[4:5], s[24:25], 1, v[196:197]
	s_waitcnt lgkmcnt(0)
	s_barrier
	global_load_dwordx4 v[6:9], v[2:3], off
	s_nop 0
	global_load_dwordx4 v[2:5], v[4:5], off
	s_mul_i32 s2, s34, 0x2400
	s_add_i32 s23, s2, 0xffffdc00
	s_cmp_lg_u32 s34, 0
	s_cselect_b32 s23, s23, 0x9000
	v_add_u32_e32 v1, s23, v201
	ds_read_b128 v[240:243], v201 offset:18432
	ds_read_b128 v[244:247], v201 offset:23040
	ds_read_b128 v[10:13], v1 offset:36864
	ds_read_b128 v[66:69], v1 offset:36896
	ds_read_b128 v[70:73], v1 offset:41472
	ds_read_b128 v[74:77], v1 offset:41504
	ds_read_b128 v[128:131], v1 offset:36928
	ds_read_b128 v[132:135], v1 offset:36960
	ds_read_b128 v[136:139], v1 offset:41536
	ds_read_b128 v[142:145], v1 offset:41568
	s_setprio 3
	v_mov_b32_e32 v1, 0
	v_cvt_pk_bf16_f32 v178, v116, v117
	v_cvt_pk_bf16_f32 v179, v118, v119
	v_cvt_pk_bf16_f32 v180, v112, v113
	v_cvt_pk_bf16_f32 v181, v114, v115
	s_waitcnt lgkmcnt(7)
	s_nop 0
	v_mfma_f32_32x32x16_bf16 v[16:31], v[10:13], v[178:181], v[16:31]
	v_add_f32_e32 v1, v1, v116
	v_add_f32_e32 v1, v1, v117
	v_add_f32_e32 v1, v1, v118
	v_add_f32_e32 v1, v1, v119
	s_waitcnt lgkmcnt(5)
	v_mfma_f32_32x32x16_bf16 v[32:47], v[70:73], v[178:181], v[32:47]
	v_cvt_pk_bf16_f32 v10, v208, v207
	v_cvt_pk_bf16_f32 v11, v206, v205
	v_cvt_pk_bf16_f32 v12, v204, v187
	v_cvt_pk_bf16_f32 v13, v186, v185
	v_add_f32_e32 v1, v1, v112
	v_add_f32_e32 v1, v1, v113
	v_add_f32_e32 v1, v1, v114
	v_add_f32_e32 v1, v1, v115
	s_nop 0
	v_mfma_f32_32x32x16_bf16 v[16:31], v[66:69], v[10:13], v[16:31]
	v_add_f32_e32 v1, v1, v208
	v_add_f32_e32 v1, v1, v207
	v_add_f32_e32 v1, v1, v206
	v_add_f32_e32 v1, v1, v205
	s_waitcnt lgkmcnt(4)
	v_mfma_f32_32x32x16_bf16 v[32:47], v[74:77], v[10:13], v[32:47]
	v_cvt_pk_bf16_f32 v66, v177, v176
	v_cvt_pk_bf16_f32 v67, v149, v148
	v_cvt_pk_bf16_f32 v68, v147, v146
	v_cvt_pk_bf16_f32 v69, v141, v140
	v_add_f32_e32 v1, v1, v204
	v_add_f32_e32 v1, v1, v187
	v_add_f32_e32 v1, v1, v186
	v_add_f32_e32 v1, v1, v185
	s_waitcnt lgkmcnt(3)
	v_mfma_f32_32x32x16_bf16 v[16:31], v[128:131], v[66:69], v[16:31]
	v_add_f32_e32 v1, v1, v177
	v_add_f32_e32 v1, v1, v176
	v_add_f32_e32 v1, v1, v149
	v_add_f32_e32 v1, v1, v148
	s_waitcnt lgkmcnt(1)
	v_mfma_f32_32x32x16_bf16 v[32:47], v[136:139], v[66:69], v[32:47]
	v_cvt_pk_bf16_f32 v10, v123, v122
	v_cvt_pk_bf16_f32 v11, v121, v120
	v_cvt_pk_bf16_f32 v12, v127, v126
	v_cvt_pk_bf16_f32 v13, v125, v124
	v_add_f32_e32 v1, v1, v147
	v_add_f32_e32 v1, v1, v146
	v_add_f32_e32 v1, v1, v141
	v_add_f32_e32 v1, v1, v140
	s_nop 0
	v_mfma_f32_32x32x16_bf16 v[16:31], v[132:135], v[10:13], v[16:31]
	v_add_f32_e32 v1, v1, v123
	v_add_f32_e32 v1, v1, v122
	v_add_f32_e32 v1, v1, v121
	v_add_f32_e32 v1, v1, v120
	s_waitcnt lgkmcnt(0)
	v_mfma_f32_32x32x16_bf16 v[32:47], v[142:145], v[10:13], v[32:47]
	v_add_f32_e32 v1, v1, v127
	v_add_f32_e32 v1, v1, v126
	v_add_f32_e32 v1, v1, v125
	v_add_f32_e32 v1, v1, v124
	s_setprio 2
	ds_read_b128 v[66:69], v201 offset:18464
	ds_read_b128 v[76:79], v201 offset:23072
	ds_read_b128 v[144:147], v201 offset:18496
	ds_read_b128 v[176:179], v201 offset:18528
	ds_read_b128 v[204:207], v201 offset:23104
	ds_read_b128 v[208:211], v201 offset:23136
	s_waitcnt lgkmcnt(6)
	v_mfma_f32_32x32x16_bf16 v[128:143], v[240:243], v[164:167], v[48:63]
	v_exp_f32_e32 v148, v96
	v_exp_f32_e32 v149, v97
	v_exp_f32_e32 v150, v98
	v_exp_f32_e32 v151, v99
	s_waitcnt lgkmcnt(5)
	v_mfma_f32_32x32x16_bf16 v[112:127], v[244:247], v[164:167], v[48:63]
	v_exp_f32_e32 v96, v100
	v_exp_f32_e32 v97, v101
	v_exp_f32_e32 v98, v102
	v_exp_f32_e32 v99, v103
	v_mfma_f32_32x32x16_bf16 v[128:143], v[66:69], v[160:163], v[128:143]
	v_exp_f32_e32 v100, v104
	v_exp_f32_e32 v101, v105
	v_exp_f32_e32 v102, v106
	v_exp_f32_e32 v103, v107
	s_waitcnt lgkmcnt(4)
	v_mfma_f32_32x32x16_bf16 v[112:127], v[76:79], v[160:163], v[112:127]
	v_exp_f32_e32 v71, v108
	v_exp_f32_e32 v72, v109
	v_exp_f32_e32 v73, v110
	v_exp_f32_e32 v74, v111
	s_waitcnt lgkmcnt(3)
	v_mfma_f32_32x32x16_bf16 v[128:143], v[144:147], v[156:159], v[128:143]
	v_exp_f32_e32 v75, v80
	v_exp_f32_e32 v76, v81
	v_exp_f32_e32 v77, v82
	v_exp_f32_e32 v78, v83
	s_waitcnt lgkmcnt(1)
	v_mfma_f32_32x32x16_bf16 v[112:127], v[204:207], v[156:159], v[112:127]
	v_exp_f32_e32 v14, v84
	v_exp_f32_e32 v15, v85
	v_exp_f32_e32 v65, v86
	v_exp_f32_e32 v66, v87
	v_mfma_f32_32x32x16_bf16 v[128:143], v[176:179], v[152:155], v[128:143]
	v_exp_f32_e32 v67, v88
	v_exp_f32_e32 v68, v89
	v_exp_f32_e32 v69, v90
	v_exp_f32_e32 v70, v91
	s_waitcnt lgkmcnt(0)
	v_mfma_f32_32x32x16_bf16 v[112:127], v[208:211], v[152:155], v[112:127]
	v_exp_f32_e32 v79, v92
	v_exp_f32_e32 v80, v93
	v_exp_f32_e32 v81, v94
	v_exp_f32_e32 v82, v95
	s_cmp_lt_u32 s45, 3
	s_cbranch_scc1 .LBB0_699
	s_add_i32 s23, s19, s45
	v_lshl_add_u32 v10, s23, 6, v184
	v_add_u32_e32 v11, 0xffffff7f, v10
	v_cmp_lt_u32_e32 vcc, s53, v11
	v_add_u32_e32 v11, 0xffffff9f, v10
	s_nop 7
	s_nop 3
	s_nop 0
	v_cndmask_b32_e32 v128, v233, v128, vcc
	v_cmp_lt_u32_e32 vcc, s53, v11
	v_add_u32_e32 v11, 0xffffff80, v10
	s_nop 0
	v_cndmask_b32_e32 v112, v233, v112, vcc
	v_cmp_lt_u32_e32 vcc, s53, v11
	v_add_u32_e32 v11, 0xffffffa0, v10
	s_nop 0
	v_cndmask_b32_e32 v129, v233, v129, vcc
	v_cmp_lt_u32_e32 vcc, s53, v11
	v_add_u32_e32 v11, 0xffffff81, v10
	s_nop 0
	v_cndmask_b32_e32 v113, v233, v113, vcc
	v_cmp_lt_u32_e32 vcc, s53, v11
	v_add_u32_e32 v11, 0xffffffa1, v10
	s_nop 0
	v_cndmask_b32_e32 v130, v233, v130, vcc
	v_cmp_lt_u32_e32 vcc, s53, v11
	v_add_u32_e32 v11, 0xffffff82, v10
	s_nop 0
	v_cndmask_b32_e32 v114, v233, v114, vcc
	v_cmp_lt_u32_e32 vcc, s53, v11
	v_add_u32_e32 v11, 0xffffffa2, v10
	s_nop 0
	v_cndmask_b32_e32 v131, v233, v131, vcc
	v_cmp_lt_u32_e32 vcc, s53, v11
	v_add_u32_e32 v11, 0xffffff87, v10
	s_nop 0
	v_cndmask_b32_e32 v115, v233, v115, vcc
	v_cmp_lt_u32_e32 vcc, s53, v11
	v_add_u32_e32 v11, 0xffffffa7, v10
	s_nop 0
	v_cndmask_b32_e32 v132, v233, v132, vcc
	v_cmp_lt_u32_e32 vcc, s53, v11
	v_add_u32_e32 v11, 0xffffff88, v10
	s_nop 0
	v_cndmask_b32_e32 v116, v233, v116, vcc
	v_cmp_lt_u32_e32 vcc, s53, v11
	v_add_u32_e32 v11, 0xffffffa8, v10
	s_nop 0
	v_cndmask_b32_e32 v133, v233, v133, vcc
	v_cmp_lt_u32_e32 vcc, s53, v11
	v_add_u32_e32 v11, 0xffffff89, v10
	s_nop 0
	v_cndmask_b32_e32 v117, v233, v117, vcc
	v_cmp_lt_u32_e32 vcc, s53, v11
	v_add_u32_e32 v11, 0xffffffa9, v10
	s_nop 0
	v_cndmask_b32_e32 v134, v233, v134, vcc
	v_cmp_lt_u32_e32 vcc, s53, v11
	v_add_u32_e32 v11, 0xffffff8a, v10
	s_nop 0
	v_cndmask_b32_e32 v118, v233, v118, vcc
	v_cmp_lt_u32_e32 vcc, s53, v11
	v_add_u32_e32 v11, 0xffffffaa, v10
	s_nop 0
	v_cndmask_b32_e32 v135, v233, v135, vcc
	v_cmp_lt_u32_e32 vcc, s53, v11
	v_add_u32_e32 v11, 0xffffff8f, v10
	s_nop 0
	v_cndmask_b32_e32 v119, v233, v119, vcc
	v_cmp_lt_u32_e32 vcc, s53, v11
	v_add_u32_e32 v11, 0xffffffaf, v10
	s_nop 0
	v_cndmask_b32_e32 v136, v233, v136, vcc
	v_cmp_lt_u32_e32 vcc, s53, v11
	v_add_u32_e32 v11, 0xffffff90, v10
	s_nop 0
	v_cndmask_b32_e32 v120, v233, v120, vcc
	v_cmp_lt_u32_e32 vcc, s53, v11
	v_add_u32_e32 v11, 0xffffffb0, v10
	s_nop 0
	v_cndmask_b32_e32 v137, v233, v137, vcc
	v_cmp_lt_u32_e32 vcc, s53, v11
	v_add_u32_e32 v11, 0xffffff91, v10
	s_nop 0
	v_cndmask_b32_e32 v121, v233, v121, vcc
	v_cmp_lt_u32_e32 vcc, s53, v11
	v_add_u32_e32 v11, 0xffffffb1, v10
	s_nop 0
	v_cndmask_b32_e32 v138, v233, v138, vcc
	v_cmp_lt_u32_e32 vcc, s53, v11
	v_add_u32_e32 v11, 0xffffff92, v10
	s_nop 0
	v_cndmask_b32_e32 v122, v233, v122, vcc
	v_cmp_lt_u32_e32 vcc, s53, v11
	v_add_u32_e32 v11, 0xffffffb2, v10
	s_nop 0
	v_cndmask_b32_e32 v139, v233, v139, vcc
	v_cmp_lt_u32_e32 vcc, s53, v11
	v_add_u32_e32 v11, 0xffffff97, v10
	s_nop 0
	v_cndmask_b32_e32 v123, v233, v123, vcc
	v_cmp_lt_u32_e32 vcc, s53, v11
	v_add_u32_e32 v11, 0xffffffb7, v10
	s_nop 0
	v_cndmask_b32_e32 v140, v233, v140, vcc
	v_cmp_lt_u32_e32 vcc, s53, v11
	v_add_u32_e32 v11, 0xffffff98, v10
	s_nop 0
	v_cndmask_b32_e32 v124, v233, v124, vcc
	v_cmp_lt_u32_e32 vcc, s53, v11
	v_add_u32_e32 v11, 0xffffffb8, v10
	s_nop 0
	v_cndmask_b32_e32 v141, v233, v141, vcc
	v_cmp_lt_u32_e32 vcc, s53, v11
	v_add_u32_e32 v11, 0xffffff99, v10
	s_nop 0
	v_cndmask_b32_e32 v125, v233, v125, vcc
	v_cmp_lt_u32_e32 vcc, s53, v11
	v_add_u32_e32 v11, 0xffffffb9, v10
	s_nop 0
	v_cndmask_b32_e32 v142, v233, v142, vcc
	v_cmp_lt_u32_e32 vcc, s53, v11
	v_add_u32_e32 v11, 0xffffff9a, v10
	v_add_u32_e32 v10, 0xffffffba, v10
	v_cndmask_b32_e32 v126, v233, v126, vcc
	v_cmp_lt_u32_e32 vcc, s53, v11
	s_nop 1
	v_cndmask_b32_e32 v143, v233, v143, vcc
	v_cmp_lt_u32_e32 vcc, s53, v10
	s_nop 1
	v_cndmask_b32_e32 v127, v233, v127, vcc

.LBB0_701:
	s_add_i32 s2, s34, 1
	s_cmp_lg_u32 s34, 4
	s_cselect_b32 s2, s2, 0
	s_cmp_gt_i32 s2, 2
	s_cselect_b32 s23, -3, 2
	s_add_i32 s23, s23, s2
	s_mulk_i32 s23, 0x2400
	s_waitcnt vmcnt(3)
	ds_write_b128 v203, v[6:9] offset:9216
	v_add_u32_e32 v6, s23, v203
	s_add_i32 s23, s2, 1
	s_cmp_lg_u32 s2, 4
	s_cselect_b32 s23, s23, 0
	s_add_i32 s2, s45, 6
	s_add_i32 s34, s2, s13
	s_ashr_i32 s35, s34, 31
	s_lshl_b32 s26, s26, 6
	s_lshl_b64 vcc, s[34:35], 13
	s_ashr_i32 s27, s26, 31
	s_waitcnt vmcnt(2)
	ds_write_b128 v6, v[2:5] offset:36864
	v_lshl_add_u64 v[2:3], v[198:199], 0, vcc
	v_lshl_add_u64 v[6:7], s[26:27], 1, v[196:197]
	s_waitcnt lgkmcnt(0)
	s_barrier
	global_load_dwordx4 v[2:5], v[2:3], off
	s_mul_i32 s25, s23, 0x2400
	global_load_dwordx4 v[6:9], v[6:7], off
	s_add_i32 s26, s25, 0xffffdc00
	s_cmp_lg_u32 s23, 0
	s_cselect_b32 s26, s26, 0x9000
	v_add_f32_e32 v1, v64, v1
	v_add_u32_e32 v64, s26, v201
	v_add_f32_e32 v1, v1, v168
	ds_read_b128 v[240:243], v201
	ds_read_b128 v[244:247], v201 offset:4608
	ds_read_b128 v[116:119], v64 offset:41472
	ds_read_b128 v[120:123], v64 offset:36864
	ds_read_b128 v[124:127], v64 offset:36896
	ds_read_b128 v[136:139], v64 offset:41504
	ds_read_b128 v[140:143], v64 offset:36928
	ds_read_b128 v[168:171], v64 offset:41536
	ds_read_b128 v[172:175], v64 offset:36960
	ds_read_b128 v[176:179], v64 offset:41568
	s_setprio 3
	v_mov_b32_e32 v180, 0
	v_cvt_pk_bf16_f32 v204, v148, v149
	v_cvt_pk_bf16_f32 v205, v150, v151
	v_cvt_pk_bf16_f32 v206, v128, v129
	v_cvt_pk_bf16_f32 v207, v130, v131
	s_waitcnt lgkmcnt(6)
	s_nop 0
	v_mfma_f32_32x32x16_bf16 v[16:31], v[120:123], v[204:207], v[16:31]
	v_add_f32_e32 v180, v180, v148
	v_add_f32_e32 v180, v180, v149
	v_add_f32_e32 v180, v180, v150
	v_add_f32_e32 v180, v180, v151
	s_nop 0
	v_mfma_f32_32x32x16_bf16 v[32:47], v[116:119], v[204:207], v[32:47]
	v_cvt_pk_bf16_f32 v120, v132, v133
	v_cvt_pk_bf16_f32 v121, v134, v135
	v_cvt_pk_bf16_f32 v122, v71, v72
	v_cvt_pk_bf16_f32 v123, v73, v74
	v_add_f32_e32 v180, v180, v128
	v_add_f32_e32 v180, v180, v129
	v_add_f32_e32 v180, v180, v130
	v_add_f32_e32 v180, v180, v131
	s_waitcnt lgkmcnt(5)
	v_mfma_f32_32x32x16_bf16 v[16:31], v[124:127], v[120:123], v[16:31]
	v_add_f32_e32 v180, v180, v132
	v_add_f32_e32 v180, v180, v133
	v_add_f32_e32 v180, v180, v134
	v_add_f32_e32 v180, v180, v135
	s_waitcnt lgkmcnt(4)
	v_mfma_f32_32x32x16_bf16 v[32:47], v[136:139], v[120:123], v[32:47]
	v_cvt_pk_bf16_f32 v116, v75, v76
	v_cvt_pk_bf16_f32 v117, v77, v78
	v_cvt_pk_bf16_f32 v118, v14, v15
	v_cvt_pk_bf16_f32 v119, v65, v66
	v_add_f32_e32 v180, v180, v71
	v_add_f32_e32 v180, v180, v72
	v_add_f32_e32 v180, v180, v73
	v_add_f32_e32 v180, v180, v74
	s_waitcnt lgkmcnt(3)
	v_mfma_f32_32x32x16_bf16 v[16:31], v[140:143], v[116:119], v[16:31]
	v_add_f32_e32 v180, v180, v75
	v_add_f32_e32 v180, v180, v76
	v_add_f32_e32 v180, v180, v77
	v_add_f32_e32 v180, v180, v78
	s_waitcnt lgkmcnt(2)
	v_mfma_f32_32x32x16_bf16 v[32:47], v[168:171], v[116:119], v[32:47]
	v_cvt_pk_bf16_f32 v72, v67, v68
	v_cvt_pk_bf16_f32 v73, v69, v70
	v_cvt_pk_bf16_f32 v74, v79, v112
	v_cvt_pk_bf16_f32 v75, v113, v114
	v_add_f32_e32 v180, v180, v14
	v_add_f32_e32 v180, v180, v15
	v_add_f32_e32 v180, v180, v65
	v_add_f32_e32 v180, v180, v66
	s_waitcnt lgkmcnt(1)
	v_mfma_f32_32x32x16_bf16 v[16:31], v[172:175], v[72:75], v[16:31]
	v_add_f32_e32 v180, v180, v67
	v_add_f32_e32 v180, v180, v68
	v_add_f32_e32 v180, v180, v69
	v_add_f32_e32 v180, v180, v70
	s_waitcnt lgkmcnt(0)
	v_mfma_f32_32x32x16_bf16 v[32:47], v[176:179], v[72:75], v[32:47]
	v_add_f32_e32 v180, v180, v79
	v_add_f32_e32 v180, v180, v112
	v_add_f32_e32 v180, v180, v113
	v_add_f32_e32 v180, v180, v114
	s_setprio 2
	ds_read_b128 v[128:131], v201 offset:32
	ds_read_b128 v[136:139], v201 offset:4640
	ds_read_b128 v[172:175], v201 offset:64
	ds_read_b128 v[176:179], v201 offset:96
	ds_read_b128 v[204:207], v201 offset:4672
	ds_read_b128 v[208:211], v201 offset:4704
	s_waitcnt lgkmcnt(6)
	v_mfma_f32_32x32x16_bf16 v[64:79], v[240:243], v[164:167], v[48:63]
	v_exp_f32_e32 v168, v96
	v_exp_f32_e32 v169, v97
	v_exp_f32_e32 v170, v98
	v_exp_f32_e32 v171, v99
	s_waitcnt lgkmcnt(5)
	v_mfma_f32_32x32x16_bf16 v[112:127], v[244:247], v[164:167], v[48:63]
	v_exp_f32_e32 v140, v100
	v_exp_f32_e32 v141, v101
	v_exp_f32_e32 v142, v102
	v_exp_f32_e32 v143, v103
	v_mfma_f32_32x32x16_bf16 v[64:79], v[128:131], v[160:163], v[64:79]
	v_exp_f32_e32 v148, v104
	v_exp_f32_e32 v149, v105
	v_exp_f32_e32 v150, v106
	v_exp_f32_e32 v151, v107
	s_waitcnt lgkmcnt(4)
	v_mfma_f32_32x32x16_bf16 v[112:127], v[136:139], v[160:163], v[112:127]
	v_exp_f32_e32 v132, v108
	v_exp_f32_e32 v133, v109
	v_exp_f32_e32 v134, v110
	v_exp_f32_e32 v135, v111
	s_waitcnt lgkmcnt(3)
	v_mfma_f32_32x32x16_bf16 v[64:79], v[172:175], v[156:159], v[64:79]
	v_exp_f32_e32 v136, v80
	v_exp_f32_e32 v137, v81
	v_exp_f32_e32 v138, v82
	v_exp_f32_e32 v139, v83
	s_waitcnt lgkmcnt(1)
	v_mfma_f32_32x32x16_bf16 v[112:127], v[204:207], v[156:159], v[112:127]
	v_exp_f32_e32 v128, v84
	v_exp_f32_e32 v129, v85
	v_exp_f32_e32 v130, v86
	v_exp_f32_e32 v131, v87
	v_mfma_f32_32x32x16_bf16 v[64:79], v[176:179], v[152:155], v[64:79]
	v_exp_f32_e32 v84, v88
	v_exp_f32_e32 v85, v89
	v_exp_f32_e32 v86, v90
	v_exp_f32_e32 v87, v91
	s_waitcnt lgkmcnt(0)
	v_mfma_f32_32x32x16_bf16 v[112:127], v[208:211], v[152:155], v[112:127]
	v_exp_f32_e32 v88, v92
	v_exp_f32_e32 v89, v93
	v_exp_f32_e32 v90, v94
	v_exp_f32_e32 v91, v95
	v_sub_u32_e32 v14, s24, v202
	v_add_u32_e32 v14, v14, v183
	v_add_u32_e32 v15, 0xffffff7f, v14
	v_cmp_lt_u32_e32 vcc, s53, v15
	v_add_u32_e32 v15, 0xffffff9f, v14
	s_cmp_gt_i32 s23, 2
	v_cndmask_b32_e32 v80, v233, v64, vcc
	v_cmp_lt_u32_e32 vcc, s53, v15
	v_add_u32_e32 v64, 0xffffff80, v14
	s_cselect_b32 s24, -3, 2
	v_cndmask_b32_e32 v15, v233, v112, vcc
	v_cmp_lt_u32_e32 vcc, s53, v64
	v_add_u32_e32 v64, 0xffffffa0, v14
	s_add_i32 s24, s24, s23
	v_cndmask_b32_e32 v81, v233, v65, vcc
	v_cmp_lt_u32_e32 vcc, s53, v64
	v_add_u32_e32 v64, 0xffffff81, v14
	s_mulk_i32 s24, 0x2400
	v_cndmask_b32_e32 v100, v233, v113, vcc
	v_cmp_lt_u32_e32 vcc, s53, v64
	v_add_u32_e32 v64, 0xffffffa1, v14
	s_add_i32 s27, s77, s18
	v_cndmask_b32_e32 v82, v233, v66, vcc
	v_cmp_lt_u32_e32 vcc, s53, v64
	v_add_u32_e32 v64, 0xffffff82, v14
	s_nop 7
	s_nop 3
	s_waitcnt vmcnt(3)
	ds_write_b128 v203, v[144:147] offset:18432
	v_cndmask_b32_e32 v101, v233, v114, vcc
	v_cmp_lt_u32_e32 vcc, s53, v64
	v_add_u32_e32 v64, 0xffffffa2, v14
	s_lshl_b32 s34, s34, 6
	v_cndmask_b32_e32 v83, v233, v67, vcc
	v_cmp_lt_u32_e32 vcc, s53, v64
	v_add_u32_e32 v64, 0xffffff87, v14
	s_ashr_i32 s35, s34, 31
	v_cndmask_b32_e32 v102, v233, v115, vcc
	v_cmp_lt_u32_e32 vcc, s53, v64
	v_add_u32_e32 v64, 0xffffffa7, v14
	v_add_f32_e32 v1, v1, v180
	v_cndmask_b32_e32 v105, v233, v68, vcc
	v_cmp_lt_u32_e32 vcc, s53, v64
	v_add_u32_e32 v64, 0xffffff88, v14
	v_add_u32_e32 v68, 0xffffff9a, v14
	v_cndmask_b32_e32 v103, v233, v116, vcc
	v_cmp_lt_u32_e32 vcc, s53, v64
	v_add_u32_e32 v64, 0xffffffa8, v14
	s_add_i32 s26, s23, 1
	v_cndmask_b32_e32 v107, v233, v69, vcc
	v_cmp_lt_u32_e32 vcc, s53, v64
	v_add_u32_e32 v64, 0xffffff89, v14
	s_nop 0
	v_cndmask_b32_e32 v104, v233, v117, vcc
	v_cmp_lt_u32_e32 vcc, s53, v64
	v_add_u32_e32 v64, 0xffffffa9, v14
	s_nop 0
	v_cndmask_b32_e32 v109, v233, v70, vcc
	v_cmp_lt_u32_e32 vcc, s53, v64
	v_add_u32_e32 v64, 0xffffff8a, v14
	s_nop 0
	v_cndmask_b32_e32 v106, v233, v118, vcc
	v_cmp_lt_u32_e32 vcc, s53, v64
	v_add_u32_e32 v64, 0xffffffaa, v14
	s_nop 0
	v_cndmask_b32_e32 v111, v233, v71, vcc
	v_cmp_lt_u32_e32 vcc, s53, v64
	v_add_u32_e32 v64, 0xffffff8f, v14
	s_nop 0
	v_cndmask_b32_e32 v108, v233, v119, vcc
	v_cmp_lt_u32_e32 vcc, s53, v64
	v_add_u32_e32 v64, 0xffffffaf, v14
	s_nop 0
	v_cndmask_b32_e32 v113, v233, v72, vcc
	v_cmp_lt_u32_e32 vcc, s53, v64
	v_add_u32_e32 v64, 0xffffff90, v14
	s_nop 0
	v_cndmask_b32_e32 v110, v233, v120, vcc
	v_cmp_lt_u32_e32 vcc, s53, v64
	v_add_u32_e32 v64, 0xffffffb0, v14
	s_nop 0
	v_cndmask_b32_e32 v115, v233, v73, vcc
	v_cmp_lt_u32_e32 vcc, s53, v64
	v_add_u32_e32 v64, 0xffffff91, v14
	s_nop 0
	v_cndmask_b32_e32 v112, v233, v121, vcc
	v_cmp_lt_u32_e32 vcc, s53, v64
	v_add_u32_e32 v64, 0xffffffb1, v14
	s_nop 0
	v_cndmask_b32_e32 v117, v233, v74, vcc
	v_cmp_lt_u32_e32 vcc, s53, v64
	v_add_u32_e32 v64, 0xffffff92, v14
	s_nop 0
	v_cndmask_b32_e32 v114, v233, v122, vcc
	v_cmp_lt_u32_e32 vcc, s53, v64
	v_add_u32_e32 v64, 0xffffffb2, v14
	s_nop 0
	v_cndmask_b32_e32 v119, v233, v75, vcc
	v_cmp_lt_u32_e32 vcc, s53, v64
	v_add_u32_e32 v64, 0xffffff97, v14
	s_nop 0
	v_cndmask_b32_e32 v116, v233, v123, vcc
	v_cmp_lt_u32_e32 vcc, s53, v64
	v_add_u32_e32 v64, 0xffffffb7, v14
	s_nop 0
	v_cndmask_b32_e32 v121, v233, v76, vcc
	v_cmp_lt_u32_e32 vcc, s53, v64
	v_add_u32_e32 v64, 0xffffff98, v14
	s_nop 0
	v_cndmask_b32_e32 v118, v233, v124, vcc
	v_cmp_lt_u32_e32 vcc, s53, v64
	v_add_u32_e32 v64, 0xffffffb8, v14
	s_nop 0
	v_cndmask_b32_e32 v123, v233, v77, vcc
	v_cmp_lt_u32_e32 vcc, s53, v64
	v_add_u32_e32 v64, 0xffffff99, v14
	s_nop 0
	v_cndmask_b32_e32 v120, v233, v125, vcc
	v_cmp_lt_u32_e32 vcc, s53, v64
	v_add_u32_e32 v64, 0xffffffb9, v14
	v_add_u32_e32 v14, 0xffffffba, v14
	v_cndmask_b32_e32 v125, v233, v78, vcc
	v_cmp_lt_u32_e32 vcc, s53, v64
	s_nop 1
	v_cndmask_b32_e32 v122, v233, v126, vcc
	v_cmp_lt_u32_e32 vcc, s53, v14
	v_add_u32_e32 v14, s24, v203
	s_add_i32 s24, s27, -4
	s_waitcnt vmcnt(2)
	ds_write_b128 v14, v[10:13] offset:36864
	v_add_u32_e32 v14, s25, v201
	s_ashr_i32 s25, s24, 31
	v_cndmask_b32_e32 v124, v233, v127, vcc
	s_lshl_b64 vcc, s[24:25], 13
	v_lshl_add_u64 v[10:11], v[198:199], 0, vcc
	global_load_dwordx4 v[96:99], v[10:11], off
	v_lshl_add_u64 v[10:11], s[34:35], 1, v[196:197]
	global_load_dwordx4 v[10:13], v[10:11], off
	ds_read_b128 v[240:243], v201 offset:9216
	ds_read_b128 v[244:247], v201 offset:13824
	ds_read_b128 v[64:67], v14 offset:41472
	ds_read_b128 v[70:73], v14 offset:36864
	ds_read_b128 v[74:77], v14 offset:36896
	ds_read_b128 v[92:95], v14 offset:41504
	ds_read_b128 v[144:147], v14 offset:36928
	ds_read_b128 v[172:175], v14 offset:41536
	ds_read_b128 v[176:179], v14 offset:36960
	ds_read_b128 v[204:207], v14 offset:41568
	s_setprio 1
	v_mov_b32_e32 v14, 0
	v_cvt_pk_bf16_f32 v208, v168, v169
	v_cvt_pk_bf16_f32 v209, v170, v171
	v_cvt_pk_bf16_f32 v210, v140, v141
	v_cvt_pk_bf16_f32 v211, v142, v143
	s_waitcnt lgkmcnt(6)
	s_nop 0
	v_mfma_f32_32x32x16_bf16 v[16:31], v[70:73], v[208:211], v[16:31]
	v_add_f32_e32 v14, v14, v168
	v_add_f32_e32 v14, v14, v169
	v_add_f32_e32 v14, v14, v170
	v_add_f32_e32 v14, v14, v171
	s_nop 0
	v_mfma_f32_32x32x16_bf16 v[32:47], v[64:67], v[208:211], v[32:47]
	v_cvt_pk_bf16_f32 v70, v148, v149
	v_cvt_pk_bf16_f32 v71, v150, v151
	v_cvt_pk_bf16_f32 v72, v132, v133
	v_cvt_pk_bf16_f32 v73, v134, v135
	v_add_f32_e32 v14, v14, v140
	v_add_f32_e32 v14, v14, v141
	v_add_f32_e32 v14, v14, v142
	v_add_f32_e32 v14, v14, v143
	s_waitcnt lgkmcnt(5)
	v_mfma_f32_32x32x16_bf16 v[16:31], v[74:77], v[70:73], v[16:31]
	v_add_f32_e32 v14, v14, v148
	v_add_f32_e32 v14, v14, v149
	v_add_f32_e32 v14, v14, v150
	v_add_f32_e32 v14, v14, v151
	s_waitcnt lgkmcnt(4)
	v_mfma_f32_32x32x16_bf16 v[32:47], v[92:95], v[70:73], v[32:47]
	v_cvt_pk_bf16_f32 v64, v136, v137
	v_cvt_pk_bf16_f32 v65, v138, v139
	v_cvt_pk_bf16_f32 v66, v128, v129
	v_cvt_pk_bf16_f32 v67, v130, v131
	v_add_f32_e32 v14, v14, v132
	v_add_f32_e32 v14, v14, v133
	v_add_f32_e32 v14, v14, v134
	v_add_f32_e32 v14, v14, v135
	s_waitcnt lgkmcnt(3)
	v_mfma_f32_32x32x16_bf16 v[16:31], v[144:147], v[64:67], v[16:31]
	v_add_f32_e32 v14, v14, v136
	v_add_f32_e32 v14, v14, v137
	v_add_f32_e32 v14, v14, v138
	v_add_f32_e32 v14, v14, v139
	s_waitcnt lgkmcnt(2)
	v_mfma_f32_32x32x16_bf16 v[32:47], v[172:175], v[64:67], v[32:47]
	v_cvt_pk_bf16_f32 v70, v84, v85
	v_cvt_pk_bf16_f32 v71, v86, v87
	v_cvt_pk_bf16_f32 v72, v88, v89
	v_cvt_pk_bf16_f32 v73, v90, v91
	v_add_f32_e32 v14, v14, v128
	v_add_f32_e32 v14, v14, v129
	v_add_f32_e32 v14, v14, v130
	v_add_f32_e32 v14, v14, v131
	s_waitcnt lgkmcnt(1)
	v_mfma_f32_32x32x16_bf16 v[16:31], v[176:179], v[70:73], v[16:31]
	v_add_f32_e32 v14, v14, v84
	v_add_f32_e32 v14, v14, v85
	v_add_f32_e32 v14, v14, v86
	v_add_f32_e32 v14, v14, v87
	s_waitcnt lgkmcnt(0)
	v_mfma_f32_32x32x16_bf16 v[32:47], v[204:207], v[70:73], v[32:47]
	v_add_f32_e32 v14, v14, v88
	v_add_f32_e32 v14, v14, v89
	v_add_f32_e32 v14, v14, v90
	v_add_f32_e32 v14, v14, v91
	s_setprio 0
	ds_read_b128 v[130:133], v201 offset:9248
	ds_read_b128 v[168:171], v201 offset:13856
	ds_read_b128 v[172:175], v201 offset:9280
	ds_read_b128 v[176:179], v201 offset:13888
	ds_read_b128 v[204:207], v201 offset:9312
	ds_read_b128 v[208:211], v201 offset:13920
	v_cmp_lt_u32_e32 vcc, s53, v68
	s_cmp_lg_u32 s23, 4
	s_cselect_b32 s23, s26, 0
	v_cndmask_b32_e32 v135, v233, v79, vcc
	s_waitcnt lgkmcnt(6)
	v_mfma_f32_32x32x16_bf16 v[64:79], v[240:243], v[164:167], v[48:63]
	v_exp_f32_e32 v148, v80
	v_exp_f32_e32 v149, v81
	v_exp_f32_e32 v150, v82
	v_exp_f32_e32 v151, v83
	v_mfma_f32_32x32x16_bf16 v[80:95], v[244:247], v[164:167], v[48:63]
	v_exp_f32_e32 v142, v105
	v_exp_f32_e32 v143, v107
	v_exp_f32_e32 v144, v109
	v_exp_f32_e32 v147, v111
	s_waitcnt lgkmcnt(5)
	v_mfma_f32_32x32x16_bf16 v[64:79], v[130:133], v[160:163], v[64:79]
	v_exp_f32_e32 v136, v113
	v_exp_f32_e32 v137, v115
	v_exp_f32_e32 v138, v117
	v_exp_f32_e32 v140, v119
	s_waitcnt lgkmcnt(4)
	v_mfma_f32_32x32x16_bf16 v[80:95], v[168:171], v[160:163], v[80:95]
	v_exp_f32_e32 v130, v121
	v_exp_f32_e32 v131, v123
	v_exp_f32_e32 v133, v125
	v_exp_f32_e32 v134, v135
	s_waitcnt lgkmcnt(3)
	v_mfma_f32_32x32x16_bf16 v[64:79], v[172:175], v[156:159], v[64:79]
	v_exp_f32_e32 v125, v15
	v_exp_f32_e32 v126, v100
	v_exp_f32_e32 v127, v101
	v_exp_f32_e32 v128, v102
	s_waitcnt lgkmcnt(2)
	v_mfma_f32_32x32x16_bf16 v[80:95], v[176:179], v[156:159], v[80:95]
	v_exp_f32_e32 v117, v103
	v_exp_f32_e32 v119, v104
	v_exp_f32_e32 v121, v106
	v_exp_f32_e32 v123, v108
	s_waitcnt lgkmcnt(1)
	v_mfma_f32_32x32x16_bf16 v[64:79], v[204:207], v[152:155], v[64:79]
	v_exp_f32_e32 v108, v110
	v_exp_f32_e32 v109, v112
	v_exp_f32_e32 v111, v114
	v_exp_f32_e32 v113, v116
	s_waitcnt lgkmcnt(0)
	v_mfma_f32_32x32x16_bf16 v[80:95], v[208:211], v[152:155], v[80:95]
	v_exp_f32_e32 v110, v118
	v_exp_f32_e32 v112, v120
	v_exp_f32_e32 v114, v122
	v_exp_f32_e32 v115, v124
	s_cmp_gt_i32 s23, 2
	v_sub_u32_e32 v15, s22, v202
	s_cselect_b32 s22, -3, 2
	s_add_i32 s22, s22, s23
	s_mulk_i32 s22, 0x2400
	s_nop 7
	s_nop 3
	s_waitcnt vmcnt(3)
	ds_write_b128 v203, v[2:5] offset:27648
	v_add_u32_e32 v2, s22, v203
	s_add_i32 s22, s23, 1
	s_cmp_lg_u32 s23, 4
	s_cselect_b32 s25, s22, 0
	s_add_i32 s26, s45, 8
	s_min_i32 s22, s26, s92
	s_cmp_gt_i32 s22, 3
	s_cselect_b32 s23, s13, 0
	s_add_i32 s34, s23, s22
	s_ashr_i32 s35, s34, 31
	s_lshl_b64 s[22:23], s[34:35], 13
	s_waitcnt vmcnt(2)
	ds_write_b128 v2, v[6:9] offset:36864
	v_lshl_add_u64 v[2:3], v[198:199], 0, s[22:23]
	s_lshl_b32 s22, s24, 6
	s_ashr_i32 s23, s22, 31
	v_lshl_add_u64 v[6:7], s[22:23], 1, v[196:197]
	s_waitcnt lgkmcnt(0)
	s_barrier
	global_load_dwordx4 v[2:5], v[2:3], off
	v_add_u32_e32 v168, v15, v183
	global_load_dwordx4 v[6:9], v[6:7], off
	v_add_u32_e32 v15, 0xffffff7f, v168
	v_cmp_lt_u32_e32 vcc, s53, v15
	v_add_u32_e32 v15, 0xffffff9f, v168
	s_mul_i32 s22, s25, 0x2400
	v_cndmask_b32_e32 v101, v233, v64, vcc
	v_cmp_lt_u32_e32 vcc, s53, v15
	v_add_u32_e32 v64, 0xffffff80, v168
	s_add_i32 s23, s22, 0xffffdc00
	v_cndmask_b32_e32 v15, v233, v80, vcc
	v_cmp_lt_u32_e32 vcc, s53, v64
	v_add_u32_e32 v64, 0xffffffa0, v168
	s_cmp_lg_u32 s25, 0
	v_cndmask_b32_e32 v80, v233, v65, vcc
	v_cmp_lt_u32_e32 vcc, s53, v64
	v_add_u32_e32 v64, 0xffffff81, v168
	v_add_u32_e32 v65, 0xffffffba, v168
	v_cndmask_b32_e32 v100, v233, v81, vcc
	v_cmp_lt_u32_e32 vcc, s53, v64
	v_add_u32_e32 v64, 0xffffffa1, v168
	s_cselect_b32 s23, s23, 0x9000
	v_cndmask_b32_e32 v81, v233, v66, vcc
	v_cmp_lt_u32_e32 vcc, s53, v64
	v_add_u32_e32 v64, 0xffffff82, v168
	s_nop 0
	v_cndmask_b32_e32 v102, v233, v82, vcc
	v_cmp_lt_u32_e32 vcc, s53, v64
	v_add_u32_e32 v64, 0xffffffa2, v168
	s_nop 0
	v_cndmask_b32_e32 v82, v233, v67, vcc
	v_cmp_lt_u32_e32 vcc, s53, v64
	v_add_u32_e32 v64, 0xffffff87, v168
	s_nop 0
	v_cndmask_b32_e32 v103, v233, v83, vcc
	v_cmp_lt_u32_e32 vcc, s53, v64
	v_add_u32_e32 v64, 0xffffffa7, v168
	v_add_u32_e32 v83, s23, v201
	v_cndmask_b32_e32 v106, v233, v68, vcc
	v_cmp_lt_u32_e32 vcc, s53, v64
	v_add_u32_e32 v64, 0xffffff88, v168
	s_nop 0
	v_cndmask_b32_e32 v104, v233, v84, vcc
	v_cmp_lt_u32_e32 vcc, s53, v64
	v_add_u32_e32 v64, 0xffffffa8, v168
	s_nop 0
	v_cndmask_b32_e32 v116, v233, v69, vcc
	v_cmp_lt_u32_e32 vcc, s53, v64
	v_add_u32_e32 v64, 0xffffff89, v168
	s_nop 0
	v_cndmask_b32_e32 v105, v233, v85, vcc
	v_cmp_lt_u32_e32 vcc, s53, v64
	v_add_u32_e32 v64, 0xffffffa9, v168
	s_nop 0
	v_cndmask_b32_e32 v120, v233, v70, vcc
	v_cmp_lt_u32_e32 vcc, s53, v64
	v_add_u32_e32 v64, 0xffffff8a, v168
	s_nop 0
	v_cndmask_b32_e32 v107, v233, v86, vcc
	v_cmp_lt_u32_e32 vcc, s53, v64
	v_add_u32_e32 v64, 0xffffffaa, v168
	s_nop 0
	v_cndmask_b32_e32 v124, v233, v71, vcc
	v_cmp_lt_u32_e32 vcc, s53, v64
	v_add_u32_e32 v64, 0xffffff8f, v168
	s_nop 0
	v_cndmask_b32_e32 v118, v233, v87, vcc
	v_cmp_lt_u32_e32 vcc, s53, v64
	v_add_u32_e32 v64, 0xffffffaf, v168
	s_nop 0
	v_cndmask_b32_e32 v129, v233, v72, vcc
	v_cmp_lt_u32_e32 vcc, s53, v64
	v_add_u32_e32 v64, 0xffffff90, v168
	s_nop 0
	v_cndmask_b32_e32 v122, v233, v88, vcc
	v_cmp_lt_u32_e32 vcc, s53, v64
	v_add_u32_e32 v64, 0xffffffb0, v168
	s_nop 0
	v_cndmask_b32_e32 v135, v233, v73, vcc
	v_cmp_lt_u32_e32 vcc, s53, v64
	v_add_u32_e32 v64, 0xffffff91, v168
	s_nop 0
	v_cndmask_b32_e32 v132, v233, v89, vcc
	v_cmp_lt_u32_e32 vcc, s53, v64
	v_add_u32_e32 v64, 0xffffffb1, v168
	s_nop 0
	v_cndmask_b32_e32 v141, v233, v74, vcc
	v_cmp_lt_u32_e32 vcc, s53, v64
	v_add_u32_e32 v64, 0xffffff92, v168
	s_nop 0
	v_cndmask_b32_e32 v139, v233, v90, vcc
	v_cmp_lt_u32_e32 vcc, s53, v64
	v_add_u32_e32 v64, 0xffffffb2, v168
	s_nop 0
	v_cndmask_b32_e32 v175, v233, v75, vcc
	v_cmp_lt_u32_e32 vcc, s53, v64
	v_add_u32_e32 v64, 0xffffff97, v168
	s_nop 0
	v_cndmask_b32_e32 v145, v233, v91, vcc
	v_cmp_lt_u32_e32 vcc, s53, v64
	v_add_u32_e32 v64, 0xffffffb7, v168
	s_nop 0
	v_cndmask_b32_e32 v177, v233, v76, vcc
	v_cmp_lt_u32_e32 vcc, s53, v64
	v_add_u32_e32 v64, 0xffffff98, v168
	s_nop 0
	v_cndmask_b32_e32 v146, v233, v92, vcc
	v_cmp_lt_u32_e32 vcc, s53, v64
	v_add_u32_e32 v64, 0xffffffb8, v168
	s_nop 0
	v_cndmask_b32_e32 v179, v233, v77, vcc
	v_cmp_lt_u32_e32 vcc, s53, v64
	v_add_u32_e32 v64, 0xffffff99, v168
	s_nop 0
	v_cndmask_b32_e32 v176, v233, v93, vcc
	v_cmp_lt_u32_e32 vcc, s53, v64
	v_add_u32_e32 v64, 0xffffffb9, v168
	s_nop 0
	v_cndmask_b32_e32 v181, v233, v78, vcc
	v_cmp_lt_u32_e32 vcc, s53, v64
	v_add_u32_e32 v64, 0xffffff9a, v168
	s_nop 0
	v_cndmask_b32_e32 v178, v233, v94, vcc
	v_cmp_lt_u32_e32 vcc, s53, v65
	s_nop 1
	v_cndmask_b32_e32 v180, v233, v95, vcc
	v_cmp_lt_u32_e32 vcc, s53, v64
	s_nop 1
	v_cndmask_b32_e32 v185, v233, v79, vcc
	ds_read_b128 v[240:243], v201 offset:18432
	ds_read_b128 v[244:247], v201 offset:23040
	ds_read_b128 v[64:67], v83 offset:41472
	ds_read_b128 v[68:71], v83 offset:36864
	ds_read_b128 v[72:75], v83 offset:36896
	ds_read_b128 v[76:79], v83 offset:41504
	ds_read_b128 v[84:87], v83 offset:36928
	ds_read_b128 v[88:91], v83 offset:41536
	ds_read_b128 v[92:95], v83 offset:36960
	ds_read_b128 v[168:171], v83 offset:41568
	s_setprio 3
	v_mov_b32_e32 v186, 0
	v_cvt_pk_bf16_f32 v204, v148, v149
	v_cvt_pk_bf16_f32 v205, v150, v151
	v_cvt_pk_bf16_f32 v206, v142, v143
	v_cvt_pk_bf16_f32 v207, v144, v147
	s_waitcnt lgkmcnt(6)
	s_nop 0
	v_mfma_f32_32x32x16_bf16 v[16:31], v[68:71], v[204:207], v[16:31]
	v_add_f32_e32 v186, v186, v148
	v_add_f32_e32 v186, v186, v149
	v_add_f32_e32 v186, v186, v150
	v_add_f32_e32 v186, v186, v151
	s_nop 0
	v_mfma_f32_32x32x16_bf16 v[32:47], v[64:67], v[204:207], v[32:47]
	v_cvt_pk_bf16_f32 v68, v136, v137
	v_cvt_pk_bf16_f32 v69, v138, v140
	v_cvt_pk_bf16_f32 v70, v130, v131
	v_cvt_pk_bf16_f32 v71, v133, v134
	v_add_f32_e32 v186, v186, v142
	v_add_f32_e32 v186, v186, v143
	v_add_f32_e32 v186, v186, v144
	v_add_f32_e32 v186, v186, v147
	s_waitcnt lgkmcnt(5)
	v_mfma_f32_32x32x16_bf16 v[16:31], v[72:75], v[68:71], v[16:31]
	v_add_f32_e32 v186, v186, v136
	v_add_f32_e32 v186, v186, v137
	v_add_f32_e32 v186, v186, v138
	v_add_f32_e32 v186, v186, v140
	s_waitcnt lgkmcnt(4)
	v_mfma_f32_32x32x16_bf16 v[32:47], v[76:79], v[68:71], v[32:47]
	v_cvt_pk_bf16_f32 v64, v125, v126
	v_cvt_pk_bf16_f32 v65, v127, v128
	v_cvt_pk_bf16_f32 v66, v117, v119
	v_cvt_pk_bf16_f32 v67, v121, v123
	v_add_f32_e32 v186, v186, v130
	v_add_f32_e32 v186, v186, v131
	v_add_f32_e32 v186, v186, v133
	v_add_f32_e32 v186, v186, v134
	s_waitcnt lgkmcnt(3)
	v_mfma_f32_32x32x16_bf16 v[16:31], v[84:87], v[64:67], v[16:31]
	v_add_f32_e32 v186, v186, v125
	v_add_f32_e32 v186, v186, v126
	v_add_f32_e32 v186, v186, v127
	v_add_f32_e32 v186, v186, v128
	s_waitcnt lgkmcnt(2)
	v_mfma_f32_32x32x16_bf16 v[32:47], v[88:91], v[64:67], v[32:47]
	v_cvt_pk_bf16_f32 v68, v108, v109
	v_cvt_pk_bf16_f32 v69, v111, v113
	v_cvt_pk_bf16_f32 v70, v110, v112
	v_cvt_pk_bf16_f32 v71, v114, v115
	v_add_f32_e32 v186, v186, v117
	v_add_f32_e32 v186, v186, v119
	v_add_f32_e32 v186, v186, v121
	v_add_f32_e32 v186, v186, v123
	s_waitcnt lgkmcnt(1)
	v_mfma_f32_32x32x16_bf16 v[16:31], v[92:95], v[68:71], v[16:31]
	v_add_f32_e32 v186, v186, v108
	v_add_f32_e32 v186, v186, v109
	v_add_f32_e32 v186, v186, v111
	v_add_f32_e32 v186, v186, v113
	s_waitcnt lgkmcnt(0)
	v_mfma_f32_32x32x16_bf16 v[32:47], v[168:171], v[68:71], v[32:47]
	v_add_f32_e32 v186, v186, v110
	v_add_f32_e32 v186, v186, v112
	v_add_f32_e32 v186, v186, v114
	v_add_f32_e32 v186, v186, v115
	s_setprio 2
	ds_read_b128 v[112:115], v201 offset:18464
	ds_read_b128 v[204:207], v201 offset:23072
	ds_read_b128 v[208:211], v201 offset:18496
	ds_read_b128 v[212:215], v201 offset:23104
	ds_read_b128 v[216:219], v201 offset:18528
	ds_read_b128 v[236:239], v201 offset:23136
	v_add_f32_e32 v1, v1, v14
	s_waitcnt lgkmcnt(6)
	v_mfma_f32_32x32x16_bf16 v[64:79], v[240:243], v[164:167], v[48:63]
	v_exp_f32_e32 v171, v101
	v_exp_f32_e32 v172, v80
	v_exp_f32_e32 v173, v81
	v_exp_f32_e32 v174, v82
	v_mfma_f32_32x32x16_bf16 v[80:95], v[244:247], v[164:167], v[48:63]
	v_exp_f32_e32 v151, v106
	v_exp_f32_e32 v168, v116
	v_exp_f32_e32 v169, v120
	v_exp_f32_e32 v170, v124
	s_waitcnt lgkmcnt(5)
	v_mfma_f32_32x32x16_bf16 v[64:79], v[112:115], v[160:163], v[64:79]
	v_exp_f32_e32 v147, v129
	v_exp_f32_e32 v148, v135
	v_exp_f32_e32 v149, v141
	v_exp_f32_e32 v150, v175
	s_waitcnt lgkmcnt(4)
	v_mfma_f32_32x32x16_bf16 v[80:95], v[204:207], v[160:163], v[80:95]
	v_exp_f32_e32 v141, v177
	v_exp_f32_e32 v142, v179
	v_exp_f32_e32 v143, v181
	v_exp_f32_e32 v144, v185
	s_waitcnt lgkmcnt(3)
	v_mfma_f32_32x32x16_bf16 v[64:79], v[208:211], v[156:159], v[64:79]
	v_exp_f32_e32 v135, v15
	v_exp_f32_e32 v136, v100
	v_exp_f32_e32 v137, v102
	v_exp_f32_e32 v138, v103
	s_waitcnt lgkmcnt(2)
	v_mfma_f32_32x32x16_bf16 v[80:95], v[212:215], v[156:159], v[80:95]
	v_exp_f32_e32 v128, v104
	v_exp_f32_e32 v129, v105
	v_exp_f32_e32 v130, v107
	v_exp_f32_e32 v131, v118
	s_waitcnt lgkmcnt(1)
	v_mfma_f32_32x32x16_bf16 v[64:79], v[216:219], v[152:155], v[64:79]
	v_exp_f32_e32 v118, v122
	v_exp_f32_e32 v119, v132
	v_exp_f32_e32 v120, v139
	v_exp_f32_e32 v121, v145
	s_waitcnt lgkmcnt(0)
	v_mfma_f32_32x32x16_bf16 v[80:95], v[236:239], v[152:155], v[80:95]
	v_exp_f32_e32 v122, v146
	v_exp_f32_e32 v123, v176
	v_exp_f32_e32 v124, v178
	v_exp_f32_e32 v125, v180
	s_add_i32 s87, s87, s18
	v_lshl_add_u32 v14, s87, 6, v184
	v_add_u32_e32 v15, 0xffffff7f, v14
	v_cmp_lt_u32_e32 vcc, s53, v15
	v_add_u32_e32 v15, 0xffffff9f, v14
	s_cmp_gt_i32 s25, 2
	v_cndmask_b32_e32 v101, v233, v64, vcc
	v_cmp_lt_u32_e32 vcc, s53, v15
	v_add_u32_e32 v64, 0xffffff80, v14
	s_cselect_b32 s23, -3, 2
	v_cndmask_b32_e32 v15, v233, v80, vcc
	v_cmp_lt_u32_e32 vcc, s53, v64
	v_add_u32_e32 v64, 0xffffffa0, v14
	s_add_i32 s23, s23, s25
	v_cndmask_b32_e32 v80, v233, v65, vcc
	v_cmp_lt_u32_e32 vcc, s53, v64
	v_add_u32_e32 v64, 0xffffff81, v14
	s_mulk_i32 s23, 0x2400
	v_cndmask_b32_e32 v100, v233, v81, vcc
	v_cmp_lt_u32_e32 vcc, s53, v64
	v_add_u32_e32 v64, 0xffffffa1, v14
	s_nop 7
	s_nop 3
	s_waitcnt vmcnt(3)
	ds_write_b128 v203, v[96:99]
	v_cndmask_b32_e32 v81, v233, v66, vcc
	v_cmp_lt_u32_e32 vcc, s53, v64
	v_add_u32_e32 v64, 0xffffff82, v14
	s_add_i32 s24, s25, 1
	v_cndmask_b32_e32 v102, v233, v82, vcc
	v_cmp_lt_u32_e32 vcc, s53, v64
	v_add_u32_e32 v64, 0xffffffa2, v14
	v_add_f32_e32 v1, v1, v186
	v_cndmask_b32_e32 v82, v233, v67, vcc
	v_cmp_lt_u32_e32 vcc, s53, v64
	v_add_u32_e32 v64, 0xffffff87, v14
	s_nop 0
	v_cndmask_b32_e32 v103, v233, v83, vcc
	v_cmp_lt_u32_e32 vcc, s53, v64
	v_add_u32_e32 v64, 0xffffffa7, v14
	s_nop 0
	v_cndmask_b32_e32 v106, v233, v68, vcc
	v_cmp_lt_u32_e32 vcc, s53, v64
	v_add_u32_e32 v64, 0xffffff88, v14
	v_add_u32_e32 v68, 0xffffff9a, v14
	v_cndmask_b32_e32 v104, v233, v84, vcc
	v_cmp_lt_u32_e32 vcc, s53, v64
	v_add_u32_e32 v64, 0xffffffa8, v14
	s_nop 0
	v_cndmask_b32_e32 v108, v233, v69, vcc
	v_cmp_lt_u32_e32 vcc, s53, v64
	v_add_u32_e32 v64, 0xffffff89, v14
	s_nop 0
	v_cndmask_b32_e32 v105, v233, v85, vcc
	v_cmp_lt_u32_e32 vcc, s53, v64
	v_add_u32_e32 v64, 0xffffffa9, v14
	s_nop 0
	v_cndmask_b32_e32 v110, v233, v70, vcc
	v_cmp_lt_u32_e32 vcc, s53, v64
	v_add_u32_e32 v64, 0xffffff8a, v14
	s_nop 0
	v_cndmask_b32_e32 v107, v233, v86, vcc
	v_cmp_lt_u32_e32 vcc, s53, v64
	v_add_u32_e32 v64, 0xffffffaa, v14
	s_nop 0
	v_cndmask_b32_e32 v112, v233, v71, vcc
	v_cmp_lt_u32_e32 vcc, s53, v64
	v_add_u32_e32 v64, 0xffffff8f, v14
	s_nop 0
	v_cndmask_b32_e32 v109, v233, v87, vcc
	v_cmp_lt_u32_e32 vcc, s53, v64
	v_add_u32_e32 v64, 0xffffffaf, v14
	s_nop 0
	v_cndmask_b32_e32 v114, v233, v72, vcc
	v_cmp_lt_u32_e32 vcc, s53, v64
	v_add_u32_e32 v64, 0xffffff90, v14
	s_nop 0
	v_cndmask_b32_e32 v111, v233, v88, vcc
	v_cmp_lt_u32_e32 vcc, s53, v64
	v_add_u32_e32 v64, 0xffffffb0, v14
	s_nop 0
	v_cndmask_b32_e32 v116, v233, v73, vcc
	v_cmp_lt_u32_e32 vcc, s53, v64
	v_add_u32_e32 v64, 0xffffff91, v14
	s_nop 0
	v_cndmask_b32_e32 v113, v233, v89, vcc
	v_cmp_lt_u32_e32 vcc, s53, v64
	v_add_u32_e32 v64, 0xffffffb1, v14
	s_nop 0
	v_cndmask_b32_e32 v126, v233, v74, vcc
	v_cmp_lt_u32_e32 vcc, s53, v64
	v_add_u32_e32 v64, 0xffffff92, v14
	s_nop 0
	v_cndmask_b32_e32 v115, v233, v90, vcc
	v_cmp_lt_u32_e32 vcc, s53, v64
	v_add_u32_e32 v64, 0xffffffb2, v14
	s_nop 0
	v_cndmask_b32_e32 v132, v233, v75, vcc
	v_cmp_lt_u32_e32 vcc, s53, v64
	v_add_u32_e32 v64, 0xffffff97, v14
	s_nop 0
	v_cndmask_b32_e32 v117, v233, v91, vcc
	v_cmp_lt_u32_e32 vcc, s53, v64
	v_add_u32_e32 v64, 0xffffffb7, v14
	s_nop 0
	v_cndmask_b32_e32 v134, v233, v76, vcc
	v_cmp_lt_u32_e32 vcc, s53, v64
	v_add_u32_e32 v64, 0xffffff98, v14
	s_nop 0
	v_cndmask_b32_e32 v127, v233, v92, vcc
	v_cmp_lt_u32_e32 vcc, s53, v64
	v_add_u32_e32 v64, 0xffffffb8, v14
	s_nop 0
	v_cndmask_b32_e32 v140, v233, v77, vcc
	v_cmp_lt_u32_e32 vcc, s53, v64
	v_add_u32_e32 v64, 0xffffff99, v14
	s_nop 0
	v_cndmask_b32_e32 v133, v233, v93, vcc
	v_cmp_lt_u32_e32 vcc, s53, v64
	v_add_u32_e32 v64, 0xffffffb9, v14
	v_add_u32_e32 v14, 0xffffffba, v14
	v_cndmask_b32_e32 v146, v233, v78, vcc
	v_cmp_lt_u32_e32 vcc, s53, v64
	s_nop 1
	v_cndmask_b32_e32 v139, v233, v94, vcc
	v_cmp_lt_u32_e32 vcc, s53, v14
	v_add_u32_e32 v14, s23, v203
	s_waitcnt vmcnt(2)
	ds_write_b128 v14, v[10:13] offset:36864
	v_add_u32_e32 v14, s22, v201
	s_add_i32 s22, s45, 9
	s_min_i32 s22, s22, s92
	s_cmp_gt_i32 s22, 3
	s_cselect_b32 s23, s13, 0
	s_add_i32 s22, s23, s22
	s_ashr_i32 s23, s22, 31
	v_cndmask_b32_e32 v145, v233, v95, vcc
	s_lshl_b64 vcc, s[22:23], 13
	s_lshl_b32 s34, s34, 6
	v_lshl_add_u64 v[10:11], v[198:199], 0, vcc
	s_ashr_i32 s35, s34, 31
	global_load_dwordx4 v[96:99], v[10:11], off
	v_lshl_add_u64 v[10:11], s[34:35], 1, v[196:197]
	global_load_dwordx4 v[10:13], v[10:11], off
	ds_read_b128 v[240:243], v201 offset:27648
	ds_read_b128 v[244:247], v201 offset:32256
	ds_read_b128 v[64:67], v14 offset:41472
	ds_read_b128 v[70:73], v14 offset:36864
	ds_read_b128 v[74:77], v14 offset:36896
	ds_read_b128 v[84:87], v14 offset:41504
	ds_read_b128 v[88:91], v14 offset:36928
	ds_read_b128 v[92:95], v14 offset:41536
	ds_read_b128 v[176:179], v14 offset:36960
	ds_read_b128 v[204:207], v14 offset:41568
	s_setprio 1
	v_mov_b32_e32 v14, 0
	v_cvt_pk_bf16_f32 v208, v171, v172
	v_cvt_pk_bf16_f32 v209, v173, v174
	v_cvt_pk_bf16_f32 v210, v151, v168
	v_cvt_pk_bf16_f32 v211, v169, v170
	s_waitcnt lgkmcnt(6)
	s_nop 0
	v_mfma_f32_32x32x16_bf16 v[16:31], v[70:73], v[208:211], v[16:31]
	v_add_f32_e32 v14, v14, v171
	v_add_f32_e32 v14, v14, v172
	v_add_f32_e32 v14, v14, v173
	v_add_f32_e32 v14, v14, v174
	s_nop 0
	v_mfma_f32_32x32x16_bf16 v[32:47], v[64:67], v[208:211], v[32:47]
	v_cvt_pk_bf16_f32 v70, v147, v148
	v_cvt_pk_bf16_f32 v71, v149, v150
	v_cvt_pk_bf16_f32 v72, v141, v142
	v_cvt_pk_bf16_f32 v73, v143, v144
	v_add_f32_e32 v14, v14, v151
	v_add_f32_e32 v14, v14, v168
	v_add_f32_e32 v14, v14, v169
	v_add_f32_e32 v14, v14, v170
	s_waitcnt lgkmcnt(5)
	v_mfma_f32_32x32x16_bf16 v[16:31], v[74:77], v[70:73], v[16:31]
	v_add_f32_e32 v14, v14, v147
	v_add_f32_e32 v14, v14, v148
	v_add_f32_e32 v14, v14, v149
	v_add_f32_e32 v14, v14, v150
	s_waitcnt lgkmcnt(4)
	v_mfma_f32_32x32x16_bf16 v[32:47], v[84:87], v[70:73], v[32:47]
	v_cvt_pk_bf16_f32 v64, v135, v136
	v_cvt_pk_bf16_f32 v65, v137, v138
	v_cvt_pk_bf16_f32 v66, v128, v129
	v_cvt_pk_bf16_f32 v67, v130, v131
	v_add_f32_e32 v14, v14, v141
	v_add_f32_e32 v14, v14, v142
	v_add_f32_e32 v14, v14, v143
	v_add_f32_e32 v14, v14, v144
	s_waitcnt lgkmcnt(3)
	v_mfma_f32_32x32x16_bf16 v[16:31], v[88:91], v[64:67], v[16:31]
	v_add_f32_e32 v14, v14, v135
	v_add_f32_e32 v14, v14, v136
	v_add_f32_e32 v14, v14, v137
	v_add_f32_e32 v14, v14, v138
	s_waitcnt lgkmcnt(2)
	v_mfma_f32_32x32x16_bf16 v[32:47], v[92:95], v[64:67], v[32:47]
	v_cvt_pk_bf16_f32 v70, v118, v119
	v_cvt_pk_bf16_f32 v71, v120, v121
	v_cvt_pk_bf16_f32 v72, v122, v123
	v_cvt_pk_bf16_f32 v73, v124, v125
	v_add_f32_e32 v14, v14, v128
	v_add_f32_e32 v14, v14, v129
	v_add_f32_e32 v14, v14, v130
	v_add_f32_e32 v14, v14, v131
	s_waitcnt lgkmcnt(1)
	v_mfma_f32_32x32x16_bf16 v[16:31], v[176:179], v[70:73], v[16:31]
	v_add_f32_e32 v14, v14, v118
	v_add_f32_e32 v14, v14, v119
	v_add_f32_e32 v14, v14, v120
	v_add_f32_e32 v14, v14, v121
	s_waitcnt lgkmcnt(0)
	v_mfma_f32_32x32x16_bf16 v[32:47], v[204:207], v[70:73], v[32:47]
	v_add_f32_e32 v14, v14, v122
	v_add_f32_e32 v14, v14, v123
	v_add_f32_e32 v14, v14, v124
	v_add_f32_e32 v14, v14, v125
	s_setprio 0
	ds_read_b128 v[122:125], v201 offset:27680
	ds_read_b128 v[174:177], v201 offset:32288
	ds_read_b128 v[178:181], v201 offset:27712
	ds_read_b128 v[204:207], v201 offset:32320
	ds_read_b128 v[208:211], v201 offset:27744
	ds_read_b128 v[212:215], v201 offset:32352
	v_cmp_lt_u32_e32 vcc, s53, v68
	s_cmp_lg_u32 s25, 4
	s_cselect_b32 s23, s24, 0
	v_cndmask_b32_e32 v131, v233, v79, vcc
	s_waitcnt lgkmcnt(6)
	v_mfma_f32_32x32x16_bf16 v[64:79], v[240:243], v[164:167], v[48:63]
	v_exp_f32_e32 v169, v101
	v_exp_f32_e32 v170, v80
	v_exp_f32_e32 v171, v81
	v_exp_f32_e32 v172, v82
	v_mfma_f32_32x32x16_bf16 v[80:95], v[244:247], v[164:167], v[48:63]
	v_exp_f32_e32 v147, v106
	v_exp_f32_e32 v148, v108
	v_exp_f32_e32 v149, v110
	v_exp_f32_e32 v150, v112
	s_waitcnt lgkmcnt(5)
	v_mfma_f32_32x32x16_bf16 v[64:79], v[122:125], v[160:163], v[64:79]
	v_exp_f32_e32 v138, v114
	v_exp_f32_e32 v141, v116
	v_exp_f32_e32 v142, v126
	v_exp_f32_e32 v143, v132
	s_waitcnt lgkmcnt(4)
	v_mfma_f32_32x32x16_bf16 v[80:95], v[174:177], v[160:163], v[80:95]
	v_exp_f32_e32 v128, v134
	v_exp_f32_e32 v129, v140
	v_exp_f32_e32 v130, v146
	v_exp_f32_e32 v135, v131
	s_waitcnt lgkmcnt(3)
	v_mfma_f32_32x32x16_bf16 v[64:79], v[178:181], v[156:159], v[64:79]
	v_exp_f32_e32 v122, v15
	v_exp_f32_e32 v123, v100
	v_exp_f32_e32 v124, v102
	v_exp_f32_e32 v125, v103
	s_waitcnt lgkmcnt(2)
	v_mfma_f32_32x32x16_bf16 v[80:95], v[204:207], v[156:159], v[80:95]
	v_exp_f32_e32 v118, v104
	v_exp_f32_e32 v119, v105
	v_exp_f32_e32 v120, v107
	v_exp_f32_e32 v121, v109
	s_waitcnt lgkmcnt(1)
	v_mfma_f32_32x32x16_bf16 v[64:79], v[208:211], v[152:155], v[64:79]
	v_exp_f32_e32 v107, v111
	v_exp_f32_e32 v108, v113
	v_exp_f32_e32 v109, v115
	v_exp_f32_e32 v110, v117
	s_waitcnt lgkmcnt(0)
	v_mfma_f32_32x32x16_bf16 v[80:95], v[212:215], v[152:155], v[80:95]
	v_exp_f32_e32 v111, v127
	v_exp_f32_e32 v113, v133
	v_exp_f32_e32 v114, v139
	v_exp_f32_e32 v115, v145
	s_add_i32 s2, s2, s18
	s_cmp_gt_i32 s23, 2
	v_lshl_add_u32 v127, s2, 6, v184
	s_cselect_b32 s2, -3, 2
	s_add_i32 s2, s2, s23
	s_mulk_i32 s2, 0x2400
	s_nop 7
	s_nop 3
	s_waitcnt vmcnt(3)
	ds_write_b128 v203, v[2:5] offset:9216
	v_add_u32_e32 v2, s2, v203
	s_add_i32 s2, s23, 1
	s_cmp_lg_u32 s23, 4
	s_cselect_b32 s2, s2, 0
	s_add_i32 s23, s45, 10
	s_min_i32 s23, s23, s92
	s_cmp_gt_i32 s23, 3
	s_cselect_b32 s24, s13, 0
	s_add_i32 s24, s24, s23
	s_ashr_i32 s25, s24, 31
	s_lshl_b32 s22, s22, 6
	s_lshl_b64 s[34:35], s[24:25], 13
	s_ashr_i32 s23, s22, 31
	s_waitcnt vmcnt(2)
	ds_write_b128 v2, v[6:9] offset:36864
	v_lshl_add_u64 v[2:3], v[198:199], 0, s[34:35]
	v_lshl_add_u64 v[6:7], s[22:23], 1, v[196:197]
	s_waitcnt lgkmcnt(0)
	s_barrier
	global_load_dwordx4 v[2:5], v[2:3], off
	v_add_u32_e32 v15, 0xffffff7f, v127
	global_load_dwordx4 v[6:9], v[6:7], off
	v_cmp_lt_u32_e32 vcc, s53, v15
	v_add_u32_e32 v15, 0xffffff9f, v127
	s_mul_i32 s22, s2, 0x2400
	v_cndmask_b32_e32 v101, v233, v64, vcc
	v_cmp_lt_u32_e32 vcc, s53, v15
	v_add_u32_e32 v64, 0xffffff80, v127
	s_add_i32 s23, s22, 0xffffdc00
	v_cndmask_b32_e32 v15, v233, v80, vcc
	v_cmp_lt_u32_e32 vcc, s53, v64
	v_add_u32_e32 v64, 0xffffffa0, v127
	s_cmp_lg_u32 s2, 0
	v_cndmask_b32_e32 v80, v233, v65, vcc
	v_cmp_lt_u32_e32 vcc, s53, v64
	v_add_u32_e32 v64, 0xffffff81, v127
	v_add_u32_e32 v65, 0xffffffba, v127
	v_cndmask_b32_e32 v100, v233, v81, vcc
	v_cmp_lt_u32_e32 vcc, s53, v64
	v_add_u32_e32 v64, 0xffffffa1, v127
	s_cselect_b32 s23, s23, 0x9000
	v_cndmask_b32_e32 v81, v233, v66, vcc
	v_cmp_lt_u32_e32 vcc, s53, v64
	v_add_u32_e32 v64, 0xffffff82, v127
	s_nop 0
	v_cndmask_b32_e32 v102, v233, v82, vcc
	v_cmp_lt_u32_e32 vcc, s53, v64
	v_add_u32_e32 v64, 0xffffffa2, v127
	s_nop 0
	v_cndmask_b32_e32 v82, v233, v67, vcc
	v_cmp_lt_u32_e32 vcc, s53, v64
	v_add_u32_e32 v64, 0xffffff87, v127
	s_nop 0
	v_cndmask_b32_e32 v103, v233, v83, vcc
	v_cmp_lt_u32_e32 vcc, s53, v64
	v_add_u32_e32 v64, 0xffffffa7, v127
	v_add_u32_e32 v83, s23, v201
	v_cndmask_b32_e32 v106, v233, v68, vcc
	v_cmp_lt_u32_e32 vcc, s53, v64
	v_add_u32_e32 v64, 0xffffff88, v127
	s_nop 0
	v_cndmask_b32_e32 v104, v233, v84, vcc
	v_cmp_lt_u32_e32 vcc, s53, v64
	v_add_u32_e32 v64, 0xffffffa8, v127
	s_nop 0
	v_cndmask_b32_e32 v116, v233, v69, vcc
	v_cmp_lt_u32_e32 vcc, s53, v64
	v_add_u32_e32 v64, 0xffffff89, v127
	s_nop 0
	v_cndmask_b32_e32 v105, v233, v85, vcc
	v_cmp_lt_u32_e32 vcc, s53, v64
	v_add_u32_e32 v64, 0xffffffa9, v127
	s_nop 0
	v_cndmask_b32_e32 v117, v233, v70, vcc
	v_cmp_lt_u32_e32 vcc, s53, v64
	v_add_u32_e32 v64, 0xffffff8a, v127
	s_nop 0
	v_cndmask_b32_e32 v112, v233, v86, vcc
	v_cmp_lt_u32_e32 vcc, s53, v64
	v_add_u32_e32 v64, 0xffffffaa, v127
	s_nop 0
	v_cndmask_b32_e32 v126, v233, v71, vcc
	v_cmp_lt_u32_e32 vcc, s53, v64
	v_add_u32_e32 v64, 0xffffff8f, v127
	s_nop 0
	v_cndmask_b32_e32 v131, v233, v87, vcc
	v_cmp_lt_u32_e32 vcc, s53, v64
	v_add_u32_e32 v64, 0xffffffaf, v127
	s_nop 0
	v_cndmask_b32_e32 v134, v233, v72, vcc
	v_cmp_lt_u32_e32 vcc, s53, v64
	v_add_u32_e32 v64, 0xffffff90, v127
	s_nop 0
	v_cndmask_b32_e32 v132, v233, v88, vcc
	v_cmp_lt_u32_e32 vcc, s53, v64
	v_add_u32_e32 v64, 0xffffffb0, v127
	s_nop 0
	v_cndmask_b32_e32 v137, v233, v73, vcc
	v_cmp_lt_u32_e32 vcc, s53, v64
	v_add_u32_e32 v64, 0xffffff91, v127
	s_nop 0
	v_cndmask_b32_e32 v133, v233, v89, vcc
	v_cmp_lt_u32_e32 vcc, s53, v64
	v_add_u32_e32 v64, 0xffffffb1, v127
	s_nop 0
	v_cndmask_b32_e32 v140, v233, v74, vcc
	v_cmp_lt_u32_e32 vcc, s53, v64
	v_add_u32_e32 v64, 0xffffff92, v127
	s_nop 0
	v_cndmask_b32_e32 v136, v233, v90, vcc
	v_cmp_lt_u32_e32 vcc, s53, v64
	v_add_u32_e32 v64, 0xffffffb2, v127
	s_nop 0
	v_cndmask_b32_e32 v145, v233, v75, vcc
	v_cmp_lt_u32_e32 vcc, s53, v64
	v_add_u32_e32 v64, 0xffffff97, v127
	s_nop 0
	v_cndmask_b32_e32 v139, v233, v91, vcc
	v_cmp_lt_u32_e32 vcc, s53, v64
	v_add_u32_e32 v64, 0xffffffb7, v127
	s_nop 0
	v_cndmask_b32_e32 v151, v233, v76, vcc
	v_cmp_lt_u32_e32 vcc, s53, v64
	v_add_u32_e32 v64, 0xffffff98, v127
	s_nop 0
	v_cndmask_b32_e32 v144, v233, v92, vcc
	v_cmp_lt_u32_e32 vcc, s53, v64
	v_add_u32_e32 v64, 0xffffffb8, v127
	s_nop 0
	v_cndmask_b32_e32 v173, v233, v77, vcc
	v_cmp_lt_u32_e32 vcc, s53, v64
	v_add_u32_e32 v64, 0xffffff99, v127
	s_nop 0
	v_cndmask_b32_e32 v146, v233, v93, vcc
	v_cmp_lt_u32_e32 vcc, s53, v64
	v_add_u32_e32 v64, 0xffffffb9, v127
	s_nop 0
	v_cndmask_b32_e32 v175, v233, v78, vcc
	v_cmp_lt_u32_e32 vcc, s53, v64
	v_add_u32_e32 v64, 0xffffff9a, v127
	s_nop 0
	v_cndmask_b32_e32 v168, v233, v94, vcc
	v_cmp_lt_u32_e32 vcc, s53, v65
	s_nop 1
	v_cndmask_b32_e32 v174, v233, v95, vcc
	v_cmp_lt_u32_e32 vcc, s53, v64
	s_nop 1
	v_cndmask_b32_e32 v180, v233, v79, vcc
	ds_read_b128 v[240:243], v201
	ds_read_b128 v[244:247], v201 offset:4608
	ds_read_b128 v[64:67], v83 offset:41472
	ds_read_b128 v[68:71], v83 offset:36864
	ds_read_b128 v[72:75], v83 offset:36896
	ds_read_b128 v[76:79], v83 offset:41504
	ds_read_b128 v[84:87], v83 offset:36928
	ds_read_b128 v[88:91], v83 offset:41536
	ds_read_b128 v[92:95], v83 offset:36960
	ds_read_b128 v[176:179], v83 offset:41568
	s_setprio 3
	v_mov_b32_e32 v230, 0
	v_cvt_pk_bf16_f32 v204, v169, v170
	v_cvt_pk_bf16_f32 v205, v171, v172
	v_cvt_pk_bf16_f32 v206, v147, v148
	v_cvt_pk_bf16_f32 v207, v149, v150
	s_waitcnt lgkmcnt(6)
	s_nop 0
	v_mfma_f32_32x32x16_bf16 v[16:31], v[68:71], v[204:207], v[16:31]
	v_add_f32_e32 v230, v230, v169
	v_add_f32_e32 v230, v230, v170
	v_add_f32_e32 v230, v230, v171
	v_add_f32_e32 v230, v230, v172
	s_nop 0
	v_mfma_f32_32x32x16_bf16 v[32:47], v[64:67], v[204:207], v[32:47]
	v_cvt_pk_bf16_f32 v68, v138, v141
	v_cvt_pk_bf16_f32 v69, v142, v143
	v_cvt_pk_bf16_f32 v70, v128, v129
	v_cvt_pk_bf16_f32 v71, v130, v135
	v_add_f32_e32 v230, v230, v147
	v_add_f32_e32 v230, v230, v148
	v_add_f32_e32 v230, v230, v149
	v_add_f32_e32 v230, v230, v150
	s_waitcnt lgkmcnt(5)
	v_mfma_f32_32x32x16_bf16 v[16:31], v[72:75], v[68:71], v[16:31]
	v_add_f32_e32 v230, v230, v138
	v_add_f32_e32 v230, v230, v141
	v_add_f32_e32 v230, v230, v142
	v_add_f32_e32 v230, v230, v143
	s_waitcnt lgkmcnt(4)
	v_mfma_f32_32x32x16_bf16 v[32:47], v[76:79], v[68:71], v[32:47]
	v_cvt_pk_bf16_f32 v64, v122, v123
	v_cvt_pk_bf16_f32 v65, v124, v125
	v_cvt_pk_bf16_f32 v66, v118, v119
	v_cvt_pk_bf16_f32 v67, v120, v121
	v_add_f32_e32 v230, v230, v128
	v_add_f32_e32 v230, v230, v129
	v_add_f32_e32 v230, v230, v130
	v_add_f32_e32 v230, v230, v135
	s_waitcnt lgkmcnt(3)
	v_mfma_f32_32x32x16_bf16 v[16:31], v[84:87], v[64:67], v[16:31]
	v_add_f32_e32 v230, v230, v122
	v_add_f32_e32 v230, v230, v123
	v_add_f32_e32 v230, v230, v124
	v_add_f32_e32 v230, v230, v125
	s_waitcnt lgkmcnt(2)
	v_mfma_f32_32x32x16_bf16 v[32:47], v[88:91], v[64:67], v[32:47]
	v_cvt_pk_bf16_f32 v68, v107, v108
	v_cvt_pk_bf16_f32 v69, v109, v110
	v_cvt_pk_bf16_f32 v70, v111, v113
	v_cvt_pk_bf16_f32 v71, v114, v115
	v_add_f32_e32 v230, v230, v118
	v_add_f32_e32 v230, v230, v119
	v_add_f32_e32 v230, v230, v120
	v_add_f32_e32 v230, v230, v121
	s_waitcnt lgkmcnt(1)
	v_mfma_f32_32x32x16_bf16 v[16:31], v[92:95], v[68:71], v[16:31]
	v_add_f32_e32 v230, v230, v107
	v_add_f32_e32 v230, v230, v108
	v_add_f32_e32 v230, v230, v109
	v_add_f32_e32 v230, v230, v110
	s_waitcnt lgkmcnt(0)
	v_mfma_f32_32x32x16_bf16 v[32:47], v[176:179], v[68:71], v[32:47]
	v_add_f32_e32 v230, v230, v111
	v_add_f32_e32 v230, v230, v113
	v_add_f32_e32 v230, v230, v114
	v_add_f32_e32 v230, v230, v115
	s_setprio 2
	ds_read_b128 v[118:121], v201 offset:32
	ds_read_b128 v[176:179], v201 offset:4640
	ds_read_b128 v[206:209], v201 offset:64
	ds_read_b128 v[210:213], v201 offset:4672
	ds_read_b128 v[214:217], v201 offset:96
	ds_read_b128 v[218:221], v201 offset:4704
	v_add_f32_e32 v169, v1, v14
	s_waitcnt lgkmcnt(6)
	v_mfma_f32_32x32x16_bf16 v[64:79], v[240:243], v[164:167], v[48:63]
	v_exp_f32_e32 v185, v101
	v_exp_f32_e32 v186, v80
	v_exp_f32_e32 v187, v81
	v_exp_f32_e32 v204, v82
	v_mfma_f32_32x32x16_bf16 v[80:95], v[244:247], v[164:167], v[48:63]
	v_exp_f32_e32 v127, v106
	v_exp_f32_e32 v128, v116
	v_exp_f32_e32 v129, v117
	v_exp_f32_e32 v130, v126
	s_waitcnt lgkmcnt(5)
	v_mfma_f32_32x32x16_bf16 v[64:79], v[118:121], v[160:163], v[64:79]
	v_exp_f32_e32 v123, v134
	v_exp_f32_e32 v124, v137
	v_exp_f32_e32 v125, v140
	v_exp_f32_e32 v126, v145
	s_waitcnt lgkmcnt(4)
	v_mfma_f32_32x32x16_bf16 v[80:95], v[176:179], v[160:163], v[80:95]
	v_exp_f32_e32 v119, v151
	v_exp_f32_e32 v120, v173
	v_exp_f32_e32 v121, v175
	v_exp_f32_e32 v122, v180
	s_waitcnt lgkmcnt(3)
	v_mfma_f32_32x32x16_bf16 v[64:79], v[206:209], v[156:159], v[64:79]
	v_exp_f32_e32 v111, v15
	v_exp_f32_e32 v116, v100
	v_exp_f32_e32 v117, v102
	v_exp_f32_e32 v118, v103
	s_waitcnt lgkmcnt(2)
	v_mfma_f32_32x32x16_bf16 v[80:95], v[210:213], v[156:159], v[80:95]
	v_exp_f32_e32 v107, v104
	v_exp_f32_e32 v108, v105
	v_exp_f32_e32 v109, v112
	v_exp_f32_e32 v110, v131
	s_waitcnt lgkmcnt(1)
	v_mfma_f32_32x32x16_bf16 v[64:79], v[214:217], v[152:155], v[64:79]
	v_exp_f32_e32 v103, v132
	v_exp_f32_e32 v104, v133
	v_exp_f32_e32 v105, v136
	v_exp_f32_e32 v106, v139
	s_waitcnt lgkmcnt(0)
	v_mfma_f32_32x32x16_bf16 v[80:95], v[218:221], v[152:155], v[80:95]
	v_exp_f32_e32 v1, v144
	v_exp_f32_e32 v100, v146
	v_exp_f32_e32 v101, v168
	v_exp_f32_e32 v102, v174
	v_lshl_add_u32 v131, s27, 6, v184
	v_add_u32_e32 v14, 0xffffff7f, v131
	v_cmp_lt_u32_e32 vcc, s53, v14
	v_add_u32_e32 v14, 0xffffff9f, v131
	v_add_u32_e32 v15, 0xffffff80, v131
	v_cndmask_b32_e32 v112, v233, v64, vcc
	v_cmp_lt_u32_e32 vcc, s53, v14
	v_add_u32_e32 v64, 0xffffff81, v131
	s_cmp_gt_i32 s2, 2
	v_cndmask_b32_e32 v14, v233, v80, vcc
	v_cmp_lt_u32_e32 vcc, s53, v15
	v_add_u32_e32 v15, 0xffffffa0, v131
	s_cselect_b32 s23, -3, 2
	v_cndmask_b32_e32 v113, v233, v65, vcc
	v_cmp_lt_u32_e32 vcc, s53, v15
	s_add_i32 s23, s23, s2
	v_add_u32_e32 v65, 0xffffffba, v131
	v_cndmask_b32_e32 v15, v233, v81, vcc
	v_cmp_lt_u32_e32 vcc, s53, v64
	v_add_u32_e32 v64, 0xffffffa1, v131
	s_mulk_i32 s23, 0x2400
	v_cndmask_b32_e32 v114, v233, v66, vcc
	v_cmp_lt_u32_e32 vcc, s53, v64
	v_add_u32_e32 v64, 0xffffff82, v131
	s_nop 7
	s_nop 3
	s_waitcnt vmcnt(3)
	ds_write_b128 v203, v[96:99] offset:18432
	v_cndmask_b32_e32 v132, v233, v82, vcc
	v_cmp_lt_u32_e32 vcc, s53, v64
	v_add_u32_e32 v64, 0xffffffa2, v131
	v_add_f32_e32 v96, v169, v230
	v_cndmask_b32_e32 v115, v233, v67, vcc
	v_cmp_lt_u32_e32 vcc, s53, v64
	v_add_u32_e32 v64, 0xffffff87, v131
	s_nop 0
	v_cndmask_b32_e32 v133, v233, v83, vcc
	v_cmp_lt_u32_e32 vcc, s53, v64
	v_add_u32_e32 v64, 0xffffffa7, v131
	s_nop 0
	v_cndmask_b32_e32 v140, v233, v68, vcc
	v_cmp_lt_u32_e32 vcc, s53, v64
	v_add_u32_e32 v64, 0xffffff88, v131
	s_nop 0
	v_cndmask_b32_e32 v134, v233, v84, vcc
	v_cmp_lt_u32_e32 vcc, s53, v64
	v_add_u32_e32 v64, 0xffffffa8, v131
	s_nop 0
	v_cndmask_b32_e32 v141, v233, v69, vcc
	v_cmp_lt_u32_e32 vcc, s53, v64
	v_add_u32_e32 v64, 0xffffff89, v131
	s_nop 0
	v_cndmask_b32_e32 v135, v233, v85, vcc
	v_cmp_lt_u32_e32 vcc, s53, v64
	v_add_u32_e32 v64, 0xffffffa9, v131
	s_nop 0
	v_cndmask_b32_e32 v146, v233, v70, vcc
	v_cmp_lt_u32_e32 vcc, s53, v64
	v_add_u32_e32 v64, 0xffffff8a, v131
	s_nop 0
	v_cndmask_b32_e32 v136, v233, v86, vcc
	v_cmp_lt_u32_e32 vcc, s53, v64
	v_add_u32_e32 v64, 0xffffffaa, v131
	s_nop 0
	v_cndmask_b32_e32 v147, v233, v71, vcc
	v_cmp_lt_u32_e32 vcc, s53, v64
	v_add_u32_e32 v64, 0xffffff8f, v131
	s_nop 0
	v_cndmask_b32_e32 v137, v233, v87, vcc
	v_cmp_lt_u32_e32 vcc, s53, v64
	v_add_u32_e32 v64, 0xffffffaf, v131
	s_nop 0
	v_cndmask_b32_e32 v148, v233, v72, vcc
	v_cmp_lt_u32_e32 vcc, s53, v64
	v_add_u32_e32 v64, 0xffffff90, v131
	s_nop 0
	v_cndmask_b32_e32 v138, v233, v88, vcc
	v_cmp_lt_u32_e32 vcc, s53, v64
	v_add_u32_e32 v64, 0xffffffb0, v131
	v_add_u32_e32 v88, s22, v201
	v_cndmask_b32_e32 v149, v233, v73, vcc
	v_cmp_lt_u32_e32 vcc, s53, v64
	v_add_u32_e32 v64, 0xffffff91, v131
	s_add_i32 s22, s45, 11
	v_cndmask_b32_e32 v139, v233, v89, vcc
	v_cmp_lt_u32_e32 vcc, s53, v64
	v_add_u32_e32 v64, 0xffffffb1, v131
	s_min_i32 s22, s22, s92
	v_cndmask_b32_e32 v176, v233, v74, vcc
	v_cmp_lt_u32_e32 vcc, s53, v64
	v_add_u32_e32 v64, 0xffffff92, v131
	s_cmp_gt_i32 s22, 3
	v_cndmask_b32_e32 v142, v233, v90, vcc
	v_cmp_lt_u32_e32 vcc, s53, v64
	v_add_u32_e32 v64, 0xffffffb2, v131
	s_nop 0
	v_cndmask_b32_e32 v177, v233, v75, vcc
	v_cmp_lt_u32_e32 vcc, s53, v64
	v_add_u32_e32 v64, 0xffffff97, v131
	s_nop 0
	v_cndmask_b32_e32 v143, v233, v91, vcc
	v_cmp_lt_u32_e32 vcc, s53, v64
	v_add_u32_e32 v64, 0xffffffb7, v131
	s_nop 0
	v_cndmask_b32_e32 v178, v233, v76, vcc
	v_cmp_lt_u32_e32 vcc, s53, v64
	v_add_u32_e32 v64, 0xffffff98, v131
	s_nop 0
	v_cndmask_b32_e32 v144, v233, v92, vcc
	v_cmp_lt_u32_e32 vcc, s53, v64
	v_add_u32_e32 v64, 0xffffffb8, v131
	s_nop 0
	v_cndmask_b32_e32 v179, v233, v77, vcc
	v_cmp_lt_u32_e32 vcc, s53, v64
	v_add_u32_e32 v64, 0xffffff99, v131
	s_nop 0
	v_cndmask_b32_e32 v145, v233, v93, vcc
	v_cmp_lt_u32_e32 vcc, s53, v64
	v_add_u32_e32 v64, 0xffffffb9, v131
	s_nop 0
	v_cndmask_b32_e32 v180, v233, v78, vcc
	v_cmp_lt_u32_e32 vcc, s53, v64
	v_add_u32_e32 v64, 0xffffff9a, v131
	s_nop 0
	v_cndmask_b32_e32 v150, v233, v94, vcc
	v_cmp_lt_u32_e32 vcc, s53, v65
	v_add_u32_e32 v65, s23, v203
	s_cselect_b32 s23, s13, 0
	s_add_i32 s22, s23, s22
	s_ashr_i32 s23, s22, 31
	s_lshl_b64 s[22:23], s[22:23], 13
	s_waitcnt vmcnt(2)
	ds_write_b128 v65, v[10:13] offset:36864
	v_lshl_add_u64 v[10:11], v[198:199], 0, s[22:23]
	s_lshl_b32 s22, s24, 6
	s_ashr_i32 s23, s22, 31
	global_load_dwordx4 v[168:171], v[10:11], off
	v_lshl_add_u64 v[10:11], s[22:23], 1, v[196:197]
	global_load_dwordx4 v[172:175], v[10:11], off
	v_cndmask_b32_e32 v151, v233, v95, vcc
	v_cmp_lt_u32_e32 vcc, s53, v64
	s_nop 1
	v_cndmask_b32_e32 v181, v233, v79, vcc
	ds_read_b128 v[240:243], v201 offset:9216
	ds_read_b128 v[244:247], v201 offset:13824
	ds_read_b128 v[10:13], v88 offset:41472
	ds_read_b128 v[64:67], v88 offset:36864
	ds_read_b128 v[68:71], v88 offset:36896
	ds_read_b128 v[72:75], v88 offset:41504
	ds_read_b128 v[76:79], v88 offset:36928
	ds_read_b128 v[80:83], v88 offset:41536
	ds_read_b128 v[84:87], v88 offset:36960
	ds_read_b128 v[88:91], v88 offset:41568
	s_setprio 1
	v_mov_b32_e32 v97, 0
	v_mov_b32_e32 v98, v112
	v_cvt_pk_bf16_f32 v92, v185, v186
	v_cvt_pk_bf16_f32 v93, v187, v204
	v_cvt_pk_bf16_f32 v94, v127, v128
	v_cvt_pk_bf16_f32 v95, v129, v130
	s_waitcnt lgkmcnt(6)
	s_nop 0
	v_mfma_f32_32x32x16_bf16 v[16:31], v[64:67], v[92:95], v[16:31]
	v_max3_f32 v98, v98, v113, v114
	v_max3_f32 v98, v98, v115, v140
	v_add_f32_e32 v97, v97, v185
	v_add_f32_e32 v97, v97, v186
	v_add_f32_e32 v97, v97, v187
	v_add_f32_e32 v97, v97, v204
	s_nop 0
	v_mfma_f32_32x32x16_bf16 v[32:47], v[10:13], v[92:95], v[32:47]
	v_cvt_pk_bf16_f32 v64, v123, v124
	v_cvt_pk_bf16_f32 v65, v125, v126
	v_cvt_pk_bf16_f32 v66, v119, v120
	v_cvt_pk_bf16_f32 v67, v121, v122
	v_max3_f32 v98, v98, v141, v146
	v_max3_f32 v98, v98, v147, v148
	v_add_f32_e32 v97, v97, v127
	v_add_f32_e32 v97, v97, v128
	v_add_f32_e32 v97, v97, v129
	v_add_f32_e32 v97, v97, v130
	s_waitcnt lgkmcnt(5)
	v_mfma_f32_32x32x16_bf16 v[16:31], v[68:71], v[64:67], v[16:31]
	v_max3_f32 v98, v98, v149, v176
	v_max3_f32 v98, v98, v177, v178
	v_add_f32_e32 v97, v97, v123
	v_add_f32_e32 v97, v97, v124
	v_add_f32_e32 v97, v97, v125
	v_add_f32_e32 v97, v97, v126
	s_waitcnt lgkmcnt(4)
	v_mfma_f32_32x32x16_bf16 v[32:47], v[72:75], v[64:67], v[32:47]
	v_cvt_pk_bf16_f32 v10, v111, v116
	v_cvt_pk_bf16_f32 v11, v117, v118
	v_cvt_pk_bf16_f32 v12, v107, v108
	v_cvt_pk_bf16_f32 v13, v109, v110
	v_max3_f32 v98, v98, v179, v180
	v_max3_f32 v98, v98, v181, v14
	v_add_f32_e32 v97, v97, v119
	v_add_f32_e32 v97, v97, v120
	v_add_f32_e32 v97, v97, v121
	v_add_f32_e32 v97, v97, v122
	s_waitcnt lgkmcnt(3)
	v_mfma_f32_32x32x16_bf16 v[16:31], v[76:79], v[10:13], v[16:31]
	v_max3_f32 v98, v98, v15, v132
	v_max3_f32 v98, v98, v133, v134
	v_add_f32_e32 v97, v97, v111
	v_add_f32_e32 v97, v97, v116
	v_add_f32_e32 v97, v97, v117
	v_add_f32_e32 v97, v97, v118
	s_waitcnt lgkmcnt(2)
	v_mfma_f32_32x32x16_bf16 v[32:47], v[80:83], v[10:13], v[32:47]
	v_cvt_pk_bf16_f32 v64, v103, v104
	v_cvt_pk_bf16_f32 v65, v105, v106
	v_cvt_pk_bf16_f32 v66, v1, v100
	v_cvt_pk_bf16_f32 v67, v101, v102
	v_max3_f32 v98, v98, v135, v136
	v_max3_f32 v98, v98, v137, v138
	v_add_f32_e32 v97, v97, v107
	v_add_f32_e32 v97, v97, v108
	v_add_f32_e32 v97, v97, v109
	v_add_f32_e32 v97, v97, v110
	s_waitcnt lgkmcnt(1)
	v_mfma_f32_32x32x16_bf16 v[16:31], v[84:87], v[64:67], v[16:31]
	v_max3_f32 v98, v98, v139, v142
	v_max3_f32 v98, v98, v143, v144
	v_add_f32_e32 v97, v97, v103
	v_add_f32_e32 v97, v97, v104
	v_add_f32_e32 v97, v97, v105
	v_add_f32_e32 v97, v97, v106
	s_waitcnt lgkmcnt(0)
	v_mfma_f32_32x32x16_bf16 v[32:47], v[88:91], v[64:67], v[32:47]
	v_max3_f32 v98, v98, v145, v150
	v_max3_f32 v98, v98, v151, v151
	v_add_f32_e32 v97, v97, v1
	v_add_f32_e32 v97, v97, v100
	v_add_f32_e32 v97, v97, v101
	v_add_f32_e32 v97, v97, v102
	s_setprio 0
	ds_read_b128 v[124:127], v201 offset:9248
	ds_read_b128 v[120:123], v201 offset:13856
	ds_read_b128 v[74:77], v201 offset:9280
	ds_read_b128 v[66:69], v201 offset:9312
	ds_read_b128 v[70:73], v201 offset:13888
	ds_read_b128 v[10:13], v201 offset:13920
	v_add_f32_e32 v64, v96, v97
	v_mov_b32_e32 v1, v98
	s_nop 1
	v_permlane32_swap_b32_e32 v98, v1
	v_max_f32_e32 v1, v1, v1
	v_max_f32_e32 v65, v98, v98
	v_max_f32_e32 v1, v65, v1
	v_cmp_lt_f32_e32 vcc, s52, v1
	s_cbranch_vccz .LBB0_703
	v_max_f32_e32 v1, v1, v1
	v_max_f32_e32 v82, 0, v1
	v_add_f32_e32 v195, v195, v82
	v_xor_b32_e32 v48, 0x80000000, v195
	v_pk_add_f32 v[112:113], v[112:113], v[82:83] op_sel_hi:[1,0] neg_lo:[0,1] neg_hi:[0,1]
	v_pk_add_f32 v[14:15], v[14:15], v[82:83] op_sel_hi:[1,0] neg_lo:[0,1] neg_hi:[0,1]
	v_pk_add_f32 v[114:115], v[114:115], v[82:83] op_sel_hi:[1,0] neg_lo:[0,1] neg_hi:[0,1]
	v_pk_add_f32 v[132:133], v[132:133], v[82:83] op_sel_hi:[1,0] neg_lo:[0,1] neg_hi:[0,1]
	v_pk_add_f32 v[140:141], v[140:141], v[82:83] op_sel_hi:[1,0] neg_lo:[0,1] neg_hi:[0,1]
	v_pk_add_f32 v[134:135], v[134:135], v[82:83] op_sel_hi:[1,0] neg_lo:[0,1] neg_hi:[0,1]
	v_pk_add_f32 v[146:147], v[146:147], v[82:83] op_sel_hi:[1,0] neg_lo:[0,1] neg_hi:[0,1]
	v_pk_add_f32 v[136:137], v[136:137], v[82:83] op_sel_hi:[1,0] neg_lo:[0,1] neg_hi:[0,1]
	v_pk_add_f32 v[148:149], v[148:149], v[82:83] op_sel_hi:[1,0] neg_lo:[0,1] neg_hi:[0,1]
	v_pk_add_f32 v[138:139], v[138:139], v[82:83] op_sel_hi:[1,0] neg_lo:[0,1] neg_hi:[0,1]
	v_pk_add_f32 v[176:177], v[176:177], v[82:83] op_sel_hi:[1,0] neg_lo:[0,1] neg_hi:[0,1]
	v_pk_add_f32 v[142:143], v[142:143], v[82:83] op_sel_hi:[1,0] neg_lo:[0,1] neg_hi:[0,1]
	v_pk_add_f32 v[178:179], v[178:179], v[82:83] op_sel_hi:[1,0] neg_lo:[0,1] neg_hi:[0,1]
	v_pk_add_f32 v[144:145], v[144:145], v[82:83] op_sel_hi:[1,0] neg_lo:[0,1] neg_hi:[0,1]
	v_pk_add_f32 v[180:181], v[180:181], v[82:83] op_sel_hi:[1,0] neg_lo:[0,1] neg_hi:[0,1]
	v_pk_add_f32 v[150:151], v[150:151], v[82:83] op_sel_hi:[1,0] neg_lo:[0,1] neg_hi:[0,1]
	v_exp_f32_e64 v82, -v82
	v_mov_b32_e32 v49, v48
	v_mov_b32_e32 v50, v48
	v_mov_b32_e32 v51, v48
	v_mov_b32_e32 v52, v48
	v_mov_b32_e32 v53, v48
	v_mov_b32_e32 v54, v48
	v_mov_b32_e32 v55, v48
	v_mov_b32_e32 v56, v48
	v_mov_b32_e32 v57, v48
	v_mov_b32_e32 v58, v48
	v_mov_b32_e32 v59, v48
	v_mov_b32_e32 v60, v48
	v_mov_b32_e32 v61, v48
	v_mov_b32_e32 v62, v48
	v_mov_b32_e32 v63, v48
	s_nop 11
	v_pk_mul_f32 v[30:31], v[30:31], v[82:83] op_sel_hi:[1,0]
	v_pk_mul_f32 v[28:29], v[28:29], v[82:83] op_sel_hi:[1,0]
	v_pk_mul_f32 v[26:27], v[26:27], v[82:83] op_sel_hi:[1,0]
	v_pk_mul_f32 v[24:25], v[24:25], v[82:83] op_sel_hi:[1,0]
	v_pk_mul_f32 v[22:23], v[22:23], v[82:83] op_sel_hi:[1,0]
	v_pk_mul_f32 v[20:21], v[20:21], v[82:83] op_sel_hi:[1,0]
	v_pk_mul_f32 v[18:19], v[18:19], v[82:83] op_sel_hi:[1,0]
	v_pk_mul_f32 v[16:17], v[16:17], v[82:83] op_sel_hi:[1,0]
	v_pk_mul_f32 v[46:47], v[46:47], v[82:83] op_sel_hi:[1,0]
	v_pk_mul_f32 v[44:45], v[44:45], v[82:83] op_sel_hi:[1,0]
	v_pk_mul_f32 v[42:43], v[42:43], v[82:83] op_sel_hi:[1,0]
	v_pk_mul_f32 v[40:41], v[40:41], v[82:83] op_sel_hi:[1,0]
	v_pk_mul_f32 v[38:39], v[38:39], v[82:83] op_sel_hi:[1,0]
	v_pk_mul_f32 v[36:37], v[36:37], v[82:83] op_sel_hi:[1,0]
	v_pk_mul_f32 v[34:35], v[34:35], v[82:83] op_sel_hi:[1,0]
	v_pk_mul_f32 v[32:33], v[32:33], v[82:83] op_sel_hi:[1,0]
	v_mul_f32_e32 v64, v64, v82
